# all 36 GEMM L-slot wait pairs (vmcnt(N) then lgkmcnt(0)) merged into one s_waitcnt: one issue slot less on the co-critical load slot
# baseline (speedup 1.0000x reference)
; #define PG8_STAGE(bufoff, gbase, voff) do { _Pragma("unroll") for (int _i = 0; _i < 2; ++_i) \
;         __builtin_amdgcn_global_load_lds((const unsigned*)((const char*)(gbase) + (voff)[_i]), (PG8_LAS unsigned*)(lds + (bufoff) + ldsw + _i * 8192), 16, 0, 0); } while (0)
; #define PG8_LDA(dst, b, h) do { _Pragma("unroll") for (int m = 0; m < 4; ++m) _Pragma("unroll") for (int k = 0; k < 2; ++k) dst[m][k] = *(const PG8_LAS bf16x8*)(lds + PG8_SA(b, h) + aoff + m * 2048 + k * 1024); } while (0)
; #define PG8_LDB(dst, b, h) do { _Pragma("unroll") for (int n = 0; n < 2; ++n) _Pragma("unroll") for (int k = 0; k < 2; ++k) dst[n][k] = *(const PG8_LAS bf16x8*)(lds + PG8_SB(b, h) + boff + n * 2048 + k * 1024); } while (0)
; #define PG8_WAIT_V(n) asm volatile("s_waitcnt vmcnt(" #n ")" ::: "memory")
; #define PG8_WAIT_L(n) asm volatile("s_waitcnt lgkmcnt(" #n ")" ::: "memory")
; #define PG8_BAR __builtin_amdgcn_s_barrier()
; #define PG8_SCHED __builtin_amdgcn_sched_barrier(0)
; template <class Epi, class Sched, bool ALIGN_EPI = false, bool SP2 = false, bool F8 = false>
; __device__ __forceinline__ void gemm_phase(PG8_LAS unsigned char* lds, const Gemm g, const Sched& S, const Epi& E) {
;     ...
;             PG8_LDB(B0, 0, 0); PG8_LDB(B1, 0, 1); PG8_SCHED; PG8_LDA(At, 0, 0); PG8_STAGE(PG8_SA(1, 1), a1 + hA, voffA);
;             PG8_WAIT_V(8); PG8_WAIT_L(0); PG8_BAR; PG8_MMA(0, 0, At, B0); PG8_MMA(0, 1, At, B1); PG8_BAR; PG8_SCHED;
;             PG8_LDA(At, 0, 1); PG8_STAGE(PG8_SB(0, 0), b2, voffB); PG8_STAGE(PG8_SB(0, 1), b2 + hB, voffB); PG8_STAGE(PG8_SA(0, 0), a2, voffA);
;             PG8_WAIT_V(8); PG8_WAIT_L(0); PG8_BAR; PG8_MMA(1, 0, At, B0); PG8_MMA(1, 1, At, B1); PG8_BAR; PG8_SCHED;
;             PG8_LDB(B0, 1, 0); PG8_LDB(B1, 1, 1); PG8_SCHED; PG8_LDA(At, 1, 0); PG8_STAGE(PG8_SA(0, 1), a2 + hA, voffA);
;             PG8_WAIT_V(8); PG8_WAIT_L(0); PG8_BAR; PG8_MMA(0, 0, At, B0); PG8_MMA(0, 1, At, B1); PG8_BAR; PG8_SCHED;
;             PG8_LDA(At, 1, 1); PG8_STAGE(PG8_SB(1, 0), b3, voffB); PG8_STAGE(PG8_SB(1, 1), b3 + hB, voffB); PG8_STAGE(PG8_SA(1, 0), a3, voffA);
;             PG8_WAIT_V(8); PG8_WAIT_L(0); PG8_BAR; PG8_MMA(1, 0, At, B0); PG8_MMA(1, 1, At, B1); PG8_BAR; PG8_SCHED;
.LBB0_128:
	ds_read_b128 v[152:155], v149
	ds_read_b128 v[156:159], v149 offset:1024
	ds_read_b128 v[160:163], v149 offset:2048
	ds_read_b128 v[164:167], v149 offset:3072
	ds_read_b128 v[168:171], v150
	ds_read_b128 v[172:175], v150 offset:1024
	ds_read_b128 v[176:179], v150 offset:2048
	ds_read_b128 v[180:183], v150 offset:3072
	s_add_u32 s40, s38, 0xfff00080
	s_addc_u32 s41, s39, -1
	s_cmp_eq_u32 s66, 60
	s_cselect_b32 s43, s31, s41
	s_cselect_b32 s42, s62, s40
	s_cselect_b32 s41, s29, s65
	s_cselect_b32 s40, s63, s64
	v_lshl_add_u64 v[216:217], s[38:39], 0, v[140:141]
	s_add_i32 m0, s27, 0xc000
	ds_read_b128 v[184:187], v151
	ds_read_b128 v[188:191], v151 offset:1024
	ds_read_b128 v[192:195], v151 offset:2048
	ds_read_b128 v[196:199], v151 offset:3072
	ds_read_b128 v[200:203], v151 offset:4096
	ds_read_b128 v[204:207], v151 offset:5120
	ds_read_b128 v[208:211], v151 offset:6144
	ds_read_b128 v[212:215], v151 offset:7168
	global_load_lds_dwordx4 v[216:217], off
	v_lshl_add_u64 v[216:217], s[38:39], 0, v[138:139]
	s_add_i32 m0, s27, 0xe000
	s_nop 0
	global_load_lds_dwordx4 v[216:217], off
	s_waitcnt vmcnt(8) lgkmcnt(0)
	s_setprio 1
	s_barrier
	v_mfma_f32_16x16x32_bf16 v[126:129], v[152:155], v[184:187], v[126:129]
	v_mfma_f32_16x16x32_bf16 v[122:125], v[160:163], v[184:187], v[122:125]
	v_mfma_f32_16x16x32_bf16 v[118:121], v[152:155], v[192:195], v[118:121]
	v_mfma_f32_16x16x32_bf16 v[114:117], v[160:163], v[192:195], v[114:117]
	v_mfma_f32_16x16x32_bf16 v[102:105], v[152:155], v[200:203], v[102:105]
	v_mfma_f32_16x16x32_bf16 v[98:101], v[160:163], v[200:203], v[98:101]
	v_mfma_f32_16x16x32_bf16 v[86:89], v[152:155], v[208:211], v[86:89]
	v_mfma_f32_16x16x32_bf16 v[82:85], v[160:163], v[208:211], v[82:85]
	v_mfma_f32_16x16x32_bf16 v[126:129], v[156:159], v[188:191], v[126:129]
	v_mfma_f32_16x16x32_bf16 v[122:125], v[164:167], v[188:191], v[122:125]
	v_mfma_f32_16x16x32_bf16 v[118:121], v[156:159], v[196:199], v[118:121]
	v_mfma_f32_16x16x32_bf16 v[114:117], v[164:167], v[196:199], v[114:117]
	v_mfma_f32_16x16x32_bf16 v[102:105], v[156:159], v[204:207], v[102:105]
	v_mfma_f32_16x16x32_bf16 v[98:101], v[164:167], v[204:207], v[98:101]
	v_mfma_f32_16x16x32_bf16 v[86:89], v[156:159], v[212:215], v[86:89]
	v_mfma_f32_16x16x32_bf16 v[82:85], v[164:167], v[212:215], v[82:85]
	v_mfma_f32_16x16x32_bf16 v[110:113], v[168:171], v[184:187], v[110:113]
	v_mfma_f32_16x16x32_bf16 v[106:109], v[176:179], v[184:187], v[106:109]
	v_mfma_f32_16x16x32_bf16 v[94:97], v[168:171], v[192:195], v[94:97]
	v_mfma_f32_16x16x32_bf16 v[90:93], v[176:179], v[192:195], v[90:93]
	v_mfma_f32_16x16x32_bf16 v[78:81], v[168:171], v[200:203], v[78:81]
	v_mfma_f32_16x16x32_bf16 v[74:77], v[176:179], v[200:203], v[74:77]
	v_mfma_f32_16x16x32_bf16 v[70:73], v[168:171], v[208:211], v[70:73]
	v_mfma_f32_16x16x32_bf16 v[66:69], v[176:179], v[208:211], v[66:69]
	v_mfma_f32_16x16x32_bf16 v[110:113], v[172:175], v[188:191], v[110:113]
	v_mfma_f32_16x16x32_bf16 v[106:109], v[180:183], v[188:191], v[106:109]
	v_mfma_f32_16x16x32_bf16 v[94:97], v[172:175], v[196:199], v[94:97]
	v_mfma_f32_16x16x32_bf16 v[90:93], v[180:183], v[196:199], v[90:93]
	v_mfma_f32_16x16x32_bf16 v[78:81], v[172:175], v[204:207], v[78:81]
	v_mfma_f32_16x16x32_bf16 v[74:77], v[180:183], v[204:207], v[74:77]
	v_mfma_f32_16x16x32_bf16 v[70:73], v[172:175], v[212:215], v[70:73]
	v_mfma_f32_16x16x32_bf16 v[66:69], v[180:183], v[212:215], v[66:69]
	s_barrier
	s_setprio 0
	s_add_i32 s67, s55, s45
	v_lshl_add_u64 v[216:217], s[40:41], 0, v[134:135]
	s_mov_b32 m0, s67
	ds_read_b128 v[184:187], v151 offset:16384
	ds_read_b128 v[188:191], v151 offset:17408
	ds_read_b128 v[192:195], v151 offset:18432
	ds_read_b128 v[196:199], v151 offset:19456
	ds_read_b128 v[200:203], v151 offset:20480
	ds_read_b128 v[204:207], v151 offset:21504
	ds_read_b128 v[208:211], v151 offset:22528
	ds_read_b128 v[212:215], v151 offset:23552
	global_load_lds_dwordx4 v[216:217], off
	s_add_i32 m0, s67, 0x2000
	s_add_u32 s70, s40, 0x100000
	v_lshl_add_u64 v[218:219], s[40:41], 0, v[130:131]
	s_addc_u32 s71, s41, 0
	s_add_i32 s67, s56, s45
	global_load_lds_dwordx4 v[218:219], off
	v_lshl_add_u64 v[220:221], s[70:71], 0, v[134:135]
	s_mov_b32 m0, s67
	v_lshl_add_u64 v[222:223], s[42:43], 0, v[132:133]
	global_load_lds_dwordx4 v[220:221], off
	v_lshl_add_u64 v[220:221], s[70:71], 0, v[130:131]
	s_add_i32 m0, s67, 0x2000
	s_nop 0
	global_load_lds_dwordx4 v[220:221], off
	v_lshl_add_u64 v[220:221], s[42:43], 0, v[136:137]
	s_mov_b32 m0, s27
	s_nop 0
	global_load_lds_dwordx4 v[220:221], off
	s_mov_b32 m0, s48
	s_nop 0
	global_load_lds_dwordx4 v[222:223], off
	s_waitcnt vmcnt(8) lgkmcnt(0)
	s_setprio 1
	s_barrier
; #define PG8_STAGE(bufoff, gbase, voff) do { _Pragma("unroll") for (int _i = 0; _i < 2; ++_i) \
;         __builtin_amdgcn_global_load_lds((const unsigned*)((const char*)(gbase) + (voff)[_i]), (PG8_LAS unsigned*)(lds + (bufoff) + ldsw + _i * 8192), 16, 0, 0); } while (0)
; #define PG8_LDA(dst, b, h) do { _Pragma("unroll") for (int m = 0; m < 4; ++m) _Pragma("unroll") for (int k = 0; k < 2; ++k) dst[m][k] = *(const PG8_LAS bf16x8*)(lds + PG8_SA(b, h) + aoff + m * 2048 + k * 1024); } while (0)
; #define PG8_LDB(dst, b, h) do { _Pragma("unroll") for (int n = 0; n < 2; ++n) _Pragma("unroll") for (int k = 0; k < 2; ++k) dst[n][k] = *(const PG8_LAS bf16x8*)(lds + PG8_SB(b, h) + boff + n * 2048 + k * 1024); } while (0)
; #define PG8_WAIT_V(n) asm volatile("s_waitcnt vmcnt(" #n ")" ::: "memory")
; #define PG8_WAIT_L(n) asm volatile("s_waitcnt lgkmcnt(" #n ")" ::: "memory")
; #define PG8_BAR __builtin_amdgcn_s_barrier()
; #define PG8_SCHED __builtin_amdgcn_sched_barrier(0)
; template <class Epi, class Sched, bool ALIGN_EPI = false, bool SP2 = false, bool F8 = false>
; __device__ __forceinline__ void gemm_phase(PG8_LAS unsigned char* lds, const Gemm g, const Sched& S, const Epi& E) {
;     ...
;             PG8_LDB(B0, 0, 0); PG8_LDB(B1, 0, 1); PG8_SCHED; PG8_LDA(At, 0, 0); PG8_STAGE(PG8_SA(1, 1), a1 + hA, voffA);
;             PG8_WAIT_V(8); PG8_WAIT_L(0); PG8_BAR; PG8_MMA(0, 0, At, B0); PG8_MMA(0, 1, At, B1); PG8_BAR; PG8_SCHED;
;             PG8_LDA(At, 0, 1); PG8_STAGE(PG8_SB(0, 0), b2, voffB); PG8_STAGE(PG8_SB(0, 1), b2 + hB, voffB); PG8_STAGE(PG8_SA(0, 0), a2, voffA);
;             PG8_WAIT_V(8); PG8_WAIT_L(0); PG8_BAR; PG8_MMA(1, 0, At, B0); PG8_MMA(1, 1, At, B1); PG8_BAR; PG8_SCHED;
;             PG8_LDB(B0, 1, 0); PG8_LDB(B1, 1, 1); PG8_SCHED; PG8_LDA(At, 1, 0); PG8_STAGE(PG8_SA(0, 1), a2 + hA, voffA);
;             PG8_WAIT_V(8); PG8_WAIT_L(0); PG8_BAR; PG8_MMA(0, 0, At, B0); PG8_MMA(0, 1, At, B1); PG8_BAR; PG8_SCHED;
;             PG8_LDA(At, 1, 1); PG8_STAGE(PG8_SB(1, 0), b3, voffB); PG8_STAGE(PG8_SB(1, 1), b3 + hB, voffB); PG8_STAGE(PG8_SA(1, 0), a3, voffA);
;             PG8_WAIT_V(8); PG8_WAIT_L(0); PG8_BAR; PG8_MMA(1, 0, At, B0); PG8_MMA(1, 1, At, B1); PG8_BAR; PG8_SCHED;
	v_mfma_f32_16x16x32_bf16 v[62:65], v[152:155], v[184:187], v[62:65]
	v_mfma_f32_16x16x32_bf16 v[58:61], v[160:163], v[184:187], v[58:61]
	v_mfma_f32_16x16x32_bf16 v[54:57], v[152:155], v[192:195], v[54:57]
	v_mfma_f32_16x16x32_bf16 v[50:53], v[160:163], v[192:195], v[50:53]
	v_mfma_f32_16x16x32_bf16 v[38:41], v[152:155], v[200:203], v[38:41]
	v_mfma_f32_16x16x32_bf16 v[34:37], v[160:163], v[200:203], v[34:37]
	v_mfma_f32_16x16x32_bf16 v[22:25], v[152:155], v[208:211], v[22:25]
	v_mfma_f32_16x16x32_bf16 v[18:21], v[160:163], v[208:211], v[18:21]
	v_mfma_f32_16x16x32_bf16 v[62:65], v[156:159], v[188:191], v[62:65]
	v_mfma_f32_16x16x32_bf16 v[58:61], v[164:167], v[188:191], v[58:61]
	v_mfma_f32_16x16x32_bf16 v[54:57], v[156:159], v[196:199], v[54:57]
	v_mfma_f32_16x16x32_bf16 v[50:53], v[164:167], v[196:199], v[50:53]
	v_mfma_f32_16x16x32_bf16 v[38:41], v[156:159], v[204:207], v[38:41]
	v_mfma_f32_16x16x32_bf16 v[34:37], v[164:167], v[204:207], v[34:37]
	v_mfma_f32_16x16x32_bf16 v[22:25], v[156:159], v[212:215], v[22:25]
	v_mfma_f32_16x16x32_bf16 v[18:21], v[164:167], v[212:215], v[18:21]
	v_mfma_f32_16x16x32_bf16 v[46:49], v[168:171], v[184:187], v[46:49]
	v_mfma_f32_16x16x32_bf16 v[42:45], v[176:179], v[184:187], v[42:45]
	v_mfma_f32_16x16x32_bf16 v[30:33], v[168:171], v[192:195], v[30:33]
	v_mfma_f32_16x16x32_bf16 v[26:29], v[176:179], v[192:195], v[26:29]
	v_mfma_f32_16x16x32_bf16 v[14:17], v[168:171], v[200:203], v[14:17]
	v_mfma_f32_16x16x32_bf16 v[10:13], v[176:179], v[200:203], v[10:13]
	v_mfma_f32_16x16x32_bf16 v[6:9], v[168:171], v[208:211], v[6:9]
	v_mfma_f32_16x16x32_bf16 v[2:5], v[176:179], v[208:211], v[2:5]
	v_mfma_f32_16x16x32_bf16 v[46:49], v[172:175], v[188:191], v[46:49]
	v_mfma_f32_16x16x32_bf16 v[42:45], v[180:183], v[188:191], v[42:45]
	v_mfma_f32_16x16x32_bf16 v[30:33], v[172:175], v[196:199], v[30:33]
	v_mfma_f32_16x16x32_bf16 v[26:29], v[180:183], v[196:199], v[26:29]
	v_mfma_f32_16x16x32_bf16 v[14:17], v[172:175], v[204:207], v[14:17]
	v_mfma_f32_16x16x32_bf16 v[10:13], v[180:183], v[204:207], v[10:13]
	v_mfma_f32_16x16x32_bf16 v[6:9], v[172:175], v[212:215], v[6:9]
	v_mfma_f32_16x16x32_bf16 v[2:5], v[180:183], v[212:215], v[2:5]
	s_barrier
	s_setprio 0
	s_add_i32 s67, 0, 0x18000
	s_add_i32 s69, 0, 0x1c000
	v_add_u32_e32 v164, s67, v147
	v_add_u32_e32 v180, s69, v147
	ds_read_b128 v[152:155], v164
	ds_read_b128 v[156:159], v164 offset:1024
	ds_read_b128 v[160:163], v164 offset:2048
	ds_read_b128 v[164:167], v164 offset:3072
	ds_read_b128 v[168:171], v180
	ds_read_b128 v[172:175], v180 offset:1024
	ds_read_b128 v[176:179], v180 offset:2048
	ds_read_b128 v[180:183], v180 offset:3072
	s_add_u32 s42, s42, 0x100000
	s_addc_u32 s43, s43, 0
	s_mov_b32 m0, s49
	v_lshl_add_u64 v[224:225], s[42:43], 0, v[136:137]
	ds_read_b128 v[184:187], v151 offset:32768
	ds_read_b128 v[188:191], v151 offset:33792
	ds_read_b128 v[192:195], v151 offset:34816
	ds_read_b128 v[196:199], v151 offset:35840
	ds_read_b128 v[200:203], v151 offset:36864
	ds_read_b128 v[204:207], v151 offset:37888
	ds_read_b128 v[208:211], v151 offset:38912
	ds_read_b128 v[212:215], v151 offset:39936
	global_load_lds_dwordx4 v[224:225], off
	v_lshl_add_u64 v[224:225], s[42:43], 0, v[132:133]
	s_mov_b32 m0, s50
	s_nop 0
	global_load_lds_dwordx4 v[224:225], off
	s_waitcnt vmcnt(8) lgkmcnt(0)
	s_setprio 1
	s_barrier
	v_mfma_f32_16x16x32_bf16 v[126:129], v[152:155], v[184:187], v[126:129]
	v_mfma_f32_16x16x32_bf16 v[122:125], v[160:163], v[184:187], v[122:125]
	v_mfma_f32_16x16x32_bf16 v[118:121], v[152:155], v[192:195], v[118:121]
	v_mfma_f32_16x16x32_bf16 v[114:117], v[160:163], v[192:195], v[114:117]
	v_mfma_f32_16x16x32_bf16 v[102:105], v[152:155], v[200:203], v[102:105]
	v_mfma_f32_16x16x32_bf16 v[98:101], v[160:163], v[200:203], v[98:101]
	v_mfma_f32_16x16x32_bf16 v[86:89], v[152:155], v[208:211], v[86:89]
	v_mfma_f32_16x16x32_bf16 v[82:85], v[160:163], v[208:211], v[82:85]
	v_mfma_f32_16x16x32_bf16 v[126:129], v[156:159], v[188:191], v[126:129]
	v_mfma_f32_16x16x32_bf16 v[122:125], v[164:167], v[188:191], v[122:125]
	v_mfma_f32_16x16x32_bf16 v[118:121], v[156:159], v[196:199], v[118:121]
	v_mfma_f32_16x16x32_bf16 v[114:117], v[164:167], v[196:199], v[114:117]
	v_mfma_f32_16x16x32_bf16 v[102:105], v[156:159], v[204:207], v[102:105]
	v_mfma_f32_16x16x32_bf16 v[98:101], v[164:167], v[204:207], v[98:101]
	v_mfma_f32_16x16x32_bf16 v[86:89], v[156:159], v[212:215], v[86:89]
	v_mfma_f32_16x16x32_bf16 v[82:85], v[164:167], v[212:215], v[82:85]
	v_mfma_f32_16x16x32_bf16 v[110:113], v[168:171], v[184:187], v[110:113]
	v_mfma_f32_16x16x32_bf16 v[106:109], v[176:179], v[184:187], v[106:109]
	v_mfma_f32_16x16x32_bf16 v[94:97], v[168:171], v[192:195], v[94:97]
	v_mfma_f32_16x16x32_bf16 v[90:93], v[176:179], v[192:195], v[90:93]
	v_mfma_f32_16x16x32_bf16 v[78:81], v[168:171], v[200:203], v[78:81]
	v_mfma_f32_16x16x32_bf16 v[74:77], v[176:179], v[200:203], v[74:77]
	v_mfma_f32_16x16x32_bf16 v[70:73], v[168:171], v[208:211], v[70:73]
	v_mfma_f32_16x16x32_bf16 v[66:69], v[176:179], v[208:211], v[66:69]
	v_mfma_f32_16x16x32_bf16 v[110:113], v[172:175], v[188:191], v[110:113]
	v_mfma_f32_16x16x32_bf16 v[106:109], v[180:183], v[188:191], v[106:109]
	v_mfma_f32_16x16x32_bf16 v[94:97], v[172:175], v[196:199], v[94:97]
	v_mfma_f32_16x16x32_bf16 v[90:93], v[180:183], v[196:199], v[90:93]
	v_mfma_f32_16x16x32_bf16 v[78:81], v[172:175], v[204:207], v[78:81]
	v_mfma_f32_16x16x32_bf16 v[74:77], v[180:183], v[204:207], v[74:77]
	v_mfma_f32_16x16x32_bf16 v[70:73], v[172:175], v[212:215], v[70:73]
	v_mfma_f32_16x16x32_bf16 v[66:69], v[180:183], v[212:215], v[66:69]
	s_barrier
; #define PG8_STAGE(bufoff, gbase, voff) do { _Pragma("unroll") for (int _i = 0; _i < 2; ++_i) \
;         __builtin_amdgcn_global_load_lds((const unsigned*)((const char*)(gbase) + (voff)[_i]), (PG8_LAS unsigned*)(lds + (bufoff) + ldsw + _i * 8192), 16, 0, 0); } while (0)
; #define PG8_LDA(dst, b, h) do { _Pragma("unroll") for (int m = 0; m < 4; ++m) _Pragma("unroll") for (int k = 0; k < 2; ++k) dst[m][k] = *(const PG8_LAS bf16x8*)(lds + PG8_SA(b, h) + aoff + m * 2048 + k * 1024); } while (0)
; #define PG8_LDB(dst, b, h) do { _Pragma("unroll") for (int n = 0; n < 2; ++n) _Pragma("unroll") for (int k = 0; k < 2; ++k) dst[n][k] = *(const PG8_LAS bf16x8*)(lds + PG8_SB(b, h) + boff + n * 2048 + k * 1024); } while (0)
; #define PG8_WAIT_V(n) asm volatile("s_waitcnt vmcnt(" #n ")" ::: "memory")
; #define PG8_WAIT_L(n) asm volatile("s_waitcnt lgkmcnt(" #n ")" ::: "memory")
; #define PG8_BAR __builtin_amdgcn_s_barrier()
; #define PG8_SCHED __builtin_amdgcn_sched_barrier(0)
; template <class Epi, class Sched, bool ALIGN_EPI = false, bool SP2 = false, bool F8 = false>
; __device__ __forceinline__ void gemm_phase(PG8_LAS unsigned char* lds, const Gemm g, const Sched& S, const Epi& E) {
;     ...
;             PG8_LDB(B0, 0, 0); PG8_LDB(B1, 0, 1); PG8_SCHED; PG8_LDA(At, 0, 0); PG8_STAGE(PG8_SA(1, 1), a1 + hA, voffA);
;             PG8_WAIT_V(8); PG8_WAIT_L(0); PG8_BAR; PG8_MMA(0, 0, At, B0); PG8_MMA(0, 1, At, B1); PG8_BAR; PG8_SCHED;
;             PG8_LDA(At, 0, 1); PG8_STAGE(PG8_SB(0, 0), b2, voffB); PG8_STAGE(PG8_SB(0, 1), b2 + hB, voffB); PG8_STAGE(PG8_SA(0, 0), a2, voffA);
;             PG8_WAIT_V(8); PG8_WAIT_L(0); PG8_BAR; PG8_MMA(1, 0, At, B0); PG8_MMA(1, 1, At, B1); PG8_BAR; PG8_SCHED;
;             PG8_LDB(B0, 1, 0); PG8_LDB(B1, 1, 1); PG8_SCHED; PG8_LDA(At, 1, 0); PG8_STAGE(PG8_SA(0, 1), a2 + hA, voffA);
;             PG8_WAIT_V(8); PG8_WAIT_L(0); PG8_BAR; PG8_MMA(0, 0, At, B0); PG8_MMA(0, 1, At, B1); PG8_BAR; PG8_SCHED;
;             PG8_LDA(At, 1, 1); PG8_STAGE(PG8_SB(1, 0), b3, voffB); PG8_STAGE(PG8_SB(1, 1), b3 + hB, voffB); PG8_STAGE(PG8_SA(1, 0), a3, voffA);
;             PG8_WAIT_V(8); PG8_WAIT_L(0); PG8_BAR; PG8_MMA(1, 0, At, B0); PG8_MMA(1, 1, At, B1); PG8_BAR; PG8_SCHED;
	s_setprio 0
	s_add_i32 s42, s67, s45
	v_lshl_add_u64 v[216:217], v[216:217], 0, s[12:13]
	s_mov_b32 m0, s42
	ds_read_b128 v[184:187], v151 offset:49152
	ds_read_b128 v[188:191], v151 offset:50176
	ds_read_b128 v[192:195], v151 offset:51200
	ds_read_b128 v[196:199], v151 offset:52224
	ds_read_b128 v[200:203], v151 offset:53248
	ds_read_b128 v[204:207], v151 offset:54272
	ds_read_b128 v[208:211], v151 offset:55296
	ds_read_b128 v[212:215], v151 offset:56320
	global_load_lds_dwordx4 v[216:217], off
	s_add_i32 m0, s42, 0x2000
	s_add_u32 s40, s40, 0x100080
	v_lshl_add_u64 v[216:217], v[218:219], 0, s[12:13]
	s_addc_u32 s41, s41, 0
	s_add_i32 s42, s69, s45
	global_load_lds_dwordx4 v[216:217], off
	v_lshl_add_u64 v[216:217], s[40:41], 0, v[134:135]
	s_mov_b32 m0, s42
	s_nop 0
	global_load_lds_dwordx4 v[216:217], off
	v_lshl_add_u64 v[216:217], s[40:41], 0, v[130:131]
	s_add_i32 m0, s42, 0x2000
	s_nop 0
	global_load_lds_dwordx4 v[216:217], off
	v_lshl_add_u64 v[216:217], v[220:221], 0, s[12:13]
	s_mov_b32 m0, s52
	s_nop 0
	global_load_lds_dwordx4 v[216:217], off
	v_lshl_add_u64 v[216:217], v[222:223], 0, s[12:13]
	s_mov_b32 m0, s53
	s_nop 0
	global_load_lds_dwordx4 v[216:217], off
	s_waitcnt vmcnt(8) lgkmcnt(0)
	s_setprio 1
	s_barrier
	v_mfma_f32_16x16x32_bf16 v[62:65], v[152:155], v[184:187], v[62:65]
	v_mfma_f32_16x16x32_bf16 v[58:61], v[160:163], v[184:187], v[58:61]
	v_mfma_f32_16x16x32_bf16 v[54:57], v[152:155], v[192:195], v[54:57]
	v_mfma_f32_16x16x32_bf16 v[50:53], v[160:163], v[192:195], v[50:53]
	v_mfma_f32_16x16x32_bf16 v[38:41], v[152:155], v[200:203], v[38:41]
	v_mfma_f32_16x16x32_bf16 v[34:37], v[160:163], v[200:203], v[34:37]
	v_mfma_f32_16x16x32_bf16 v[22:25], v[152:155], v[208:211], v[22:25]
	v_mfma_f32_16x16x32_bf16 v[18:21], v[160:163], v[208:211], v[18:21]
	v_mfma_f32_16x16x32_bf16 v[62:65], v[156:159], v[188:191], v[62:65]
	v_mfma_f32_16x16x32_bf16 v[58:61], v[164:167], v[188:191], v[58:61]
	v_mfma_f32_16x16x32_bf16 v[54:57], v[156:159], v[196:199], v[54:57]
	v_mfma_f32_16x16x32_bf16 v[50:53], v[164:167], v[196:199], v[50:53]
	v_mfma_f32_16x16x32_bf16 v[38:41], v[156:159], v[204:207], v[38:41]
	v_mfma_f32_16x16x32_bf16 v[34:37], v[164:167], v[204:207], v[34:37]
	v_mfma_f32_16x16x32_bf16 v[22:25], v[156:159], v[212:215], v[22:25]
	v_mfma_f32_16x16x32_bf16 v[18:21], v[164:167], v[212:215], v[18:21]
	v_mfma_f32_16x16x32_bf16 v[46:49], v[168:171], v[184:187], v[46:49]
	v_mfma_f32_16x16x32_bf16 v[42:45], v[176:179], v[184:187], v[42:45]
	v_mfma_f32_16x16x32_bf16 v[30:33], v[168:171], v[192:195], v[30:33]
	v_mfma_f32_16x16x32_bf16 v[26:29], v[176:179], v[192:195], v[26:29]
	v_mfma_f32_16x16x32_bf16 v[14:17], v[168:171], v[200:203], v[14:17]
	v_mfma_f32_16x16x32_bf16 v[10:13], v[176:179], v[200:203], v[10:13]
	v_mfma_f32_16x16x32_bf16 v[6:9], v[168:171], v[208:211], v[6:9]
	v_mfma_f32_16x16x32_bf16 v[2:5], v[176:179], v[208:211], v[2:5]
	v_mfma_f32_16x16x32_bf16 v[46:49], v[172:175], v[188:191], v[46:49]
	v_mfma_f32_16x16x32_bf16 v[42:45], v[180:183], v[188:191], v[42:45]
	v_mfma_f32_16x16x32_bf16 v[30:33], v[172:175], v[196:199], v[30:33]
	v_mfma_f32_16x16x32_bf16 v[26:29], v[180:183], v[196:199], v[26:29]
	v_mfma_f32_16x16x32_bf16 v[14:17], v[172:175], v[204:207], v[14:17]
	v_mfma_f32_16x16x32_bf16 v[10:13], v[180:183], v[204:207], v[10:13]
	v_mfma_f32_16x16x32_bf16 v[6:9], v[172:175], v[212:215], v[6:9]
	v_mfma_f32_16x16x32_bf16 v[2:5], v[180:183], v[212:215], v[2:5]
	s_barrier
	s_setprio 0
	s_add_i32 s66, s66, 2
	s_add_u32 s64, s64, 0x100
	s_addc_u32 s65, s65, 0
	s_add_u32 s38, s38, 0x100
	s_addc_u32 s39, s39, 0
	s_cmp_gt_u32 s66, 61
	s_cbranch_scc0 .LBB0_128
	s_and_b64 vcc, exec, s[14:15]
	s_cbranch_vccz .LBB0_131
	s_barrier

; #define PG8_STAGE(bufoff, gbase, voff) do { _Pragma("unroll") for (int _i = 0; _i < 2; ++_i) \
;         __builtin_amdgcn_global_load_lds((const unsigned*)((const char*)(gbase) + (voff)[_i]), (PG8_LAS unsigned*)(lds + (bufoff) + ldsw + _i * 8192), 16, 0, 0); } while (0)
; #define PG8_LDA(dst, b, h) do { _Pragma("unroll") for (int m = 0; m < 4; ++m) _Pragma("unroll") for (int k = 0; k < 2; ++k) dst[m][k] = *(const PG8_LAS bf16x8*)(lds + PG8_SA(b, h) + aoff + m * 2048 + k * 1024); } while (0)
; #define PG8_LDB(dst, b, h) do { _Pragma("unroll") for (int n = 0; n < 2; ++n) _Pragma("unroll") for (int k = 0; k < 2; ++k) dst[n][k] = *(const PG8_LAS bf16x8*)(lds + PG8_SB(b, h) + boff + n * 2048 + k * 1024); } while (0)
; #define PG8_WAIT_V(n) asm volatile("s_waitcnt vmcnt(" #n ")" ::: "memory")
; #define PG8_WAIT_L(n) asm volatile("s_waitcnt lgkmcnt(" #n ")" ::: "memory")
; #define PG8_BAR __builtin_amdgcn_s_barrier()
; #define PG8_SCHED __builtin_amdgcn_sched_barrier(0)
; template <class Epi, class Sched, bool ALIGN_EPI = false, bool SP2 = false, bool F8 = false>
; __device__ __forceinline__ void gemm_phase(PG8_LAS unsigned char* lds, const Gemm g, const Sched& S, const Epi& E) {
;     ...
;             PG8_LDB(B0, 0, 0); PG8_LDB(B1, 0, 1); PG8_SCHED; PG8_LDA(At, 0, 0); PG8_STAGE(PG8_SA(1, 1), a1 + hA, voffA);
;             PG8_WAIT_V(8); PG8_WAIT_L(0); PG8_BAR; PG8_MMA(0, 0, At, B0); PG8_MMA(0, 1, At, B1); PG8_BAR; PG8_SCHED;
;             PG8_LDA(At, 0, 1); PG8_STAGE(PG8_SB(0, 0), b2, voffB); PG8_STAGE(PG8_SB(0, 1), b2 + hB, voffB); PG8_STAGE(PG8_SA(0, 0), a2, voffA);
;             PG8_WAIT_V(8); PG8_WAIT_L(0); PG8_BAR; PG8_MMA(1, 0, At, B0); PG8_MMA(1, 1, At, B1); PG8_BAR; PG8_SCHED;
;             PG8_LDB(B0, 1, 0); PG8_LDB(B1, 1, 1); PG8_SCHED; PG8_LDA(At, 1, 0); PG8_STAGE(PG8_SA(0, 1), a2 + hA, voffA);
;             PG8_WAIT_V(8); PG8_WAIT_L(0); PG8_BAR; PG8_MMA(0, 0, At, B0); PG8_MMA(0, 1, At, B1); PG8_BAR; PG8_SCHED;
;             PG8_LDA(At, 1, 1); PG8_STAGE(PG8_SB(1, 0), b3, voffB); PG8_STAGE(PG8_SB(1, 1), b3 + hB, voffB); PG8_STAGE(PG8_SA(1, 0), a3, voffA);
;             PG8_WAIT_V(8); PG8_WAIT_L(0); PG8_BAR; PG8_MMA(1, 0, At, B0); PG8_MMA(1, 1, At, B1); PG8_BAR; PG8_SCHED;
.LBB0_146:
	ds_read_b128 v[26:29], v190
	ds_read_b128 v[30:33], v190 offset:1024
	ds_read_b128 v[18:21], v190 offset:2048
	ds_read_b128 v[22:25], v190 offset:3072
	ds_read_b128 v[10:13], v191
	ds_read_b128 v[14:17], v191 offset:1024
	ds_read_b128 v[2:5], v191 offset:2048
	ds_read_b128 v[6:9], v191 offset:3072
	s_add_u32 s40, s6, 0xfff80080
	s_addc_u32 s41, s7, -1
	s_cmp_eq_u32 s60, 28
	s_cselect_b32 s43, s29, s41
	s_cselect_b32 s42, s37, s40
	s_cselect_b32 s41, s27, s59
	s_cselect_b32 s40, s44, s45
	v_lshl_add_u64 v[218:219], s[6:7], 0, v[172:173]
	s_add_i32 m0, s39, 0xc000
	ds_read_b128 v[178:181], v192
	ds_read_b128 v[182:185], v192 offset:1024
	ds_read_b128 v[194:197], v192 offset:2048
	ds_read_b128 v[198:201], v192 offset:3072
	ds_read_b128 v[202:205], v192 offset:4096
	ds_read_b128 v[206:209], v192 offset:5120
	ds_read_b128 v[210:213], v192 offset:6144
	ds_read_b128 v[214:217], v192 offset:7168
	global_load_lds_dwordx4 v[218:219], off
	v_lshl_add_u64 v[218:219], s[6:7], 0, v[170:171]
	s_add_i32 m0, s39, 0xe000
	s_nop 0
	global_load_lds_dwordx4 v[218:219], off
	s_waitcnt vmcnt(8) lgkmcnt(0)
	s_setprio 1
	s_barrier
	v_mfma_scale_f32_16x16x128_f8f6f4 v[158:161], v[26:33], v[178:185], v[158:161], v186, v186 op_sel_hi:[0,0,0]
	v_mfma_scale_f32_16x16x128_f8f6f4 v[154:157], v[18:25], v[178:185], v[154:157], v186, v186 op_sel_hi:[0,0,0]
	v_mfma_scale_f32_16x16x128_f8f6f4 v[142:145], v[26:33], v[194:201], v[142:145], v186, v186 op_sel_hi:[0,0,0]
	v_mfma_scale_f32_16x16x128_f8f6f4 v[138:141], v[18:25], v[194:201], v[138:141], v186, v186 op_sel_hi:[0,0,0]
	v_mfma_scale_f32_16x16x128_f8f6f4 v[126:129], v[26:33], v[202:209], v[126:129], v186, v186 op_sel_hi:[0,0,0]
	v_mfma_scale_f32_16x16x128_f8f6f4 v[122:125], v[18:25], v[202:209], v[122:125], v186, v186 op_sel_hi:[0,0,0]
	v_mfma_scale_f32_16x16x128_f8f6f4 v[110:113], v[26:33], v[210:217], v[110:113], v186, v186 op_sel_hi:[0,0,0]
	v_mfma_scale_f32_16x16x128_f8f6f4 v[106:109], v[18:25], v[210:217], v[106:109], v186, v186 op_sel_hi:[0,0,0]
	v_mfma_scale_f32_16x16x128_f8f6f4 v[150:153], v[10:17], v[178:185], v[150:153], v186, v186 op_sel_hi:[0,0,0]
	v_mfma_scale_f32_16x16x128_f8f6f4 v[146:149], v[2:9], v[178:185], v[146:149], v186, v186 op_sel_hi:[0,0,0]
	v_mfma_scale_f32_16x16x128_f8f6f4 v[134:137], v[10:17], v[194:201], v[134:137], v186, v186 op_sel_hi:[0,0,0]
	v_mfma_scale_f32_16x16x128_f8f6f4 v[130:133], v[2:9], v[194:201], v[130:133], v186, v186 op_sel_hi:[0,0,0]
	v_mfma_scale_f32_16x16x128_f8f6f4 v[118:121], v[10:17], v[202:209], v[118:121], v186, v186 op_sel_hi:[0,0,0]
	v_mfma_scale_f32_16x16x128_f8f6f4 v[114:117], v[2:9], v[202:209], v[114:117], v186, v186 op_sel_hi:[0,0,0]
	v_mfma_scale_f32_16x16x128_f8f6f4 v[102:105], v[10:17], v[210:217], v[102:105], v186, v186 op_sel_hi:[0,0,0]
	v_mfma_scale_f32_16x16x128_f8f6f4 v[98:101], v[2:9], v[210:217], v[98:101], v186, v186 op_sel_hi:[0,0,0]
	s_barrier
	s_setprio 0
	s_add_i32 s61, s57, s47
	v_lshl_add_u64 v[178:179], s[40:41], 0, v[164:165]
	s_mov_b32 m0, s61
	ds_read_b128 v[194:197], v192 offset:16384
	ds_read_b128 v[198:201], v192 offset:17408
	ds_read_b128 v[202:205], v192 offset:18432
	ds_read_b128 v[206:209], v192 offset:19456
	ds_read_b128 v[210:213], v192 offset:20480
	ds_read_b128 v[214:217], v192 offset:21504
	ds_read_b128 v[218:221], v192 offset:22528
	ds_read_b128 v[222:225], v192 offset:23552
	global_load_lds_dwordx4 v[178:179], off
	s_add_i32 m0, s61, 0x2000
	s_add_u32 s62, s40, 0x80000
	v_lshl_add_u64 v[180:181], s[40:41], 0, v[168:169]
	s_addc_u32 s63, s41, 0
	s_add_i32 s61, s58, s47
	global_load_lds_dwordx4 v[180:181], off
	v_lshl_add_u64 v[182:183], s[62:63], 0, v[164:165]
	s_mov_b32 m0, s61
	v_lshl_add_u64 v[184:185], s[42:43], 0, v[166:167]
	global_load_lds_dwordx4 v[182:183], off
	v_lshl_add_u64 v[182:183], s[62:63], 0, v[168:169]
	s_add_i32 m0, s61, 0x2000
	s_nop 0
	global_load_lds_dwordx4 v[182:183], off
	v_lshl_add_u64 v[182:183], s[42:43], 0, v[162:163]
	s_mov_b32 m0, s39
	s_nop 0
	global_load_lds_dwordx4 v[182:183], off
	s_mov_b32 m0, s48
	s_nop 0
	global_load_lds_dwordx4 v[184:185], off
	s_waitcnt vmcnt(8) lgkmcnt(0)
	s_setprio 1
	s_barrier
	v_mfma_scale_f32_16x16x128_f8f6f4 v[94:97], v[26:33], v[194:201], v[94:97], v186, v186 op_sel_hi:[0,0,0]
	v_mfma_scale_f32_16x16x128_f8f6f4 v[90:93], v[18:25], v[194:201], v[90:93], v186, v186 op_sel_hi:[0,0,0]
	v_mfma_scale_f32_16x16x128_f8f6f4 v[78:81], v[26:33], v[202:209], v[78:81], v186, v186 op_sel_hi:[0,0,0]
	v_mfma_scale_f32_16x16x128_f8f6f4 v[74:77], v[18:25], v[202:209], v[74:77], v186, v186 op_sel_hi:[0,0,0]
	v_mfma_scale_f32_16x16x128_f8f6f4 v[62:65], v[26:33], v[210:217], v[62:65], v186, v186 op_sel_hi:[0,0,0]
	v_mfma_scale_f32_16x16x128_f8f6f4 v[58:61], v[18:25], v[210:217], v[58:61], v186, v186 op_sel_hi:[0,0,0]
	v_mfma_scale_f32_16x16x128_f8f6f4 v[46:49], v[26:33], v[218:225], v[46:49], v186, v186 op_sel_hi:[0,0,0]
	v_mfma_scale_f32_16x16x128_f8f6f4 v[42:45], v[18:25], v[218:225], v[42:45], v186, v186 op_sel_hi:[0,0,0]
	v_mfma_scale_f32_16x16x128_f8f6f4 v[86:89], v[10:17], v[194:201], v[86:89], v186, v186 op_sel_hi:[0,0,0]
	v_mfma_scale_f32_16x16x128_f8f6f4 v[82:85], v[2:9], v[194:201], v[82:85], v186, v186 op_sel_hi:[0,0,0]
	v_mfma_scale_f32_16x16x128_f8f6f4 v[70:73], v[10:17], v[202:209], v[70:73], v186, v186 op_sel_hi:[0,0,0]
	v_mfma_scale_f32_16x16x128_f8f6f4 v[66:69], v[2:9], v[202:209], v[66:69], v186, v186 op_sel_hi:[0,0,0]
	v_mfma_scale_f32_16x16x128_f8f6f4 v[54:57], v[10:17], v[210:217], v[54:57], v186, v186 op_sel_hi:[0,0,0]
	v_mfma_scale_f32_16x16x128_f8f6f4 v[50:53], v[2:9], v[210:217], v[50:53], v186, v186 op_sel_hi:[0,0,0]
	v_mfma_scale_f32_16x16x128_f8f6f4 v[38:41], v[10:17], v[218:225], v[38:41], v186, v186 op_sel_hi:[0,0,0]
	v_mfma_scale_f32_16x16x128_f8f6f4 v[34:37], v[2:9], v[218:225], v[34:37], v186, v186 op_sel_hi:[0,0,0]
	s_barrier
; #define PG8_STAGE(bufoff, gbase, voff) do { _Pragma("unroll") for (int _i = 0; _i < 2; ++_i) \
;         __builtin_amdgcn_global_load_lds((const unsigned*)((const char*)(gbase) + (voff)[_i]), (PG8_LAS unsigned*)(lds + (bufoff) + ldsw + _i * 8192), 16, 0, 0); } while (0)
; #define PG8_LDA(dst, b, h) do { _Pragma("unroll") for (int m = 0; m < 4; ++m) _Pragma("unroll") for (int k = 0; k < 2; ++k) dst[m][k] = *(const PG8_LAS bf16x8*)(lds + PG8_SA(b, h) + aoff + m * 2048 + k * 1024); } while (0)
; #define PG8_LDB(dst, b, h) do { _Pragma("unroll") for (int n = 0; n < 2; ++n) _Pragma("unroll") for (int k = 0; k < 2; ++k) dst[n][k] = *(const PG8_LAS bf16x8*)(lds + PG8_SB(b, h) + boff + n * 2048 + k * 1024); } while (0)
; #define PG8_WAIT_V(n) asm volatile("s_waitcnt vmcnt(" #n ")" ::: "memory")
; #define PG8_WAIT_L(n) asm volatile("s_waitcnt lgkmcnt(" #n ")" ::: "memory")
; #define PG8_BAR __builtin_amdgcn_s_barrier()
; #define PG8_SCHED __builtin_amdgcn_sched_barrier(0)
; template <class Epi, class Sched, bool ALIGN_EPI = false, bool SP2 = false, bool F8 = false>
; __device__ __forceinline__ void gemm_phase(PG8_LAS unsigned char* lds, const Gemm g, const Sched& S, const Epi& E) {
;     ...
;             PG8_LDB(B0, 0, 0); PG8_LDB(B1, 0, 1); PG8_SCHED; PG8_LDA(At, 0, 0); PG8_STAGE(PG8_SA(1, 1), a1 + hA, voffA);
;             PG8_WAIT_V(8); PG8_WAIT_L(0); PG8_BAR; PG8_MMA(0, 0, At, B0); PG8_MMA(0, 1, At, B1); PG8_BAR; PG8_SCHED;
;             PG8_LDA(At, 0, 1); PG8_STAGE(PG8_SB(0, 0), b2, voffB); PG8_STAGE(PG8_SB(0, 1), b2 + hB, voffB); PG8_STAGE(PG8_SA(0, 0), a2, voffA);
;             PG8_WAIT_V(8); PG8_WAIT_L(0); PG8_BAR; PG8_MMA(1, 0, At, B0); PG8_MMA(1, 1, At, B1); PG8_BAR; PG8_SCHED;
;             PG8_LDB(B0, 1, 0); PG8_LDB(B1, 1, 1); PG8_SCHED; PG8_LDA(At, 1, 0); PG8_STAGE(PG8_SA(0, 1), a2 + hA, voffA);
;             PG8_WAIT_V(8); PG8_WAIT_L(0); PG8_BAR; PG8_MMA(0, 0, At, B0); PG8_MMA(0, 1, At, B1); PG8_BAR; PG8_SCHED;
;             PG8_LDA(At, 1, 1); PG8_STAGE(PG8_SB(1, 0), b3, voffB); PG8_STAGE(PG8_SB(1, 1), b3 + hB, voffB); PG8_STAGE(PG8_SA(1, 0), a3, voffA);
;             PG8_WAIT_V(8); PG8_WAIT_L(0); PG8_BAR; PG8_MMA(1, 0, At, B0); PG8_MMA(1, 1, At, B1); PG8_BAR; PG8_SCHED;
	s_setprio 0
	s_add_i32 s61, 0, 0x18000
	s_add_i32 s62, 0, 0x1c000
	v_add_u32_e32 v14, s61, v188
	v_add_u32_e32 v30, s62, v188
	ds_read_b128 v[2:5], v14
	ds_read_b128 v[6:9], v14 offset:1024
	ds_read_b128 v[10:13], v14 offset:2048
	ds_read_b128 v[14:17], v14 offset:3072
	ds_read_b128 v[18:21], v30
	ds_read_b128 v[22:25], v30 offset:1024
	ds_read_b128 v[26:29], v30 offset:2048
	ds_read_b128 v[30:33], v30 offset:3072
	s_add_u32 s42, s42, 0x80000
	s_addc_u32 s43, s43, 0
	s_mov_b32 m0, s49
	v_lshl_add_u64 v[226:227], s[42:43], 0, v[162:163]
	ds_read_b128 v[194:197], v192 offset:32768
	ds_read_b128 v[198:201], v192 offset:33792
	ds_read_b128 v[202:205], v192 offset:34816
	ds_read_b128 v[206:209], v192 offset:35840
	ds_read_b128 v[210:213], v192 offset:36864
	ds_read_b128 v[214:217], v192 offset:37888
	ds_read_b128 v[218:221], v192 offset:38912
	ds_read_b128 v[222:225], v192 offset:39936
	global_load_lds_dwordx4 v[226:227], off
	v_lshl_add_u64 v[226:227], s[42:43], 0, v[166:167]
	s_mov_b32 m0, s50
	s_nop 0
	global_load_lds_dwordx4 v[226:227], off
	s_waitcnt vmcnt(8) lgkmcnt(0)
	s_setprio 1
	s_barrier
	v_mfma_scale_f32_16x16x128_f8f6f4 v[158:161], v[2:9], v[194:201], v[158:161], v186, v186 op_sel_hi:[0,0,0]
	v_mfma_scale_f32_16x16x128_f8f6f4 v[154:157], v[10:17], v[194:201], v[154:157], v186, v186 op_sel_hi:[0,0,0]
	v_mfma_scale_f32_16x16x128_f8f6f4 v[142:145], v[2:9], v[202:209], v[142:145], v186, v186 op_sel_hi:[0,0,0]
	v_mfma_scale_f32_16x16x128_f8f6f4 v[138:141], v[10:17], v[202:209], v[138:141], v186, v186 op_sel_hi:[0,0,0]
	v_mfma_scale_f32_16x16x128_f8f6f4 v[126:129], v[2:9], v[210:217], v[126:129], v186, v186 op_sel_hi:[0,0,0]
	v_mfma_scale_f32_16x16x128_f8f6f4 v[122:125], v[10:17], v[210:217], v[122:125], v186, v186 op_sel_hi:[0,0,0]
	v_mfma_scale_f32_16x16x128_f8f6f4 v[110:113], v[2:9], v[218:225], v[110:113], v186, v186 op_sel_hi:[0,0,0]
	v_mfma_scale_f32_16x16x128_f8f6f4 v[106:109], v[10:17], v[218:225], v[106:109], v186, v186 op_sel_hi:[0,0,0]
	v_mfma_scale_f32_16x16x128_f8f6f4 v[150:153], v[18:25], v[194:201], v[150:153], v186, v186 op_sel_hi:[0,0,0]
	v_mfma_scale_f32_16x16x128_f8f6f4 v[146:149], v[26:33], v[194:201], v[146:149], v186, v186 op_sel_hi:[0,0,0]
	v_mfma_scale_f32_16x16x128_f8f6f4 v[134:137], v[18:25], v[202:209], v[134:137], v186, v186 op_sel_hi:[0,0,0]
	v_mfma_scale_f32_16x16x128_f8f6f4 v[130:133], v[26:33], v[202:209], v[130:133], v186, v186 op_sel_hi:[0,0,0]
	v_mfma_scale_f32_16x16x128_f8f6f4 v[118:121], v[18:25], v[210:217], v[118:121], v186, v186 op_sel_hi:[0,0,0]
	v_mfma_scale_f32_16x16x128_f8f6f4 v[114:117], v[26:33], v[210:217], v[114:117], v186, v186 op_sel_hi:[0,0,0]
	v_mfma_scale_f32_16x16x128_f8f6f4 v[102:105], v[18:25], v[218:225], v[102:105], v186, v186 op_sel_hi:[0,0,0]
	v_mfma_scale_f32_16x16x128_f8f6f4 v[98:101], v[26:33], v[218:225], v[98:101], v186, v186 op_sel_hi:[0,0,0]
	s_barrier
	s_setprio 0
	s_add_i32 s42, s61, s47
	v_lshl_add_u64 v[178:179], v[178:179], 0, s[22:23]
	s_mov_b32 m0, s42
	ds_read_b128 v[194:197], v192 offset:49152
	ds_read_b128 v[198:201], v192 offset:50176
	ds_read_b128 v[202:205], v192 offset:51200
	ds_read_b128 v[206:209], v192 offset:52224
	ds_read_b128 v[210:213], v192 offset:53248
	ds_read_b128 v[214:217], v192 offset:54272
	ds_read_b128 v[218:221], v192 offset:55296
	ds_read_b128 v[222:225], v192 offset:56320
	global_load_lds_dwordx4 v[178:179], off
	s_add_i32 m0, s42, 0x2000
	s_add_u32 s40, s40, 0x80080
	v_lshl_add_u64 v[178:179], v[180:181], 0, s[22:23]
	s_addc_u32 s41, s41, 0
	s_add_i32 s42, s62, s47
	global_load_lds_dwordx4 v[178:179], off
	v_lshl_add_u64 v[178:179], s[40:41], 0, v[164:165]
	s_mov_b32 m0, s42
	s_nop 0
	global_load_lds_dwordx4 v[178:179], off
	v_lshl_add_u64 v[178:179], s[40:41], 0, v[168:169]
	s_add_i32 m0, s42, 0x2000
	s_nop 0
	global_load_lds_dwordx4 v[178:179], off
	v_lshl_add_u64 v[178:179], v[182:183], 0, s[22:23]
	s_mov_b32 m0, s52
	s_nop 0
	global_load_lds_dwordx4 v[178:179], off
	v_lshl_add_u64 v[178:179], v[184:185], 0, s[22:23]
	s_mov_b32 m0, s53
	s_nop 0
	global_load_lds_dwordx4 v[178:179], off
	s_waitcnt vmcnt(8) lgkmcnt(0)
	s_setprio 1
	s_barrier
	v_mfma_scale_f32_16x16x128_f8f6f4 v[94:97], v[2:9], v[194:201], v[94:97], v186, v186 op_sel_hi:[0,0,0]
	v_mfma_scale_f32_16x16x128_f8f6f4 v[90:93], v[10:17], v[194:201], v[90:93], v186, v186 op_sel_hi:[0,0,0]
	v_mfma_scale_f32_16x16x128_f8f6f4 v[78:81], v[2:9], v[202:209], v[78:81], v186, v186 op_sel_hi:[0,0,0]
	v_mfma_scale_f32_16x16x128_f8f6f4 v[74:77], v[10:17], v[202:209], v[74:77], v186, v186 op_sel_hi:[0,0,0]
	v_mfma_scale_f32_16x16x128_f8f6f4 v[62:65], v[2:9], v[210:217], v[62:65], v186, v186 op_sel_hi:[0,0,0]
	v_mfma_scale_f32_16x16x128_f8f6f4 v[58:61], v[10:17], v[210:217], v[58:61], v186, v186 op_sel_hi:[0,0,0]
	v_mfma_scale_f32_16x16x128_f8f6f4 v[46:49], v[2:9], v[218:225], v[46:49], v186, v186 op_sel_hi:[0,0,0]
	v_mfma_scale_f32_16x16x128_f8f6f4 v[42:45], v[10:17], v[218:225], v[42:45], v186, v186 op_sel_hi:[0,0,0]
	v_mfma_scale_f32_16x16x128_f8f6f4 v[86:89], v[18:25], v[194:201], v[86:89], v186, v186 op_sel_hi:[0,0,0]
	v_mfma_scale_f32_16x16x128_f8f6f4 v[82:85], v[26:33], v[194:201], v[82:85], v186, v186 op_sel_hi:[0,0,0]
	v_mfma_scale_f32_16x16x128_f8f6f4 v[70:73], v[18:25], v[202:209], v[70:73], v186, v186 op_sel_hi:[0,0,0]
	v_mfma_scale_f32_16x16x128_f8f6f4 v[66:69], v[26:33], v[202:209], v[66:69], v186, v186 op_sel_hi:[0,0,0]
	v_mfma_scale_f32_16x16x128_f8f6f4 v[54:57], v[18:25], v[210:217], v[54:57], v186, v186 op_sel_hi:[0,0,0]
	v_mfma_scale_f32_16x16x128_f8f6f4 v[50:53], v[26:33], v[210:217], v[50:53], v186, v186 op_sel_hi:[0,0,0]
	v_mfma_scale_f32_16x16x128_f8f6f4 v[38:41], v[18:25], v[218:225], v[38:41], v186, v186 op_sel_hi:[0,0,0]
	v_mfma_scale_f32_16x16x128_f8f6f4 v[34:37], v[26:33], v[218:225], v[34:37], v186, v186 op_sel_hi:[0,0,0]
	s_barrier
	s_setprio 0
	s_add_i32 s60, s60, 2
	s_add_u32 s45, s45, 0x100
	s_addc_u32 s59, s59, 0
	s_add_u32 s6, s6, 0x100
	s_addc_u32 s7, s7, 0
	s_cmp_gt_u32 s60, 29
	s_cbranch_scc0 .LBB0_146
	s_and_b64 vcc, exec, s[24:25]
	s_cbranch_vccz .LBB0_149
	s_barrier

; #define PG8_STAGE(bufoff, gbase, voff) do { _Pragma("unroll") for (int _i = 0; _i < 2; ++_i) \
;         __builtin_amdgcn_global_load_lds((const unsigned*)((const char*)(gbase) + (voff)[_i]), (PG8_LAS unsigned*)(lds + (bufoff) + ldsw + _i * 8192), 16, 0, 0); } while (0)
; #define PG8_LDA(dst, b, h) do { _Pragma("unroll") for (int m = 0; m < 4; ++m) _Pragma("unroll") for (int k = 0; k < 2; ++k) dst[m][k] = *(const PG8_LAS bf16x8*)(lds + PG8_SA(b, h) + aoff + m * 2048 + k * 1024); } while (0)
; #define PG8_LDB(dst, b, h) do { _Pragma("unroll") for (int n = 0; n < 2; ++n) _Pragma("unroll") for (int k = 0; k < 2; ++k) dst[n][k] = *(const PG8_LAS bf16x8*)(lds + PG8_SB(b, h) + boff + n * 2048 + k * 1024); } while (0)
; #define PG8_WAIT_V(n) asm volatile("s_waitcnt vmcnt(" #n ")" ::: "memory")
; #define PG8_WAIT_L(n) asm volatile("s_waitcnt lgkmcnt(" #n ")" ::: "memory")
; #define PG8_BAR __builtin_amdgcn_s_barrier()
; #define PG8_SCHED __builtin_amdgcn_sched_barrier(0)
; template <class Epi, class Sched, bool ALIGN_EPI = false, bool SP2 = false, bool F8 = false>
; __device__ __forceinline__ void gemm_phase(PG8_LAS unsigned char* lds, const Gemm g, const Sched& S, const Epi& E) {
;     ...
;             PG8_LDB(B0, 0, 0); PG8_LDB(B1, 0, 1); PG8_SCHED; PG8_LDA(At, 0, 0); PG8_STAGE(PG8_SA(1, 1), a1 + hA, voffA);
;             PG8_WAIT_V(8); PG8_WAIT_L(0); PG8_BAR; PG8_MMA(0, 0, At, B0); PG8_MMA(0, 1, At, B1); PG8_BAR; PG8_SCHED;
;             PG8_LDA(At, 0, 1); PG8_STAGE(PG8_SB(0, 0), b2, voffB); PG8_STAGE(PG8_SB(0, 1), b2 + hB, voffB); PG8_STAGE(PG8_SA(0, 0), a2, voffA);
;             PG8_WAIT_V(8); PG8_WAIT_L(0); PG8_BAR; PG8_MMA(1, 0, At, B0); PG8_MMA(1, 1, At, B1); PG8_BAR; PG8_SCHED;
;             PG8_LDB(B0, 1, 0); PG8_LDB(B1, 1, 1); PG8_SCHED; PG8_LDA(At, 1, 0); PG8_STAGE(PG8_SA(0, 1), a2 + hA, voffA);
;             PG8_WAIT_V(8); PG8_WAIT_L(0); PG8_BAR; PG8_MMA(0, 0, At, B0); PG8_MMA(0, 1, At, B1); PG8_BAR; PG8_SCHED;
;             PG8_LDA(At, 1, 1); PG8_STAGE(PG8_SB(1, 0), b3, voffB); PG8_STAGE(PG8_SB(1, 1), b3 + hB, voffB); PG8_STAGE(PG8_SA(1, 0), a3, voffA);
;             PG8_WAIT_V(8); PG8_WAIT_L(0); PG8_BAR; PG8_MMA(1, 0, At, B0); PG8_MMA(1, 1, At, B1); PG8_BAR; PG8_SCHED;
.LBB0_618:
	ds_read_b128 v[130:133], v185
	ds_read_b128 v[134:137], v185 offset:1024
	ds_read_b128 v[138:141], v185 offset:2048
	ds_read_b128 v[142:145], v185 offset:3072
	ds_read_b128 v[146:149], v186
	ds_read_b128 v[150:153], v186 offset:1024
	ds_read_b128 v[154:157], v186 offset:2048
	ds_read_b128 v[174:177], v186 offset:3072
	s_add_u32 s40, s38, 0xfff80080
	s_addc_u32 s41, s39, -1
	s_cmp_eq_u32 s59, 4
	s_cselect_b32 s43, s29, s41
	s_cselect_b32 s42, s55, s40
	s_cselect_b32 s41, s27, s58
	s_cselect_b32 s40, s56, s57
	v_lshl_add_u64 v[216:217], s[38:39], 0, v[168:169]
	s_add_i32 m0, s37, 0xc000
	ds_read_b128 v[178:181], v187
	ds_read_b128 v[188:191], v187 offset:1024
	ds_read_b128 v[192:195], v187 offset:2048
	ds_read_b128 v[196:199], v187 offset:3072
	ds_read_b128 v[200:203], v187 offset:4096
	ds_read_b128 v[204:207], v187 offset:5120
	ds_read_b128 v[208:211], v187 offset:6144
	ds_read_b128 v[212:215], v187 offset:7168
	global_load_lds_dwordx4 v[216:217], off
	v_lshl_add_u64 v[216:217], s[38:39], 0, v[166:167]
	s_add_i32 m0, s37, 0xe000
	s_nop 0
	global_load_lds_dwordx4 v[216:217], off
	s_waitcnt vmcnt(8) lgkmcnt(0)
	s_setprio 1
	s_barrier
	v_mfma_f32_16x16x32_bf16 v[126:129], v[130:133], v[178:181], v[126:129]
	v_mfma_f32_16x16x32_bf16 v[122:125], v[138:141], v[178:181], v[122:125]
	v_mfma_f32_16x16x32_bf16 v[110:113], v[130:133], v[192:195], v[110:113]
	v_mfma_f32_16x16x32_bf16 v[106:109], v[138:141], v[192:195], v[106:109]
	v_mfma_f32_16x16x32_bf16 v[94:97], v[130:133], v[200:203], v[94:97]
	v_mfma_f32_16x16x32_bf16 v[90:93], v[138:141], v[200:203], v[90:93]
	v_mfma_f32_16x16x32_bf16 v[78:81], v[130:133], v[208:211], v[78:81]
	v_mfma_f32_16x16x32_bf16 v[74:77], v[138:141], v[208:211], v[74:77]
	v_mfma_f32_16x16x32_bf16 v[126:129], v[134:137], v[188:191], v[126:129]
	v_mfma_f32_16x16x32_bf16 v[122:125], v[142:145], v[188:191], v[122:125]
	v_mfma_f32_16x16x32_bf16 v[110:113], v[134:137], v[196:199], v[110:113]
	v_mfma_f32_16x16x32_bf16 v[106:109], v[142:145], v[196:199], v[106:109]
	v_mfma_f32_16x16x32_bf16 v[94:97], v[134:137], v[204:207], v[94:97]
	v_mfma_f32_16x16x32_bf16 v[90:93], v[142:145], v[204:207], v[90:93]
	v_mfma_f32_16x16x32_bf16 v[78:81], v[134:137], v[212:215], v[78:81]
	v_mfma_f32_16x16x32_bf16 v[74:77], v[142:145], v[212:215], v[74:77]
	v_mfma_f32_16x16x32_bf16 v[118:121], v[146:149], v[178:181], v[118:121]
	v_mfma_f32_16x16x32_bf16 v[114:117], v[154:157], v[178:181], v[114:117]
	v_mfma_f32_16x16x32_bf16 v[102:105], v[146:149], v[192:195], v[102:105]
	v_mfma_f32_16x16x32_bf16 v[98:101], v[154:157], v[192:195], v[98:101]
	v_mfma_f32_16x16x32_bf16 v[86:89], v[146:149], v[200:203], v[86:89]
	v_mfma_f32_16x16x32_bf16 v[82:85], v[154:157], v[200:203], v[82:85]
	v_mfma_f32_16x16x32_bf16 v[70:73], v[146:149], v[208:211], v[70:73]
	v_mfma_f32_16x16x32_bf16 v[66:69], v[154:157], v[208:211], v[66:69]
	v_mfma_f32_16x16x32_bf16 v[118:121], v[150:153], v[188:191], v[118:121]
	v_mfma_f32_16x16x32_bf16 v[114:117], v[174:177], v[188:191], v[114:117]
	v_mfma_f32_16x16x32_bf16 v[102:105], v[150:153], v[196:199], v[102:105]
	v_mfma_f32_16x16x32_bf16 v[98:101], v[174:177], v[196:199], v[98:101]
	v_mfma_f32_16x16x32_bf16 v[86:89], v[150:153], v[204:207], v[86:89]
	v_mfma_f32_16x16x32_bf16 v[82:85], v[174:177], v[204:207], v[82:85]
	v_mfma_f32_16x16x32_bf16 v[70:73], v[150:153], v[212:215], v[70:73]
	v_mfma_f32_16x16x32_bf16 v[66:69], v[174:177], v[212:215], v[66:69]
	s_barrier
	s_setprio 0
	s_add_i32 s60, s52, s19
	v_lshl_add_u64 v[216:217], s[40:41], 0, v[162:163]
	s_mov_b32 m0, s60
	ds_read_b128 v[178:181], v187 offset:16384
	ds_read_b128 v[188:191], v187 offset:17408
	ds_read_b128 v[192:195], v187 offset:18432
	ds_read_b128 v[196:199], v187 offset:19456
	ds_read_b128 v[200:203], v187 offset:20480
	ds_read_b128 v[204:207], v187 offset:21504
	ds_read_b128 v[208:211], v187 offset:22528
	ds_read_b128 v[212:215], v187 offset:23552
	global_load_lds_dwordx4 v[216:217], off
	s_add_i32 m0, s60, 0x2000
	s_add_u32 s60, s40, 0x20000
	v_lshl_add_u64 v[218:219], s[40:41], 0, v[158:159]
	s_addc_u32 s61, s41, 0
	s_add_i32 s62, s53, s19
	global_load_lds_dwordx4 v[218:219], off
	v_lshl_add_u64 v[220:221], s[60:61], 0, v[162:163]
	s_mov_b32 m0, s62
	v_lshl_add_u64 v[222:223], s[42:43], 0, v[160:161]
	global_load_lds_dwordx4 v[220:221], off
	v_lshl_add_u64 v[220:221], s[60:61], 0, v[158:159]
	s_add_i32 m0, s62, 0x2000
	s_nop 0
	global_load_lds_dwordx4 v[220:221], off
	v_lshl_add_u64 v[220:221], s[42:43], 0, v[164:165]
	s_mov_b32 m0, s37
	s_nop 0
	global_load_lds_dwordx4 v[220:221], off
	s_mov_b32 m0, s45
	s_nop 0
	global_load_lds_dwordx4 v[222:223], off
	s_waitcnt vmcnt(8) lgkmcnt(0)
	s_setprio 1
	s_barrier
; #define PG8_STAGE(bufoff, gbase, voff) do { _Pragma("unroll") for (int _i = 0; _i < 2; ++_i) \
;         __builtin_amdgcn_global_load_lds((const unsigned*)((const char*)(gbase) + (voff)[_i]), (PG8_LAS unsigned*)(lds + (bufoff) + ldsw + _i * 8192), 16, 0, 0); } while (0)
; #define PG8_LDA(dst, b, h) do { _Pragma("unroll") for (int m = 0; m < 4; ++m) _Pragma("unroll") for (int k = 0; k < 2; ++k) dst[m][k] = *(const PG8_LAS bf16x8*)(lds + PG8_SA(b, h) + aoff + m * 2048 + k * 1024); } while (0)
; #define PG8_LDB(dst, b, h) do { _Pragma("unroll") for (int n = 0; n < 2; ++n) _Pragma("unroll") for (int k = 0; k < 2; ++k) dst[n][k] = *(const PG8_LAS bf16x8*)(lds + PG8_SB(b, h) + boff + n * 2048 + k * 1024); } while (0)
; #define PG8_WAIT_V(n) asm volatile("s_waitcnt vmcnt(" #n ")" ::: "memory")
; #define PG8_WAIT_L(n) asm volatile("s_waitcnt lgkmcnt(" #n ")" ::: "memory")
; #define PG8_BAR __builtin_amdgcn_s_barrier()
; #define PG8_SCHED __builtin_amdgcn_sched_barrier(0)
; template <class Epi, class Sched, bool ALIGN_EPI = false, bool SP2 = false, bool F8 = false>
; __device__ __forceinline__ void gemm_phase(PG8_LAS unsigned char* lds, const Gemm g, const Sched& S, const Epi& E) {
;     ...
;             PG8_LDB(B0, 0, 0); PG8_LDB(B1, 0, 1); PG8_SCHED; PG8_LDA(At, 0, 0); PG8_STAGE(PG8_SA(1, 1), a1 + hA, voffA);
;             PG8_WAIT_V(8); PG8_WAIT_L(0); PG8_BAR; PG8_MMA(0, 0, At, B0); PG8_MMA(0, 1, At, B1); PG8_BAR; PG8_SCHED;
;             PG8_LDA(At, 0, 1); PG8_STAGE(PG8_SB(0, 0), b2, voffB); PG8_STAGE(PG8_SB(0, 1), b2 + hB, voffB); PG8_STAGE(PG8_SA(0, 0), a2, voffA);
;             PG8_WAIT_V(8); PG8_WAIT_L(0); PG8_BAR; PG8_MMA(1, 0, At, B0); PG8_MMA(1, 1, At, B1); PG8_BAR; PG8_SCHED;
;             PG8_LDB(B0, 1, 0); PG8_LDB(B1, 1, 1); PG8_SCHED; PG8_LDA(At, 1, 0); PG8_STAGE(PG8_SA(0, 1), a2 + hA, voffA);
;             PG8_WAIT_V(8); PG8_WAIT_L(0); PG8_BAR; PG8_MMA(0, 0, At, B0); PG8_MMA(0, 1, At, B1); PG8_BAR; PG8_SCHED;
;             PG8_LDA(At, 1, 1); PG8_STAGE(PG8_SB(1, 0), b3, voffB); PG8_STAGE(PG8_SB(1, 1), b3 + hB, voffB); PG8_STAGE(PG8_SA(1, 0), a3, voffA);
;             PG8_WAIT_V(8); PG8_WAIT_L(0); PG8_BAR; PG8_MMA(1, 0, At, B0); PG8_MMA(1, 1, At, B1); PG8_BAR; PG8_SCHED;
	v_mfma_f32_16x16x32_bf16 v[62:65], v[130:133], v[178:181], v[62:65]
	v_mfma_f32_16x16x32_bf16 v[58:61], v[138:141], v[178:181], v[58:61]
	v_mfma_f32_16x16x32_bf16 v[46:49], v[130:133], v[192:195], v[46:49]
	v_mfma_f32_16x16x32_bf16 v[42:45], v[138:141], v[192:195], v[42:45]
	v_mfma_f32_16x16x32_bf16 v[30:33], v[130:133], v[200:203], v[30:33]
	v_mfma_f32_16x16x32_bf16 v[26:29], v[138:141], v[200:203], v[26:29]
	v_mfma_f32_16x16x32_bf16 v[14:17], v[130:133], v[208:211], v[14:17]
	v_mfma_f32_16x16x32_bf16 v[10:13], v[138:141], v[208:211], v[10:13]
	v_mfma_f32_16x16x32_bf16 v[62:65], v[134:137], v[188:191], v[62:65]
	v_mfma_f32_16x16x32_bf16 v[58:61], v[142:145], v[188:191], v[58:61]
	v_mfma_f32_16x16x32_bf16 v[46:49], v[134:137], v[196:199], v[46:49]
	v_mfma_f32_16x16x32_bf16 v[42:45], v[142:145], v[196:199], v[42:45]
	v_mfma_f32_16x16x32_bf16 v[30:33], v[134:137], v[204:207], v[30:33]
	v_mfma_f32_16x16x32_bf16 v[26:29], v[142:145], v[204:207], v[26:29]
	v_mfma_f32_16x16x32_bf16 v[14:17], v[134:137], v[212:215], v[14:17]
	v_mfma_f32_16x16x32_bf16 v[10:13], v[142:145], v[212:215], v[10:13]
	v_mfma_f32_16x16x32_bf16 v[54:57], v[146:149], v[178:181], v[54:57]
	v_mfma_f32_16x16x32_bf16 v[50:53], v[154:157], v[178:181], v[50:53]
	v_mfma_f32_16x16x32_bf16 v[38:41], v[146:149], v[192:195], v[38:41]
	v_mfma_f32_16x16x32_bf16 v[34:37], v[154:157], v[192:195], v[34:37]
	v_mfma_f32_16x16x32_bf16 v[22:25], v[146:149], v[200:203], v[22:25]
	v_mfma_f32_16x16x32_bf16 v[18:21], v[154:157], v[200:203], v[18:21]
	v_mfma_f32_16x16x32_bf16 v[6:9], v[146:149], v[208:211], v[6:9]
	v_mfma_f32_16x16x32_bf16 v[2:5], v[154:157], v[208:211], v[2:5]
	v_mfma_f32_16x16x32_bf16 v[54:57], v[150:153], v[188:191], v[54:57]
	v_mfma_f32_16x16x32_bf16 v[50:53], v[174:177], v[188:191], v[50:53]
	v_mfma_f32_16x16x32_bf16 v[38:41], v[150:153], v[196:199], v[38:41]
	v_mfma_f32_16x16x32_bf16 v[34:37], v[174:177], v[196:199], v[34:37]
	v_mfma_f32_16x16x32_bf16 v[22:25], v[150:153], v[204:207], v[22:25]
	v_mfma_f32_16x16x32_bf16 v[18:21], v[174:177], v[204:207], v[18:21]
	v_mfma_f32_16x16x32_bf16 v[6:9], v[150:153], v[212:215], v[6:9]
	v_mfma_f32_16x16x32_bf16 v[2:5], v[174:177], v[212:215], v[2:5]
	s_barrier
	s_setprio 0
	s_add_i32 s60, 0, 0x18000
	s_add_i32 s61, 0, 0x1c000
	v_add_u32_e32 v142, s60, v183
	v_add_u32_e32 v174, s61, v183
	ds_read_b128 v[130:133], v142
	ds_read_b128 v[134:137], v142 offset:1024
	ds_read_b128 v[138:141], v142 offset:2048
	ds_read_b128 v[142:145], v142 offset:3072
	ds_read_b128 v[146:149], v174
	ds_read_b128 v[150:153], v174 offset:1024
	ds_read_b128 v[154:157], v174 offset:2048
	ds_read_b128 v[174:177], v174 offset:3072
	s_add_u32 s42, s42, 0x80000
	s_addc_u32 s43, s43, 0
	s_mov_b32 m0, s46
	v_lshl_add_u64 v[224:225], s[42:43], 0, v[164:165]
	ds_read_b128 v[178:181], v187 offset:32768
	ds_read_b128 v[188:191], v187 offset:33792
	ds_read_b128 v[192:195], v187 offset:34816
	ds_read_b128 v[196:199], v187 offset:35840
	ds_read_b128 v[200:203], v187 offset:36864
	ds_read_b128 v[204:207], v187 offset:37888
	ds_read_b128 v[208:211], v187 offset:38912
	ds_read_b128 v[212:215], v187 offset:39936
	global_load_lds_dwordx4 v[224:225], off
	v_lshl_add_u64 v[224:225], s[42:43], 0, v[160:161]
	s_mov_b32 m0, s47
	s_nop 0
	global_load_lds_dwordx4 v[224:225], off
	s_waitcnt vmcnt(8) lgkmcnt(0)
	s_setprio 1
	s_barrier
	v_mfma_f32_16x16x32_bf16 v[126:129], v[130:133], v[178:181], v[126:129]
	v_mfma_f32_16x16x32_bf16 v[122:125], v[138:141], v[178:181], v[122:125]
	v_mfma_f32_16x16x32_bf16 v[110:113], v[130:133], v[192:195], v[110:113]
	v_mfma_f32_16x16x32_bf16 v[106:109], v[138:141], v[192:195], v[106:109]
	v_mfma_f32_16x16x32_bf16 v[94:97], v[130:133], v[200:203], v[94:97]
	v_mfma_f32_16x16x32_bf16 v[90:93], v[138:141], v[200:203], v[90:93]
	v_mfma_f32_16x16x32_bf16 v[78:81], v[130:133], v[208:211], v[78:81]
	v_mfma_f32_16x16x32_bf16 v[74:77], v[138:141], v[208:211], v[74:77]
	v_mfma_f32_16x16x32_bf16 v[126:129], v[134:137], v[188:191], v[126:129]
	v_mfma_f32_16x16x32_bf16 v[122:125], v[142:145], v[188:191], v[122:125]
	v_mfma_f32_16x16x32_bf16 v[110:113], v[134:137], v[196:199], v[110:113]
	v_mfma_f32_16x16x32_bf16 v[106:109], v[142:145], v[196:199], v[106:109]
	v_mfma_f32_16x16x32_bf16 v[94:97], v[134:137], v[204:207], v[94:97]
	v_mfma_f32_16x16x32_bf16 v[90:93], v[142:145], v[204:207], v[90:93]
	v_mfma_f32_16x16x32_bf16 v[78:81], v[134:137], v[212:215], v[78:81]
	v_mfma_f32_16x16x32_bf16 v[74:77], v[142:145], v[212:215], v[74:77]
	v_mfma_f32_16x16x32_bf16 v[118:121], v[146:149], v[178:181], v[118:121]
	v_mfma_f32_16x16x32_bf16 v[114:117], v[154:157], v[178:181], v[114:117]
	v_mfma_f32_16x16x32_bf16 v[102:105], v[146:149], v[192:195], v[102:105]
	v_mfma_f32_16x16x32_bf16 v[98:101], v[154:157], v[192:195], v[98:101]
	v_mfma_f32_16x16x32_bf16 v[86:89], v[146:149], v[200:203], v[86:89]
	v_mfma_f32_16x16x32_bf16 v[82:85], v[154:157], v[200:203], v[82:85]
	v_mfma_f32_16x16x32_bf16 v[70:73], v[146:149], v[208:211], v[70:73]
	v_mfma_f32_16x16x32_bf16 v[66:69], v[154:157], v[208:211], v[66:69]
	v_mfma_f32_16x16x32_bf16 v[118:121], v[150:153], v[188:191], v[118:121]
	v_mfma_f32_16x16x32_bf16 v[114:117], v[174:177], v[188:191], v[114:117]
	v_mfma_f32_16x16x32_bf16 v[102:105], v[150:153], v[196:199], v[102:105]
	v_mfma_f32_16x16x32_bf16 v[98:101], v[174:177], v[196:199], v[98:101]
	v_mfma_f32_16x16x32_bf16 v[86:89], v[150:153], v[204:207], v[86:89]
	v_mfma_f32_16x16x32_bf16 v[82:85], v[174:177], v[204:207], v[82:85]
	v_mfma_f32_16x16x32_bf16 v[70:73], v[150:153], v[212:215], v[70:73]
	v_mfma_f32_16x16x32_bf16 v[66:69], v[174:177], v[212:215], v[66:69]
	s_barrier
; #define PG8_GAS __attribute__((address_space(1)))
; #define PG8_STAGE(bufoff, gbase, voff) do { _Pragma("unroll") for (int _i = 0; _i < 2; ++_i) \
;         __builtin_amdgcn_global_load_lds((const unsigned*)((const char*)(gbase) + (voff)[_i]), (PG8_LAS unsigned*)(lds + (bufoff) + ldsw + _i * 8192), 16, 0, 0); } while (0)
; #define PG8_LDA(dst, b, h) do { _Pragma("unroll") for (int m = 0; m < 4; ++m) _Pragma("unroll") for (int k = 0; k < 2; ++k) dst[m][k] = *(const PG8_LAS bf16x8*)(lds + PG8_SA(b, h) + aoff + m * 2048 + k * 1024); } while (0)
; #define PG8_WAIT_V(n) asm volatile("s_waitcnt vmcnt(" #n ")" ::: "memory")
; #define PG8_WAIT_L(n) asm volatile("s_waitcnt lgkmcnt(" #n ")" ::: "memory")
; #define PG8_BAR __builtin_amdgcn_s_barrier()
; #define PG8_SCHED __builtin_amdgcn_sched_barrier(0)
;     __device__ __forceinline__ void operator()(const f32x4 (&acc)[2][2][4][2], const Unit& un, int wr, int wc, int fr, int fq) const {
;         const int row0 = un.pm * BM + wr * 64 + fr, col0 = un.pn * BM + wc * 32 + 8 * fq;
;         f32x4 sc[2][2];
; #pragma unroll
;         for (int bj = 0; bj < 2; ++bj)
; #pragma unroll
;             for (int n = 0; n < 2; ++n) sc[bj][n] = *(const PG8_GAS f32x4*)(ps + col0 + bj * HALF + 4 * n);
; #pragma unroll
;         for (int ai = 0; ai < 2; ++ai) {
;             u32x4 gg[4][2];
; #pragma unroll
;             for (int m = 0; m < 4; ++m)
; #pragma unroll
;                 for (int bj = 0; bj < 2; ++bj) gg[m][bj] = *(const PG8_GAS u32x4*)(sp + (size_t)(row0 + ai * HALF + m * 16) * 4096 + col0 + bj * HALF);
; template <class Epi, class Sched, bool ALIGN_EPI = false, bool SP2 = false, bool F8 = false>
; __device__ __forceinline__ void gemm_phase(PG8_LAS unsigned char* lds, const Gemm g, const Sched& S, const Epi& E) {
;     ...
;             PG8_WAIT_V(8); PG8_WAIT_L(0); PG8_BAR; PG8_MMA(0, 0, At, B0); PG8_MMA(0, 1, At, B1); PG8_BAR; PG8_SCHED;
;             PG8_LDA(At, 1, 1); PG8_STAGE(PG8_SB(1, 0), b3, voffB); PG8_STAGE(PG8_SB(1, 1), b3 + hB, voffB); PG8_STAGE(PG8_SA(1, 0), a3, voffA);
;             PG8_WAIT_V(8); PG8_WAIT_L(0); PG8_BAR; PG8_MMA(1, 0, At, B0); PG8_MMA(1, 1, At, B1); PG8_BAR; PG8_SCHED;
	s_setprio 0
	s_add_i32 s42, s60, s19
	v_lshl_add_u64 v[216:217], v[216:217], 0, s[14:15]
	s_mov_b32 m0, s42
	ds_read_b128 v[178:181], v187 offset:49152
	ds_read_b128 v[188:191], v187 offset:50176
	ds_read_b128 v[192:195], v187 offset:51200
	ds_read_b128 v[196:199], v187 offset:52224
	ds_read_b128 v[200:203], v187 offset:53248
	ds_read_b128 v[204:207], v187 offset:54272
	ds_read_b128 v[208:211], v187 offset:55296
	ds_read_b128 v[212:215], v187 offset:56320
	global_load_lds_dwordx4 v[216:217], off
	s_add_i32 m0, s42, 0x2000
	s_add_u32 s40, s40, 0x20080
	v_lshl_add_u64 v[216:217], v[218:219], 0, s[14:15]
	s_addc_u32 s41, s41, 0
	s_add_i32 s42, s61, s19
	global_load_lds_dwordx4 v[216:217], off
	v_lshl_add_u64 v[216:217], s[40:41], 0, v[162:163]
	s_mov_b32 m0, s42
	s_nop 0
	global_load_lds_dwordx4 v[216:217], off
	v_lshl_add_u64 v[216:217], s[40:41], 0, v[158:159]
	s_add_i32 m0, s42, 0x2000
	s_nop 0
	global_load_lds_dwordx4 v[216:217], off
	v_lshl_add_u64 v[216:217], v[220:221], 0, s[14:15]
	s_mov_b32 m0, s49
	s_nop 0
	global_load_lds_dwordx4 v[216:217], off
	v_lshl_add_u64 v[216:217], v[222:223], 0, s[14:15]
	s_mov_b32 m0, s50
	s_nop 0
	global_load_lds_dwordx4 v[216:217], off
	s_waitcnt vmcnt(8) lgkmcnt(0)
	s_setprio 1
	s_barrier
	v_mfma_f32_16x16x32_bf16 v[62:65], v[130:133], v[178:181], v[62:65]
	v_mfma_f32_16x16x32_bf16 v[58:61], v[138:141], v[178:181], v[58:61]
	v_mfma_f32_16x16x32_bf16 v[46:49], v[130:133], v[192:195], v[46:49]
	v_mfma_f32_16x16x32_bf16 v[42:45], v[138:141], v[192:195], v[42:45]
	v_mfma_f32_16x16x32_bf16 v[30:33], v[130:133], v[200:203], v[30:33]
	v_mfma_f32_16x16x32_bf16 v[26:29], v[138:141], v[200:203], v[26:29]
	v_mfma_f32_16x16x32_bf16 v[14:17], v[130:133], v[208:211], v[14:17]
	v_mfma_f32_16x16x32_bf16 v[10:13], v[138:141], v[208:211], v[10:13]
	v_mfma_f32_16x16x32_bf16 v[62:65], v[134:137], v[188:191], v[62:65]
	v_mfma_f32_16x16x32_bf16 v[58:61], v[142:145], v[188:191], v[58:61]
	v_mfma_f32_16x16x32_bf16 v[46:49], v[134:137], v[196:199], v[46:49]
	v_mfma_f32_16x16x32_bf16 v[42:45], v[142:145], v[196:199], v[42:45]
	v_mfma_f32_16x16x32_bf16 v[30:33], v[134:137], v[204:207], v[30:33]
	v_mfma_f32_16x16x32_bf16 v[26:29], v[142:145], v[204:207], v[26:29]
	v_mfma_f32_16x16x32_bf16 v[14:17], v[134:137], v[212:215], v[14:17]
	v_mfma_f32_16x16x32_bf16 v[10:13], v[142:145], v[212:215], v[10:13]
	v_mfma_f32_16x16x32_bf16 v[54:57], v[146:149], v[178:181], v[54:57]
	v_mfma_f32_16x16x32_bf16 v[50:53], v[154:157], v[178:181], v[50:53]
	v_mfma_f32_16x16x32_bf16 v[38:41], v[146:149], v[192:195], v[38:41]
	v_mfma_f32_16x16x32_bf16 v[34:37], v[154:157], v[192:195], v[34:37]
	v_mfma_f32_16x16x32_bf16 v[22:25], v[146:149], v[200:203], v[22:25]
	v_mfma_f32_16x16x32_bf16 v[18:21], v[154:157], v[200:203], v[18:21]
	v_mfma_f32_16x16x32_bf16 v[6:9], v[146:149], v[208:211], v[6:9]
	v_mfma_f32_16x16x32_bf16 v[2:5], v[154:157], v[208:211], v[2:5]
	v_mfma_f32_16x16x32_bf16 v[54:57], v[150:153], v[188:191], v[54:57]
	v_mfma_f32_16x16x32_bf16 v[50:53], v[174:177], v[188:191], v[50:53]
	v_mfma_f32_16x16x32_bf16 v[38:41], v[150:153], v[196:199], v[38:41]
	v_mfma_f32_16x16x32_bf16 v[34:37], v[174:177], v[196:199], v[34:37]
	v_mfma_f32_16x16x32_bf16 v[22:25], v[150:153], v[204:207], v[22:25]
	v_mfma_f32_16x16x32_bf16 v[18:21], v[174:177], v[204:207], v[18:21]
	v_mfma_f32_16x16x32_bf16 v[6:9], v[150:153], v[212:215], v[6:9]
	v_mfma_f32_16x16x32_bf16 v[2:5], v[174:177], v[212:215], v[2:5]
	s_barrier
	s_setprio 0
	s_add_i32 s59, s59, 2
	s_add_u32 s57, s57, 0x100
	s_addc_u32 s58, s58, 0
	s_add_u32 s38, s38, 0x100
	s_addc_u32 s39, s39, 0
	s_cmp_gt_u32 s59, 5
	s_cbranch_scc0 .LBB0_618
	v_lshl_or_b32 v146, s54, 8, v184
	v_ashrrev_i32_e32 v147, 31, v146
	v_lshl_add_u32 v148, s36, 8, v182
	v_ashrrev_i32_e32 v149, 31, v148
	v_lshlrev_b64 v[174:175], 1, v[146:147]
	v_lshlrev_b64 v[178:179], 13, v[148:149]
	v_lshl_add_u64 v[176:177], s[12:13], 0, v[174:175]
	v_lshl_add_u64 v[130:131], v[146:147], 2, s[10:11]
	v_lshl_add_u64 v[146:147], v[176:177], 0, v[178:179]
	global_load_dwordx4 v[142:145], v[130:131], off
	global_load_dwordx4 v[138:141], v[130:131], off offset:16
	global_load_dwordx4 v[134:137], v[130:131], off offset:512
	s_nop 0
	global_load_dwordx4 v[130:133], v[130:131], off offset:528
	s_nop 0
	global_load_dwordx4 v[188:191], v[146:147], off
	global_load_dwordx4 v[192:195], v[146:147], off offset:256
	v_or_b32_e32 v146, 16, v148
	v_ashrrev_i32_e32 v147, 31, v146
	v_lshlrev_b64 v[208:209], 13, v[146:147]
	v_lshl_add_u64 v[146:147], v[176:177], 0, v[208:209]
	global_load_dwordx4 v[196:199], v[146:147], off
	global_load_dwordx4 v[200:203], v[146:147], off offset:256
	v_or_b32_e32 v150, 32, v148
	v_or_b32_e32 v148, 48, v148
	v_ashrrev_i32_e32 v151, 31, v150
	v_ashrrev_i32_e32 v149, 31, v148
	v_lshlrev_b64 v[210:211], 13, v[150:151]
	v_lshlrev_b64 v[180:181], 13, v[148:149]
	v_lshl_add_u64 v[146:147], s[12:13], 0, v[178:179]
	v_lshl_add_u64 v[148:149], v[176:177], 0, v[210:211]
	v_lshl_add_u64 v[212:213], v[176:177], 0, v[180:181]
	v_lshl_add_u64 v[214:215], v[146:147], 0, v[174:175]
	global_load_dwordx4 v[204:207], v[148:149], off
	global_load_dwordx4 v[154:157], v[148:149], off offset:256
	global_load_dwordx4 v[150:153], v[212:213], off
	s_nop 0
	global_load_dwordx4 v[146:149], v[212:213], off offset:256
	s_and_b64 vcc, exec, s[8:9]
	s_mov_b32 s54, s26
	s_mov_b32 s36, s28
	s_mov_b64 s[38:39], s[34:35]
	s_mov_b64 s[40:41], s[30:31]
	s_waitcnt vmcnt(0)
; #define PG8_GAS __attribute__((address_space(1)))
; __device__ __forceinline__ unsigned cvt_pk_bf16(float lo, float hi) { const f32x2c v = {lo, hi}; return __builtin_bit_cast(unsigned, __builtin_convertvector(v, bf16x2c)); }
; __device__ __forceinline__ float bf_lo(unsigned w) { return __uint_as_float(w << 16); }
; __device__ __forceinline__ float bf_hi(unsigned w) { return __uint_as_float(w & 0xffff0000u); }
;     __device__ __forceinline__ void operator()(const f32x4 (&acc)[2][2][4][2], const Unit& un, int wr, int wc, int fr, int fq) const {
;     ...
; #pragma unroll
;             for (int m = 0; m < 4; ++m)
; #pragma unroll
;                 for (int bj = 0; bj < 2; ++bj) { const u32x4 g = gg[m][bj];
;                     const f32x4 v0 = acc[ai][bj][m][0] * sc[bj][0], v1 = acc[ai][bj][m][1] * sc[bj][1];
;                     u32x4 w; w.x = cvt_pk_bf16(v0[0] * bf_lo(g.x), v0[1] * bf_hi(g.x)); w.y = cvt_pk_bf16(v0[2] * bf_lo(g.y), v0[3] * bf_hi(g.y));
;                     w.z = cvt_pk_bf16(v1[0] * bf_lo(g.z), v1[1] * bf_hi(g.z)); w.w = cvt_pk_bf16(v1[2] * bf_lo(g.w), v1[3] * bf_hi(g.w));
;                     *(PG8_GAS u32x4*)(sp + (size_t)(row0 + ai * HALF + m * 16) * 4096 + col0 + bj * HALF) = w; }
	v_pk_mul_f32 v[128:129], v[128:129], v[144:145]
	v_pk_mul_f32 v[126:127], v[126:127], v[142:143]
	v_pk_mul_f32 v[124:125], v[124:125], v[140:141]
	v_pk_mul_f32 v[122:123], v[122:123], v[138:139]
	v_pk_mul_f32 v[212:213], v[108:109], v[140:141]
	v_pk_mul_f32 v[216:217], v[106:107], v[138:139]
	v_lshlrev_b32_e32 v106, 16, v188
	v_and_b32_e32 v107, 0xffff0000, v188
	v_lshlrev_b32_e32 v108, 16, v189
	v_and_b32_e32 v109, 0xffff0000, v189
	v_lshlrev_b32_e32 v188, 16, v190
	v_and_b32_e32 v189, 0xffff0000, v190
	v_lshlrev_b32_e32 v190, 16, v191
	v_and_b32_e32 v191, 0xffff0000, v191
	v_pk_mul_f32 v[120:121], v[120:121], v[136:137]
	v_pk_mul_f32 v[118:119], v[118:119], v[134:135]
	v_pk_mul_f32 v[116:117], v[116:117], v[132:133]
	v_pk_mul_f32 v[114:115], v[114:115], v[130:131]
	v_lshlrev_b32_e32 v218, 16, v192
	v_and_b32_e32 v219, 0xffff0000, v192
	v_lshlrev_b32_e32 v192, 16, v193
	v_and_b32_e32 v193, 0xffff0000, v193
	v_lshlrev_b32_e32 v220, 16, v194
	v_and_b32_e32 v221, 0xffff0000, v194
	v_lshlrev_b32_e32 v194, 16, v195
	v_and_b32_e32 v195, 0xffff0000, v195
	v_pk_mul_f32 v[106:107], v[126:127], v[106:107]
	v_pk_mul_f32 v[108:109], v[128:129], v[108:109]
	v_pk_mul_f32 v[122:123], v[122:123], v[188:189]
	v_pk_mul_f32 v[124:125], v[124:125], v[190:191]
	v_pk_mul_f32 v[112:113], v[112:113], v[144:145]
	v_pk_mul_f32 v[110:111], v[110:111], v[142:143]
	v_lshlrev_b32_e32 v222, 16, v196
	v_and_b32_e32 v223, 0xffff0000, v196
	v_lshlrev_b32_e32 v196, 16, v197
	v_and_b32_e32 v197, 0xffff0000, v197
	v_pk_mul_f32 v[118:119], v[118:119], v[218:219]
	v_pk_mul_f32 v[120:121], v[120:121], v[192:193]
	v_pk_mul_f32 v[114:115], v[114:115], v[220:221]
	v_pk_mul_f32 v[116:117], v[116:117], v[194:195]
	v_cvt_pk_bf16_f32 v106, v106, v107
	v_cvt_pk_bf16_f32 v107, v108, v109
	v_cvt_pk_bf16_f32 v108, v122, v123
	v_cvt_pk_bf16_f32 v109, v124, v125
	v_pk_mul_f32 v[126:127], v[110:111], v[222:223]
	v_pk_mul_f32 v[128:129], v[112:113], v[196:197]
	v_cvt_pk_bf16_f32 v110, v118, v119
	v_cvt_pk_bf16_f32 v111, v120, v121
	v_cvt_pk_bf16_f32 v112, v114, v115
	v_cvt_pk_bf16_f32 v113, v116, v117
	global_store_dwordx4 v[214:215], v[106:109], off
	global_store_dwordx4 v[214:215], v[110:113], off offset:256
	v_pk_mul_f32 v[102:103], v[102:103], v[134:135]
	v_pk_mul_f32 v[108:109], v[100:101], v[132:133]
	v_pk_mul_f32 v[100:101], v[98:99], v[130:131]
	v_lshlrev_b32_e32 v98, 16, v200
	v_and_b32_e32 v99, 0xffff0000, v200
	v_lshlrev_b32_e32 v106, 16, v198
	v_and_b32_e32 v107, 0xffff0000, v198
	v_pk_mul_f32 v[104:105], v[104:105], v[136:137]
	v_pk_mul_f32 v[98:99], v[102:103], v[98:99]
	v_lshlrev_b32_e32 v102, 16, v201
	v_and_b32_e32 v103, 0xffff0000, v201
	v_pk_mul_f32 v[106:107], v[216:217], v[106:107]
	v_pk_mul_f32 v[102:103], v[104:105], v[102:103]
	v_cvt_pk_bf16_f32 v116, v106, v107
	v_lshlrev_b32_e32 v106, 16, v199
	v_and_b32_e32 v107, 0xffff0000, v199
	v_cvt_pk_bf16_f32 v98, v98, v99
	v_cvt_pk_bf16_f32 v99, v102, v103
	v_lshlrev_b32_e32 v102, 16, v202
	v_and_b32_e32 v103, 0xffff0000, v202
	v_pk_mul_f32 v[106:107], v[212:213], v[106:107]
	v_pk_mul_f32 v[100:101], v[100:101], v[102:103]
	v_lshlrev_b32_e32 v102, 16, v203
	v_and_b32_e32 v103, 0xffff0000, v203
	v_cvt_pk_bf16_f32 v117, v106, v107
	v_lshl_add_u64 v[106:107], s[12:13], 0, v[208:209]
	v_pk_mul_f32 v[102:103], v[108:109], v[102:103]
	v_lshl_add_u64 v[106:107], v[106:107], 0, v[174:175]
	v_cvt_pk_bf16_f32 v100, v100, v101
	v_cvt_pk_bf16_f32 v101, v102, v103
	global_store_dwordx4 v[106:107], v[98:101], off offset:256
	v_pk_mul_f32 v[94:95], v[94:95], v[142:143]
	v_pk_mul_f32 v[96:97], v[96:97], v[144:145]
	v_pk_mul_f32 v[98:99], v[92:93], v[140:141]
	v_pk_mul_f32 v[92:93], v[90:91], v[138:139]
	v_lshlrev_b32_e32 v90, 16, v204
	v_and_b32_e32 v91, 0xffff0000, v204
	v_pk_mul_f32 v[90:91], v[94:95], v[90:91]
	v_lshlrev_b32_e32 v94, 16, v205
	v_and_b32_e32 v95, 0xffff0000, v205
	v_pk_mul_f32 v[94:95], v[96:97], v[94:95]
	v_cvt_pk_bf16_f32 v90, v90, v91
	v_cvt_pk_bf16_f32 v91, v94, v95
	v_lshlrev_b32_e32 v94, 16, v206
	v_and_b32_e32 v95, 0xffff0000, v206
	v_pk_mul_f32 v[92:93], v[92:93], v[94:95]
	v_lshlrev_b32_e32 v94, 16, v207
	v_and_b32_e32 v95, 0xffff0000, v207
	v_pk_mul_f32 v[94:95], v[98:99], v[94:95]
	v_cvt_pk_bf16_f32 v92, v92, v93
	v_cvt_pk_bf16_f32 v93, v94, v95
	v_lshl_add_u64 v[94:95], s[12:13], 0, v[210:211]
	v_lshl_add_u64 v[102:103], v[178:179], 0, s[16:17]
	v_lshl_add_u64 v[94:95], v[94:95], 0, v[174:175]
	v_pk_mul_f32 v[86:87], v[86:87], v[134:135]
	v_lshl_add_u64 v[96:97], v[176:177], 0, v[102:103]
	v_lshlrev_b32_e32 v98, 16, v154
	v_and_b32_e32 v99, 0xffff0000, v154
	global_store_dwordx4 v[94:95], v[90:93], off
	v_pk_mul_f32 v[88:89], v[88:89], v[136:137]
	v_pk_mul_f32 v[86:87], v[86:87], v[98:99]
	v_pk_mul_f32 v[90:91], v[84:85], v[132:133]
	v_pk_mul_f32 v[92:93], v[82:83], v[130:131]
	global_load_dwordx4 v[82:85], v[96:97], off
	v_lshlrev_b32_e32 v98, 16, v155
	v_and_b32_e32 v99, 0xffff0000, v155
	v_pk_mul_f32 v[88:89], v[88:89], v[98:99]
	v_cvt_pk_bf16_f32 v86, v86, v87
	v_cvt_pk_bf16_f32 v87, v88, v89
	v_lshlrev_b32_e32 v88, 16, v156
	v_and_b32_e32 v89, 0xffff0000, v156
	v_pk_mul_f32 v[88:89], v[92:93], v[88:89]
	v_lshlrev_b32_e32 v92, 16, v157
	v_and_b32_e32 v93, 0xffff0000, v157
	v_pk_mul_f32 v[90:91], v[90:91], v[92:93]
	v_cvt_pk_bf16_f32 v88, v88, v89
	v_cvt_pk_bf16_f32 v89, v90, v91
	global_store_dwordx4 v[94:95], v[86:89], off offset:256
	v_pk_mul_f32 v[80:81], v[80:81], v[144:145]
	v_pk_mul_f32 v[90:91], v[76:77], v[140:141]
	v_pk_mul_f32 v[86:87], v[78:79], v[142:143]
	v_lshlrev_b32_e32 v88, 16, v150
	v_and_b32_e32 v89, 0xffff0000, v150
	v_pk_mul_f32 v[86:87], v[86:87], v[88:89]
	v_lshlrev_b32_e32 v88, 16, v151
; #define PG8_GAS __attribute__((address_space(1)))
; __device__ __forceinline__ unsigned cvt_pk_bf16(float lo, float hi) { const f32x2c v = {lo, hi}; return __builtin_bit_cast(unsigned, __builtin_convertvector(v, bf16x2c)); }
; __device__ __forceinline__ float bf_lo(unsigned w) { return __uint_as_float(w << 16); }
; __device__ __forceinline__ float bf_hi(unsigned w) { return __uint_as_float(w & 0xffff0000u); }
;     __device__ __forceinline__ void operator()(const f32x4 (&acc)[2][2][4][2], const Unit& un, int wr, int wc, int fr, int fq) const {
;     ...
;         for (int ai = 0; ai < 2; ++ai) {
;             u32x4 gg[4][2];
; #pragma unroll
;             for (int m = 0; m < 4; ++m)
; #pragma unroll
;                 for (int bj = 0; bj < 2; ++bj) gg[m][bj] = *(const PG8_GAS u32x4*)(sp + (size_t)(row0 + ai * HALF + m * 16) * 4096 + col0 + bj * HALF);
;             asm volatile("" ::: "memory");
; #pragma unroll
;             for (int m = 0; m < 4; ++m)
; #pragma unroll
;                 for (int bj = 0; bj < 2; ++bj) { const u32x4 g = gg[m][bj];
;                     const f32x4 v0 = acc[ai][bj][m][0] * sc[bj][0], v1 = acc[ai][bj][m][1] * sc[bj][1];
;                     u32x4 w; w.x = cvt_pk_bf16(v0[0] * bf_lo(g.x), v0[1] * bf_hi(g.x)); w.y = cvt_pk_bf16(v0[2] * bf_lo(g.y), v0[3] * bf_hi(g.y));
;                     w.z = cvt_pk_bf16(v1[0] * bf_lo(g.z), v1[1] * bf_hi(g.z)); w.w = cvt_pk_bf16(v1[2] * bf_lo(g.w), v1[3] * bf_hi(g.w));
;                     *(PG8_GAS u32x4*)(sp + (size_t)(row0 + ai * HALF + m * 16) * 4096 + col0 + bj * HALF) = w; }
	v_and_b32_e32 v89, 0xffff0000, v151
	global_load_dwordx4 v[76:79], v[96:97], off offset:256
	v_pk_mul_f32 v[80:81], v[80:81], v[88:89]
	v_pk_mul_f32 v[74:75], v[74:75], v[138:139]
	v_cvt_pk_bf16_f32 v86, v86, v87
	v_cvt_pk_bf16_f32 v87, v80, v81
	v_lshlrev_b32_e32 v80, 16, v152
	v_and_b32_e32 v81, 0xffff0000, v152
	v_pk_mul_f32 v[74:75], v[74:75], v[80:81]
	v_lshl_add_u64 v[80:81], v[178:179], 0, s[20:21]
	v_cvt_pk_bf16_f32 v88, v74, v75
	v_lshlrev_b32_e32 v74, 16, v153
	v_and_b32_e32 v75, 0xffff0000, v153
	v_pk_mul_f32 v[74:75], v[90:91], v[74:75]
	v_lshl_add_u64 v[90:91], v[176:177], 0, v[80:81]
	v_cvt_pk_bf16_f32 v89, v74, v75
	v_lshl_add_u64 v[74:75], s[12:13], 0, v[180:181]
	v_lshl_add_u64 v[74:75], v[74:75], 0, v[174:175]
	global_store_dwordx4 v[74:75], v[86:89], off
	global_load_dwordx4 v[86:89], v[90:91], off
	v_pk_mul_f32 v[70:71], v[70:71], v[134:135]
	v_pk_mul_f32 v[92:93], v[68:69], v[132:133]
	v_pk_mul_f32 v[68:69], v[66:67], v[130:131]
	v_lshlrev_b32_e32 v66, 16, v146
	v_and_b32_e32 v67, 0xffff0000, v146
	v_pk_mul_f32 v[72:73], v[72:73], v[136:137]
	v_pk_mul_f32 v[66:67], v[70:71], v[66:67]
	v_lshlrev_b32_e32 v70, 16, v147
	v_and_b32_e32 v71, 0xffff0000, v147
	v_pk_mul_f32 v[70:71], v[72:73], v[70:71]
	v_cvt_pk_bf16_f32 v66, v66, v67
	v_cvt_pk_bf16_f32 v67, v70, v71
	v_lshlrev_b32_e32 v70, 16, v148
	v_and_b32_e32 v71, 0xffff0000, v148
	v_pk_mul_f32 v[68:69], v[68:69], v[70:71]
	v_lshlrev_b32_e32 v70, 16, v149
	v_and_b32_e32 v71, 0xffff0000, v149
	v_pk_mul_f32 v[70:71], v[92:93], v[70:71]
	global_load_dwordx4 v[90:93], v[90:91], off offset:256
	v_cvt_pk_bf16_f32 v114, v126, v127
	v_cvt_pk_bf16_f32 v115, v128, v129
	v_cvt_pk_bf16_f32 v68, v68, v69
	v_cvt_pk_bf16_f32 v69, v70, v71
	v_lshl_add_u64 v[104:105], v[178:179], 0, s[22:23]
	global_store_dwordx4 v[106:107], v[114:117], off
	global_store_dwordx4 v[74:75], v[66:69], off offset:256
	v_lshl_add_u64 v[74:75], v[178:179], 0, s[24:25]
	v_pk_mul_f32 v[62:63], v[62:63], v[142:143]
	v_lshl_add_u64 v[66:67], v[176:177], 0, v[104:105]
	global_load_dwordx4 v[94:97], v[66:67], off
	global_load_dwordx4 v[98:101], v[66:67], off offset:256
	v_lshl_add_u64 v[66:67], v[176:177], 0, v[74:75]
	global_load_dwordx4 v[70:73], v[66:67], off
	s_nop 0
	global_load_dwordx4 v[66:69], v[66:67], off offset:256
	v_pk_mul_f32 v[106:107], v[60:61], v[140:141]
	v_pk_mul_f32 v[60:61], v[58:59], v[138:139]
	v_pk_mul_f32 v[64:65], v[64:65], v[144:145]
	v_pk_mul_f32 v[54:55], v[54:55], v[134:135]
	v_pk_mul_f32 v[56:57], v[56:57], v[136:137]
	s_waitcnt vmcnt(11)
	v_lshlrev_b32_e32 v58, 16, v82
	v_and_b32_e32 v59, 0xffff0000, v82
	v_pk_mul_f32 v[58:59], v[62:63], v[58:59]
	v_lshlrev_b32_e32 v62, 16, v83
	v_and_b32_e32 v63, 0xffff0000, v83
	v_pk_mul_f32 v[62:63], v[64:65], v[62:63]
	v_cvt_pk_bf16_f32 v58, v58, v59
	v_cvt_pk_bf16_f32 v59, v62, v63
	v_lshlrev_b32_e32 v62, 16, v84
	v_and_b32_e32 v63, 0xffff0000, v84
	v_pk_mul_f32 v[60:61], v[60:61], v[62:63]
	v_lshlrev_b32_e32 v62, 16, v85
	v_and_b32_e32 v63, 0xffff0000, v85
	v_pk_mul_f32 v[62:63], v[106:107], v[62:63]
	v_cvt_pk_bf16_f32 v60, v60, v61
	v_cvt_pk_bf16_f32 v61, v62, v63
	v_lshl_add_u64 v[62:63], s[12:13], 0, v[102:103]
	v_lshl_add_u64 v[62:63], v[62:63], 0, v[174:175]
	global_store_dwordx4 v[62:63], v[58:61], off
	v_pk_mul_f32 v[46:47], v[46:47], v[142:143]
	v_pk_mul_f32 v[48:49], v[48:49], v[144:145]
	v_pk_mul_f32 v[58:59], v[52:53], v[132:133]
	v_pk_mul_f32 v[52:53], v[50:51], v[130:131]
	s_waitcnt vmcnt(10)
	v_lshlrev_b32_e32 v50, 16, v76
	v_and_b32_e32 v51, 0xffff0000, v76
	v_pk_mul_f32 v[50:51], v[54:55], v[50:51]
	v_lshlrev_b32_e32 v54, 16, v77
	v_and_b32_e32 v55, 0xffff0000, v77
	v_pk_mul_f32 v[54:55], v[56:57], v[54:55]
	v_cvt_pk_bf16_f32 v50, v50, v51
	v_cvt_pk_bf16_f32 v51, v54, v55
	v_lshlrev_b32_e32 v54, 16, v78
	v_and_b32_e32 v55, 0xffff0000, v78
	v_pk_mul_f32 v[52:53], v[52:53], v[54:55]
	v_lshlrev_b32_e32 v54, 16, v79
	v_and_b32_e32 v55, 0xffff0000, v79
	v_pk_mul_f32 v[54:55], v[58:59], v[54:55]
	v_cvt_pk_bf16_f32 v52, v52, v53
	v_cvt_pk_bf16_f32 v53, v54, v55
	global_store_dwordx4 v[62:63], v[50:53], off offset:256
	v_pk_mul_f32 v[38:39], v[38:39], v[134:135]
	v_pk_mul_f32 v[40:41], v[40:41], v[136:137]
	v_pk_mul_f32 v[50:51], v[44:45], v[140:141]
	v_pk_mul_f32 v[44:45], v[42:43], v[138:139]
	s_waitcnt vmcnt(9)
; #define PG8_GAS __attribute__((address_space(1)))
; __device__ __forceinline__ unsigned cvt_pk_bf16(float lo, float hi) { const f32x2c v = {lo, hi}; return __builtin_bit_cast(unsigned, __builtin_convertvector(v, bf16x2c)); }
; __device__ __forceinline__ float bf_lo(unsigned w) { return __uint_as_float(w << 16); }
; __device__ __forceinline__ float bf_hi(unsigned w) { return __uint_as_float(w & 0xffff0000u); }
;     __device__ __forceinline__ void operator()(const f32x4 (&acc)[2][2][4][2], const Unit& un, int wr, int wc, int fr, int fq) const {
;     ...
; #pragma unroll
;             for (int m = 0; m < 4; ++m)
; #pragma unroll
;                 for (int bj = 0; bj < 2; ++bj) { const u32x4 g = gg[m][bj];
;                     const f32x4 v0 = acc[ai][bj][m][0] * sc[bj][0], v1 = acc[ai][bj][m][1] * sc[bj][1];
;                     u32x4 w; w.x = cvt_pk_bf16(v0[0] * bf_lo(g.x), v0[1] * bf_hi(g.x)); w.y = cvt_pk_bf16(v0[2] * bf_lo(g.y), v0[3] * bf_hi(g.y));
;                     w.z = cvt_pk_bf16(v1[0] * bf_lo(g.z), v1[1] * bf_hi(g.z)); w.w = cvt_pk_bf16(v1[2] * bf_lo(g.w), v1[3] * bf_hi(g.w));
;                     *(PG8_GAS u32x4*)(sp + (size_t)(row0 + ai * HALF + m * 16) * 4096 + col0 + bj * HALF) = w; }
	v_lshlrev_b32_e32 v42, 16, v86
	v_and_b32_e32 v43, 0xffff0000, v86
	v_pk_mul_f32 v[42:43], v[46:47], v[42:43]
	v_lshlrev_b32_e32 v46, 16, v87
	v_and_b32_e32 v47, 0xffff0000, v87
	v_pk_mul_f32 v[46:47], v[48:49], v[46:47]
	v_cvt_pk_bf16_f32 v42, v42, v43
	v_cvt_pk_bf16_f32 v43, v46, v47
	v_lshlrev_b32_e32 v46, 16, v88
	v_and_b32_e32 v47, 0xffff0000, v88
	v_pk_mul_f32 v[44:45], v[44:45], v[46:47]
	v_lshlrev_b32_e32 v46, 16, v89
	v_and_b32_e32 v47, 0xffff0000, v89
	v_pk_mul_f32 v[46:47], v[50:51], v[46:47]
	v_cvt_pk_bf16_f32 v44, v44, v45
	v_cvt_pk_bf16_f32 v45, v46, v47
	v_lshl_add_u64 v[46:47], s[12:13], 0, v[80:81]
	v_lshl_add_u64 v[46:47], v[46:47], 0, v[174:175]
	global_store_dwordx4 v[46:47], v[42:45], off
	v_pk_mul_f32 v[30:31], v[30:31], v[142:143]
	v_pk_mul_f32 v[32:33], v[32:33], v[144:145]
	v_pk_mul_f32 v[42:43], v[36:37], v[132:133]
	v_pk_mul_f32 v[36:37], v[34:35], v[130:131]
	s_waitcnt vmcnt(9)
	v_lshlrev_b32_e32 v34, 16, v90
	v_and_b32_e32 v35, 0xffff0000, v90
	v_pk_mul_f32 v[34:35], v[38:39], v[34:35]
	v_lshlrev_b32_e32 v38, 16, v91
	v_and_b32_e32 v39, 0xffff0000, v91
	v_pk_mul_f32 v[38:39], v[40:41], v[38:39]
	v_cvt_pk_bf16_f32 v34, v34, v35
	v_cvt_pk_bf16_f32 v35, v38, v39
	v_lshlrev_b32_e32 v38, 16, v92
	v_and_b32_e32 v39, 0xffff0000, v92
	v_pk_mul_f32 v[36:37], v[36:37], v[38:39]
	v_lshlrev_b32_e32 v38, 16, v93
	v_and_b32_e32 v39, 0xffff0000, v93
	v_pk_mul_f32 v[38:39], v[42:43], v[38:39]
	v_cvt_pk_bf16_f32 v36, v36, v37
	v_cvt_pk_bf16_f32 v37, v38, v39
	global_store_dwordx4 v[46:47], v[34:37], off offset:256
	v_pk_mul_f32 v[22:23], v[22:23], v[134:135]
	v_pk_mul_f32 v[24:25], v[24:25], v[136:137]
	v_pk_mul_f32 v[34:35], v[28:29], v[140:141]
	v_pk_mul_f32 v[28:29], v[26:27], v[138:139]
	s_waitcnt vmcnt(7)
	v_lshlrev_b32_e32 v26, 16, v94
	v_and_b32_e32 v27, 0xffff0000, v94
	v_pk_mul_f32 v[26:27], v[30:31], v[26:27]
	v_lshlrev_b32_e32 v30, 16, v95
	v_and_b32_e32 v31, 0xffff0000, v95
	v_pk_mul_f32 v[30:31], v[32:33], v[30:31]
	v_cvt_pk_bf16_f32 v26, v26, v27
	v_cvt_pk_bf16_f32 v27, v30, v31
	v_lshlrev_b32_e32 v30, 16, v96
	v_and_b32_e32 v31, 0xffff0000, v96
	v_pk_mul_f32 v[28:29], v[28:29], v[30:31]
	v_lshlrev_b32_e32 v30, 16, v97
	v_and_b32_e32 v31, 0xffff0000, v97
	v_pk_mul_f32 v[30:31], v[34:35], v[30:31]
	v_cvt_pk_bf16_f32 v28, v28, v29
	v_cvt_pk_bf16_f32 v29, v30, v31
	v_lshl_add_u64 v[30:31], s[12:13], 0, v[104:105]
	v_lshl_add_u64 v[30:31], v[30:31], 0, v[174:175]
	global_store_dwordx4 v[30:31], v[26:29], off
	v_pk_mul_f32 v[14:15], v[14:15], v[142:143]
	v_pk_mul_f32 v[16:17], v[16:17], v[144:145]
	v_pk_mul_f32 v[26:27], v[20:21], v[132:133]
	v_pk_mul_f32 v[20:21], v[18:19], v[130:131]
	s_waitcnt vmcnt(7)
	v_lshlrev_b32_e32 v18, 16, v98
	v_and_b32_e32 v19, 0xffff0000, v98
	v_pk_mul_f32 v[18:19], v[22:23], v[18:19]
	v_lshlrev_b32_e32 v22, 16, v99
	v_and_b32_e32 v23, 0xffff0000, v99
	v_pk_mul_f32 v[22:23], v[24:25], v[22:23]
	v_cvt_pk_bf16_f32 v18, v18, v19
	v_cvt_pk_bf16_f32 v19, v22, v23
	v_lshlrev_b32_e32 v22, 16, v100
	v_and_b32_e32 v23, 0xffff0000, v100
	v_pk_mul_f32 v[20:21], v[20:21], v[22:23]
	v_lshlrev_b32_e32 v22, 16, v101
	v_and_b32_e32 v23, 0xffff0000, v101
	v_pk_mul_f32 v[22:23], v[26:27], v[22:23]
	v_cvt_pk_bf16_f32 v20, v20, v21
	v_cvt_pk_bf16_f32 v21, v22, v23
	global_store_dwordx4 v[30:31], v[18:21], off offset:256
	v_pk_mul_f32 v[6:7], v[6:7], v[134:135]
	v_pk_mul_f32 v[8:9], v[8:9], v[136:137]
	v_pk_mul_f32 v[18:19], v[12:13], v[140:141]
	v_pk_mul_f32 v[12:13], v[10:11], v[138:139]
	s_waitcnt vmcnt(7)
	v_lshlrev_b32_e32 v10, 16, v70
	v_and_b32_e32 v11, 0xffff0000, v70
	v_pk_mul_f32 v[10:11], v[14:15], v[10:11]
	v_lshlrev_b32_e32 v14, 16, v71
	v_and_b32_e32 v15, 0xffff0000, v71
	v_pk_mul_f32 v[14:15], v[16:17], v[14:15]
	v_cvt_pk_bf16_f32 v10, v10, v11
	v_cvt_pk_bf16_f32 v11, v14, v15
	v_lshlrev_b32_e32 v14, 16, v72
	v_and_b32_e32 v15, 0xffff0000, v72
	v_pk_mul_f32 v[12:13], v[12:13], v[14:15]
	v_lshlrev_b32_e32 v14, 16, v73
	v_and_b32_e32 v15, 0xffff0000, v73
	v_pk_mul_f32 v[14:15], v[18:19], v[14:15]
	v_cvt_pk_bf16_f32 v12, v12, v13
	v_cvt_pk_bf16_f32 v13, v14, v15
	v_lshl_add_u64 v[14:15], s[12:13], 0, v[74:75]
	v_lshl_add_u64 v[14:15], v[14:15], 0, v[174:175]
	global_store_dwordx4 v[14:15], v[10:13], off
	s_nop 1
	v_pk_mul_f32 v[10:11], v[4:5], v[132:133]
	v_pk_mul_f32 v[4:5], v[2:3], v[130:131]
	s_waitcnt vmcnt(7)
	v_lshlrev_b32_e32 v2, 16, v66
	v_and_b32_e32 v3, 0xffff0000, v66
	v_pk_mul_f32 v[2:3], v[6:7], v[2:3]
	v_lshlrev_b32_e32 v6, 16, v67
	v_and_b32_e32 v7, 0xffff0000, v67
	v_pk_mul_f32 v[6:7], v[8:9], v[6:7]
	v_cvt_pk_bf16_f32 v2, v2, v3
	v_cvt_pk_bf16_f32 v3, v6, v7
	v_lshlrev_b32_e32 v6, 16, v68
	v_and_b32_e32 v7, 0xffff0000, v68
	v_pk_mul_f32 v[4:5], v[4:5], v[6:7]
	v_lshlrev_b32_e32 v6, 16, v69
	v_and_b32_e32 v7, 0xffff0000, v69
	v_pk_mul_f32 v[6:7], v[10:11], v[6:7]
	v_cvt_pk_bf16_f32 v4, v4, v5
	v_cvt_pk_bf16_f32 v5, v6, v7
	global_store_dwordx4 v[14:15], v[2:5], off offset:256
	s_cbranch_vccz .LBB0_615
	s_waitcnt vmcnt(0)
	s_cmpk_gt_u32 s4, 0xff
	s_cbranch_scc1 .LBB0_622
	s_barrier

; #define PG8_STAGE(bufoff, gbase, voff) do { _Pragma("unroll") for (int _i = 0; _i < 2; ++_i) \
;         __builtin_amdgcn_global_load_lds((const unsigned*)((const char*)(gbase) + (voff)[_i]), (PG8_LAS unsigned*)(lds + (bufoff) + ldsw + _i * 8192), 16, 0, 0); } while (0)
; #define PG8_LDA(dst, b, h) do { _Pragma("unroll") for (int m = 0; m < 4; ++m) _Pragma("unroll") for (int k = 0; k < 2; ++k) dst[m][k] = *(const PG8_LAS bf16x8*)(lds + PG8_SA(b, h) + aoff + m * 2048 + k * 1024); } while (0)
; #define PG8_LDB(dst, b, h) do { _Pragma("unroll") for (int n = 0; n < 2; ++n) _Pragma("unroll") for (int k = 0; k < 2; ++k) dst[n][k] = *(const PG8_LAS bf16x8*)(lds + PG8_SB(b, h) + boff + n * 2048 + k * 1024); } while (0)
; #define PG8_WAIT_V(n) asm volatile("s_waitcnt vmcnt(" #n ")" ::: "memory")
; #define PG8_WAIT_L(n) asm volatile("s_waitcnt lgkmcnt(" #n ")" ::: "memory")
; #define PG8_BAR __builtin_amdgcn_s_barrier()
; #define PG8_SCHED __builtin_amdgcn_sched_barrier(0)
; template <class Epi, class Sched, bool ALIGN_EPI = false, bool SP2 = false, bool F8 = false>
; __device__ __forceinline__ void gemm_phase(PG8_LAS unsigned char* lds, const Gemm g, const Sched& S, const Epi& E) {
;     ...
;             PG8_LDB(B0, 0, 0); PG8_LDB(B1, 0, 1); PG8_SCHED; PG8_LDA(At, 0, 0); PG8_STAGE(PG8_SA(1, 1), a1 + hA, voffA);
;             PG8_WAIT_V(8); PG8_WAIT_L(0); PG8_BAR; PG8_MMA(0, 0, At, B0); PG8_MMA(0, 1, At, B1); PG8_BAR; PG8_SCHED;
;             PG8_LDA(At, 0, 1); PG8_STAGE(PG8_SB(0, 0), b2, voffB); PG8_STAGE(PG8_SB(0, 1), b2 + hB, voffB); PG8_STAGE(PG8_SA(0, 0), a2, voffA);
;             PG8_WAIT_V(8); PG8_WAIT_L(0); PG8_BAR; PG8_MMA(1, 0, At, B0); PG8_MMA(1, 1, At, B1); PG8_BAR; PG8_SCHED;
.LBB0_630:
	ds_read_b128 v[26:29], v190
	ds_read_b128 v[30:33], v190 offset:1024
	ds_read_b128 v[18:21], v190 offset:2048
	ds_read_b128 v[22:25], v190 offset:3072
	ds_read_b128 v[10:13], v191
	ds_read_b128 v[14:17], v191 offset:1024
	ds_read_b128 v[2:5], v191 offset:2048
	ds_read_b128 v[6:9], v191 offset:3072
	s_add_u32 s30, s28, 0xfffc0080
	s_addc_u32 s31, s29, -1
	s_cmp_eq_u32 s51, 12
	s_cselect_b32 s35, s21, s31
	s_cselect_b32 s34, s47, s30
	s_cselect_b32 s31, s17, s50
	s_cselect_b32 s30, s48, s49
	v_lshl_add_u64 v[218:219], s[28:29], 0, v[172:173]
	s_add_i32 m0, s27, 0xc000
	ds_read_b128 v[178:181], v192
	ds_read_b128 v[182:185], v192 offset:1024
	ds_read_b128 v[194:197], v192 offset:2048
	ds_read_b128 v[198:201], v192 offset:3072
	ds_read_b128 v[202:205], v192 offset:4096
	ds_read_b128 v[206:209], v192 offset:5120
	ds_read_b128 v[210:213], v192 offset:6144
	ds_read_b128 v[214:217], v192 offset:7168
	global_load_lds_dwordx4 v[218:219], off
	v_lshl_add_u64 v[218:219], s[28:29], 0, v[170:171]
	s_add_i32 m0, s27, 0xe000
	s_nop 0
	global_load_lds_dwordx4 v[218:219], off
	s_waitcnt vmcnt(8) lgkmcnt(0)
	s_setprio 1
	s_barrier
	v_mfma_scale_f32_16x16x128_f8f6f4 v[158:161], v[26:33], v[178:185], v[158:161], v186, v186 op_sel_hi:[0,0,0]
	v_mfma_scale_f32_16x16x128_f8f6f4 v[154:157], v[18:25], v[178:185], v[154:157], v186, v186 op_sel_hi:[0,0,0]
	v_mfma_scale_f32_16x16x128_f8f6f4 v[146:149], v[26:33], v[194:201], v[146:149], v186, v186 op_sel_hi:[0,0,0]
	v_mfma_scale_f32_16x16x128_f8f6f4 v[138:141], v[18:25], v[194:201], v[138:141], v186, v186 op_sel_hi:[0,0,0]
	v_mfma_scale_f32_16x16x128_f8f6f4 v[130:133], v[26:33], v[202:209], v[130:133], v186, v186 op_sel_hi:[0,0,0]
	v_mfma_scale_f32_16x16x128_f8f6f4 v[122:125], v[18:25], v[202:209], v[122:125], v186, v186 op_sel_hi:[0,0,0]
	v_mfma_scale_f32_16x16x128_f8f6f4 v[114:117], v[26:33], v[210:217], v[114:117], v186, v186 op_sel_hi:[0,0,0]
	v_mfma_scale_f32_16x16x128_f8f6f4 v[106:109], v[18:25], v[210:217], v[106:109], v186, v186 op_sel_hi:[0,0,0]
	v_mfma_scale_f32_16x16x128_f8f6f4 v[150:153], v[10:17], v[178:185], v[150:153], v186, v186 op_sel_hi:[0,0,0]
	v_mfma_scale_f32_16x16x128_f8f6f4 v[142:145], v[2:9], v[178:185], v[142:145], v186, v186 op_sel_hi:[0,0,0]
	v_mfma_scale_f32_16x16x128_f8f6f4 v[134:137], v[10:17], v[194:201], v[134:137], v186, v186 op_sel_hi:[0,0,0]
	v_mfma_scale_f32_16x16x128_f8f6f4 v[126:129], v[2:9], v[194:201], v[126:129], v186, v186 op_sel_hi:[0,0,0]
	v_mfma_scale_f32_16x16x128_f8f6f4 v[118:121], v[10:17], v[202:209], v[118:121], v186, v186 op_sel_hi:[0,0,0]
	v_mfma_scale_f32_16x16x128_f8f6f4 v[110:113], v[2:9], v[202:209], v[110:113], v186, v186 op_sel_hi:[0,0,0]
	v_mfma_scale_f32_16x16x128_f8f6f4 v[102:105], v[10:17], v[210:217], v[102:105], v186, v186 op_sel_hi:[0,0,0]
	v_mfma_scale_f32_16x16x128_f8f6f4 v[98:101], v[2:9], v[210:217], v[98:101], v186, v186 op_sel_hi:[0,0,0]
	s_barrier
	s_setprio 0
	s_add_i32 s52, s44, s19
	v_lshl_add_u64 v[178:179], s[30:31], 0, v[166:167]
	s_mov_b32 m0, s52
	ds_read_b128 v[194:197], v192 offset:16384
	ds_read_b128 v[198:201], v192 offset:17408
	ds_read_b128 v[202:205], v192 offset:18432
	ds_read_b128 v[206:209], v192 offset:19456
	ds_read_b128 v[210:213], v192 offset:20480
	ds_read_b128 v[214:217], v192 offset:21504
	ds_read_b128 v[218:221], v192 offset:22528
	ds_read_b128 v[222:225], v192 offset:23552
	global_load_lds_dwordx4 v[178:179], off
	s_add_i32 m0, s52, 0x2000
	s_add_u32 s52, s30, 0x40000
	v_lshl_add_u64 v[180:181], s[30:31], 0, v[162:163]
	s_addc_u32 s53, s31, 0
	s_add_i32 s54, s45, s19
	global_load_lds_dwordx4 v[180:181], off
	v_lshl_add_u64 v[182:183], s[52:53], 0, v[166:167]
	s_mov_b32 m0, s54
	v_lshl_add_u64 v[184:185], s[34:35], 0, v[164:165]
	global_load_lds_dwordx4 v[182:183], off
	v_lshl_add_u64 v[182:183], s[52:53], 0, v[162:163]
	s_add_i32 m0, s54, 0x2000
	s_nop 0
	global_load_lds_dwordx4 v[182:183], off
	v_lshl_add_u64 v[182:183], s[34:35], 0, v[168:169]
	s_mov_b32 m0, s27
	s_nop 0
	global_load_lds_dwordx4 v[182:183], off
	s_mov_b32 m0, s37
	s_nop 0
	global_load_lds_dwordx4 v[184:185], off
	s_waitcnt vmcnt(8) lgkmcnt(0)
	s_setprio 1
	s_barrier
	v_mfma_scale_f32_16x16x128_f8f6f4 v[94:97], v[26:33], v[194:201], v[94:97], v186, v186 op_sel_hi:[0,0,0]
	v_mfma_scale_f32_16x16x128_f8f6f4 v[90:93], v[18:25], v[194:201], v[90:93], v186, v186 op_sel_hi:[0,0,0]
	v_mfma_scale_f32_16x16x128_f8f6f4 v[82:85], v[26:33], v[202:209], v[82:85], v186, v186 op_sel_hi:[0,0,0]
	v_mfma_scale_f32_16x16x128_f8f6f4 v[74:77], v[18:25], v[202:209], v[74:77], v186, v186 op_sel_hi:[0,0,0]
	v_mfma_scale_f32_16x16x128_f8f6f4 v[66:69], v[26:33], v[210:217], v[66:69], v186, v186 op_sel_hi:[0,0,0]
	v_mfma_scale_f32_16x16x128_f8f6f4 v[58:61], v[18:25], v[210:217], v[58:61], v186, v186 op_sel_hi:[0,0,0]
	v_mfma_scale_f32_16x16x128_f8f6f4 v[50:53], v[26:33], v[218:225], v[50:53], v186, v186 op_sel_hi:[0,0,0]
	v_mfma_scale_f32_16x16x128_f8f6f4 v[42:45], v[18:25], v[218:225], v[42:45], v186, v186 op_sel_hi:[0,0,0]
	v_mfma_scale_f32_16x16x128_f8f6f4 v[86:89], v[10:17], v[194:201], v[86:89], v186, v186 op_sel_hi:[0,0,0]
	v_mfma_scale_f32_16x16x128_f8f6f4 v[78:81], v[2:9], v[194:201], v[78:81], v186, v186 op_sel_hi:[0,0,0]
	v_mfma_scale_f32_16x16x128_f8f6f4 v[70:73], v[10:17], v[202:209], v[70:73], v186, v186 op_sel_hi:[0,0,0]
	v_mfma_scale_f32_16x16x128_f8f6f4 v[62:65], v[2:9], v[202:209], v[62:65], v186, v186 op_sel_hi:[0,0,0]
	v_mfma_scale_f32_16x16x128_f8f6f4 v[54:57], v[10:17], v[210:217], v[54:57], v186, v186 op_sel_hi:[0,0,0]
	v_mfma_scale_f32_16x16x128_f8f6f4 v[46:49], v[2:9], v[210:217], v[46:49], v186, v186 op_sel_hi:[0,0,0]
	v_mfma_scale_f32_16x16x128_f8f6f4 v[38:41], v[10:17], v[218:225], v[38:41], v186, v186 op_sel_hi:[0,0,0]
	v_mfma_scale_f32_16x16x128_f8f6f4 v[34:37], v[2:9], v[218:225], v[34:37], v186, v186 op_sel_hi:[0,0,0]
	s_barrier
; #define PG8_STAGE(bufoff, gbase, voff) do { _Pragma("unroll") for (int _i = 0; _i < 2; ++_i) \
;         __builtin_amdgcn_global_load_lds((const unsigned*)((const char*)(gbase) + (voff)[_i]), (PG8_LAS unsigned*)(lds + (bufoff) + ldsw + _i * 8192), 16, 0, 0); } while (0)
; #define PG8_LDA(dst, b, h) do { _Pragma("unroll") for (int m = 0; m < 4; ++m) _Pragma("unroll") for (int k = 0; k < 2; ++k) dst[m][k] = *(const PG8_LAS bf16x8*)(lds + PG8_SA(b, h) + aoff + m * 2048 + k * 1024); } while (0)
; #define PG8_LDB(dst, b, h) do { _Pragma("unroll") for (int n = 0; n < 2; ++n) _Pragma("unroll") for (int k = 0; k < 2; ++k) dst[n][k] = *(const PG8_LAS bf16x8*)(lds + PG8_SB(b, h) + boff + n * 2048 + k * 1024); } while (0)
; #define PG8_WAIT_V(n) asm volatile("s_waitcnt vmcnt(" #n ")" ::: "memory")
; #define PG8_WAIT_L(n) asm volatile("s_waitcnt lgkmcnt(" #n ")" ::: "memory")
; #define PG8_BAR __builtin_amdgcn_s_barrier()
; #define PG8_SCHED __builtin_amdgcn_sched_barrier(0)
; template <class Epi, class Sched, bool ALIGN_EPI = false, bool SP2 = false, bool F8 = false>
; __device__ __forceinline__ void gemm_phase(PG8_LAS unsigned char* lds, const Gemm g, const Sched& S, const Epi& E) {
;     ...
;             PG8_LDB(B0, 1, 0); PG8_LDB(B1, 1, 1); PG8_SCHED; PG8_LDA(At, 1, 0); PG8_STAGE(PG8_SA(0, 1), a2 + hA, voffA);
;             PG8_WAIT_V(8); PG8_WAIT_L(0); PG8_BAR; PG8_MMA(0, 0, At, B0); PG8_MMA(0, 1, At, B1); PG8_BAR; PG8_SCHED;
;             PG8_LDA(At, 1, 1); PG8_STAGE(PG8_SB(1, 0), b3, voffB); PG8_STAGE(PG8_SB(1, 1), b3 + hB, voffB); PG8_STAGE(PG8_SA(1, 0), a3, voffA);
;             PG8_WAIT_V(8); PG8_WAIT_L(0); PG8_BAR; PG8_MMA(1, 0, At, B0); PG8_MMA(1, 1, At, B1); PG8_BAR; PG8_SCHED;
	s_setprio 0
	s_add_i32 s52, 0, 0x18000
	s_add_i32 s53, 0, 0x1c000
	v_add_u32_e32 v14, s52, v188
	v_add_u32_e32 v30, s53, v188
	ds_read_b128 v[2:5], v14
	ds_read_b128 v[6:9], v14 offset:1024
	ds_read_b128 v[10:13], v14 offset:2048
	ds_read_b128 v[14:17], v14 offset:3072
	ds_read_b128 v[18:21], v30
	ds_read_b128 v[22:25], v30 offset:1024
	ds_read_b128 v[26:29], v30 offset:2048
	ds_read_b128 v[30:33], v30 offset:3072
	s_add_u32 s34, s34, 0x40000
	s_addc_u32 s35, s35, 0
	s_mov_b32 m0, s38
	v_lshl_add_u64 v[226:227], s[34:35], 0, v[168:169]
	ds_read_b128 v[194:197], v192 offset:32768
	ds_read_b128 v[198:201], v192 offset:33792
	ds_read_b128 v[202:205], v192 offset:34816
	ds_read_b128 v[206:209], v192 offset:35840
	ds_read_b128 v[210:213], v192 offset:36864
	ds_read_b128 v[214:217], v192 offset:37888
	ds_read_b128 v[218:221], v192 offset:38912
	ds_read_b128 v[222:225], v192 offset:39936
	global_load_lds_dwordx4 v[226:227], off
	v_lshl_add_u64 v[226:227], s[34:35], 0, v[164:165]
	s_mov_b32 m0, s39
	s_nop 0
	global_load_lds_dwordx4 v[226:227], off
	s_waitcnt vmcnt(8) lgkmcnt(0)
	s_setprio 1
	s_barrier
	v_mfma_scale_f32_16x16x128_f8f6f4 v[158:161], v[2:9], v[194:201], v[158:161], v186, v186 op_sel_hi:[0,0,0]
	v_mfma_scale_f32_16x16x128_f8f6f4 v[154:157], v[10:17], v[194:201], v[154:157], v186, v186 op_sel_hi:[0,0,0]
	v_mfma_scale_f32_16x16x128_f8f6f4 v[146:149], v[2:9], v[202:209], v[146:149], v186, v186 op_sel_hi:[0,0,0]
	v_mfma_scale_f32_16x16x128_f8f6f4 v[138:141], v[10:17], v[202:209], v[138:141], v186, v186 op_sel_hi:[0,0,0]
	v_mfma_scale_f32_16x16x128_f8f6f4 v[130:133], v[2:9], v[210:217], v[130:133], v186, v186 op_sel_hi:[0,0,0]
	v_mfma_scale_f32_16x16x128_f8f6f4 v[122:125], v[10:17], v[210:217], v[122:125], v186, v186 op_sel_hi:[0,0,0]
	v_mfma_scale_f32_16x16x128_f8f6f4 v[114:117], v[2:9], v[218:225], v[114:117], v186, v186 op_sel_hi:[0,0,0]
	v_mfma_scale_f32_16x16x128_f8f6f4 v[106:109], v[10:17], v[218:225], v[106:109], v186, v186 op_sel_hi:[0,0,0]
	v_mfma_scale_f32_16x16x128_f8f6f4 v[150:153], v[18:25], v[194:201], v[150:153], v186, v186 op_sel_hi:[0,0,0]
	v_mfma_scale_f32_16x16x128_f8f6f4 v[142:145], v[26:33], v[194:201], v[142:145], v186, v186 op_sel_hi:[0,0,0]
	v_mfma_scale_f32_16x16x128_f8f6f4 v[134:137], v[18:25], v[202:209], v[134:137], v186, v186 op_sel_hi:[0,0,0]
	v_mfma_scale_f32_16x16x128_f8f6f4 v[126:129], v[26:33], v[202:209], v[126:129], v186, v186 op_sel_hi:[0,0,0]
	v_mfma_scale_f32_16x16x128_f8f6f4 v[118:121], v[18:25], v[210:217], v[118:121], v186, v186 op_sel_hi:[0,0,0]
	v_mfma_scale_f32_16x16x128_f8f6f4 v[110:113], v[26:33], v[210:217], v[110:113], v186, v186 op_sel_hi:[0,0,0]
	v_mfma_scale_f32_16x16x128_f8f6f4 v[102:105], v[18:25], v[218:225], v[102:105], v186, v186 op_sel_hi:[0,0,0]
	v_mfma_scale_f32_16x16x128_f8f6f4 v[98:101], v[26:33], v[218:225], v[98:101], v186, v186 op_sel_hi:[0,0,0]
	s_barrier
	s_setprio 0
	s_add_i32 s34, s52, s19
	v_lshl_add_u64 v[178:179], v[178:179], 0, s[14:15]
	s_mov_b32 m0, s34
	ds_read_b128 v[194:197], v192 offset:49152
	ds_read_b128 v[198:201], v192 offset:50176
	ds_read_b128 v[202:205], v192 offset:51200
	ds_read_b128 v[206:209], v192 offset:52224
	ds_read_b128 v[210:213], v192 offset:53248
	ds_read_b128 v[214:217], v192 offset:54272
	ds_read_b128 v[218:221], v192 offset:55296
	ds_read_b128 v[222:225], v192 offset:56320
	global_load_lds_dwordx4 v[178:179], off
	s_add_i32 m0, s34, 0x2000
	s_add_u32 s30, s30, 0x40080
	v_lshl_add_u64 v[178:179], v[180:181], 0, s[14:15]
	s_addc_u32 s31, s31, 0
	s_add_i32 s34, s53, s19
	global_load_lds_dwordx4 v[178:179], off
	v_lshl_add_u64 v[178:179], s[30:31], 0, v[166:167]
	s_mov_b32 m0, s34
	s_nop 0
	global_load_lds_dwordx4 v[178:179], off
	v_lshl_add_u64 v[178:179], s[30:31], 0, v[162:163]
	s_add_i32 m0, s34, 0x2000
	s_nop 0
	global_load_lds_dwordx4 v[178:179], off
	v_lshl_add_u64 v[178:179], v[182:183], 0, s[14:15]
	s_mov_b32 m0, s41
	s_nop 0
	global_load_lds_dwordx4 v[178:179], off
	v_lshl_add_u64 v[178:179], v[184:185], 0, s[14:15]
	s_mov_b32 m0, s42
	s_nop 0
	global_load_lds_dwordx4 v[178:179], off
	s_waitcnt vmcnt(8) lgkmcnt(0)
	s_setprio 1
	s_barrier
	v_mfma_scale_f32_16x16x128_f8f6f4 v[94:97], v[2:9], v[194:201], v[94:97], v186, v186 op_sel_hi:[0,0,0]
	v_mfma_scale_f32_16x16x128_f8f6f4 v[90:93], v[10:17], v[194:201], v[90:93], v186, v186 op_sel_hi:[0,0,0]
	v_mfma_scale_f32_16x16x128_f8f6f4 v[82:85], v[2:9], v[202:209], v[82:85], v186, v186 op_sel_hi:[0,0,0]
	v_mfma_scale_f32_16x16x128_f8f6f4 v[74:77], v[10:17], v[202:209], v[74:77], v186, v186 op_sel_hi:[0,0,0]
	v_mfma_scale_f32_16x16x128_f8f6f4 v[66:69], v[2:9], v[210:217], v[66:69], v186, v186 op_sel_hi:[0,0,0]
	v_mfma_scale_f32_16x16x128_f8f6f4 v[58:61], v[10:17], v[210:217], v[58:61], v186, v186 op_sel_hi:[0,0,0]
	v_mfma_scale_f32_16x16x128_f8f6f4 v[50:53], v[2:9], v[218:225], v[50:53], v186, v186 op_sel_hi:[0,0,0]
	v_mfma_scale_f32_16x16x128_f8f6f4 v[42:45], v[10:17], v[218:225], v[42:45], v186, v186 op_sel_hi:[0,0,0]
	v_mfma_scale_f32_16x16x128_f8f6f4 v[86:89], v[18:25], v[194:201], v[86:89], v186, v186 op_sel_hi:[0,0,0]
	v_mfma_scale_f32_16x16x128_f8f6f4 v[78:81], v[26:33], v[194:201], v[78:81], v186, v186 op_sel_hi:[0,0,0]
	v_mfma_scale_f32_16x16x128_f8f6f4 v[70:73], v[18:25], v[202:209], v[70:73], v186, v186 op_sel_hi:[0,0,0]
	v_mfma_scale_f32_16x16x128_f8f6f4 v[62:65], v[26:33], v[202:209], v[62:65], v186, v186 op_sel_hi:[0,0,0]
	v_mfma_scale_f32_16x16x128_f8f6f4 v[54:57], v[18:25], v[210:217], v[54:57], v186, v186 op_sel_hi:[0,0,0]
	v_mfma_scale_f32_16x16x128_f8f6f4 v[46:49], v[26:33], v[210:217], v[46:49], v186, v186 op_sel_hi:[0,0,0]
	v_mfma_scale_f32_16x16x128_f8f6f4 v[38:41], v[18:25], v[218:225], v[38:41], v186, v186 op_sel_hi:[0,0,0]
	v_mfma_scale_f32_16x16x128_f8f6f4 v[34:37], v[26:33], v[218:225], v[34:37], v186, v186 op_sel_hi:[0,0,0]
	s_barrier
; #define PG8_GAS __attribute__((address_space(1)))
;     __device__ __forceinline__ void operator()(const f32x4 (&acc)[2][2][4][2], const Unit& un, int wr, int wc, int fr, int fq) const {
;         const int row0 = un.pm * BM + wr * 64 + fr, col0 = un.pn * BM + wc * 32 + 8 * fq;
; #pragma unroll
;         for (int ai = 0; ai < 2; ++ai) {
;             u32x4 gg[4][2], pp[4][2];
; #pragma unroll
;             for (int m = 0; m < 4; ++m)
; #pragma unroll
;                 for (int bj = 0; bj < 2; ++bj) { const size_t off = (size_t)(row0 + ai * HALF + m * 16) * 4096 + col0 + bj * HALF; gg[m][bj] = *(const PG8_GAS u32x4*)(sa + off); pp[m][bj] = *(const PG8_GAS u32x4*)(P + off); }
; template <class Epi, class Sched, bool ALIGN_EPI = false, bool SP2 = false, bool F8 = false>
; __device__ __forceinline__ void gemm_phase(PG8_LAS unsigned char* lds, const Gemm g, const Sched& S, const Epi& E) {
;     ...
;         if constexpr (F8) asm volatile("s_nop 15\n\ts_nop 15\n\ts_nop 7" ::: "memory");
	s_setprio 0
	s_add_i32 s51, s51, 2
	s_add_u32 s49, s49, 0x100
	s_addc_u32 s50, s50, 0
	s_add_u32 s28, s28, 0x100
	s_addc_u32 s29, s29, 0
	s_cmp_gt_u32 s51, 13
	s_cbranch_scc0 .LBB0_630
	v_lshl_add_u32 v182, s26, 8, v187
	v_lshl_or_b32 v180, s46, 8, v189
	v_ashrrev_i32_e32 v183, 31, v182
	v_ashrrev_i32_e32 v181, 31, v180
	v_lshlrev_b64 v[2:3], 12, v[182:183]
	v_lshl_add_u64 v[2:3], v[2:3], 0, v[180:181]
	v_lshlrev_b64 v[2:3], 1, v[2:3]
	s_nop 15
	s_nop 15
	s_nop 7
	v_lshl_add_u64 v[4:5], s[10:11], 0, v[2:3]
	global_load_dwordx4 v[30:33], v[4:5], off
	v_lshl_add_u64 v[4:5], s[12:13], 0, v[2:3]
	global_load_dwordx4 v[194:197], v[4:5], off
	v_or_b32_e32 v2, 0x100, v2
	v_lshl_add_u64 v[4:5], s[10:11], 0, v[2:3]
	v_lshl_add_u64 v[2:3], s[12:13], 0, v[2:3]
	global_load_dwordx4 v[198:201], v[4:5], off
	global_load_dwordx4 v[202:205], v[2:3], off
	v_or_b32_e32 v184, 16, v182
	v_ashrrev_i32_e32 v185, 31, v184
	v_lshlrev_b64 v[2:3], 13, v[182:183]
	v_lshlrev_b64 v[4:5], 12, v[184:185]
	v_lshlrev_b64 v[178:179], 1, v[180:181]
	v_lshl_add_u64 v[2:3], s[10:11], 0, v[2:3]
	v_lshl_add_u64 v[4:5], v[4:5], 0, v[180:181]
	v_lshl_add_u64 v[230:231], v[2:3], 0, v[178:179]
	v_lshlrev_b64 v[2:3], 1, v[4:5]
	v_lshl_add_u64 v[4:5], s[10:11], 0, v[2:3]
	global_load_dwordx4 v[206:209], v[4:5], off
	v_lshl_add_u64 v[4:5], s[12:13], 0, v[2:3]
	global_load_dwordx4 v[210:213], v[4:5], off
	v_or_b32_e32 v28, 32, v182
	v_or_b32_e32 v26, 48, v182
	v_ashrrev_i32_e32 v29, 31, v28
	v_ashrrev_i32_e32 v27, 31, v26
	v_lshlrev_b64 v[6:7], 12, v[28:29]
	v_lshlrev_b64 v[8:9], 12, v[26:27]
	v_lshl_add_u64 v[6:7], v[6:7], 0, v[180:181]
	v_lshl_add_u64 v[8:9], v[8:9], 0, v[180:181]
	v_lshlrev_b64 v[4:5], 1, v[6:7]
	v_lshlrev_b64 v[6:7], 1, v[8:9]
	v_or_b32_e32 v2, 0x100, v2
	v_lshl_add_u64 v[8:9], s[10:11], 0, v[4:5]
	v_lshl_add_u64 v[10:11], s[12:13], 0, v[4:5]
	v_or_b32_e32 v4, 0x100, v4
	v_lshl_add_u64 v[12:13], s[10:11], 0, v[6:7]
	v_lshl_add_u64 v[18:19], s[12:13], 0, v[6:7]
	v_or_b32_e32 v6, 0x100, v6
	v_lshl_add_u64 v[20:21], s[10:11], 0, v[2:3]
	v_lshl_add_u64 v[2:3], s[12:13], 0, v[2:3]
	global_load_dwordx4 v[214:217], v[8:9], off
	global_load_dwordx4 v[218:221], v[10:11], off
	v_lshl_add_u64 v[8:9], s[10:11], 0, v[4:5]
	v_lshl_add_u64 v[4:5], s[12:13], 0, v[4:5]
	global_load_dwordx4 v[14:17], v[12:13], off
	s_nop 0
	global_load_dwordx4 v[10:13], v[18:19], off
	v_lshl_add_u64 v[232:233], s[10:11], 0, v[6:7]
	v_lshl_add_u64 v[234:235], s[12:13], 0, v[6:7]
	global_load_dwordx4 v[222:225], v[20:21], off
	global_load_dwordx4 v[226:229], v[2:3], off
	global_load_dwordx4 v[22:25], v[8:9], off
	s_nop 0
	global_load_dwordx4 v[18:21], v[4:5], off
	global_load_dwordx4 v[6:9], v[232:233], off
	s_nop 0
	global_load_dwordx4 v[2:5], v[234:235], off
	s_and_b64 vcc, exec, s[8:9]
	s_mov_b32 s46, s16
	s_mov_b32 s26, s20
	s_mov_b64 s[28:29], s[24:25]
	s_mov_b64 s[30:31], s[22:23]
	s_waitcnt vmcnt(0)
	v_lshlrev_b32_e32 v232, 16, v30
	v_and_b32_e32 v233, 0xffff0000, v30
	v_lshlrev_b32_e32 v234, 16, v194
	v_and_b32_e32 v235, 0xffff0000, v194
	v_lshlrev_b32_e32 v30, 16, v31
	v_and_b32_e32 v31, 0xffff0000, v31
	v_lshlrev_b32_e32 v194, 16, v195
	v_and_b32_e32 v195, 0xffff0000, v195
	v_lshlrev_b32_e32 v236, 16, v32
	v_and_b32_e32 v237, 0xffff0000, v32
	v_lshlrev_b32_e32 v238, 16, v196
	v_and_b32_e32 v239, 0xffff0000, v196
	v_lshlrev_b32_e32 v32, 16, v33
	v_and_b32_e32 v33, 0xffff0000, v33
	v_lshlrev_b32_e32 v196, 16, v197
	v_and_b32_e32 v197, 0xffff0000, v197
	v_pk_fma_f32 v[158:159], v[158:159], v[232:233], v[234:235]
	v_pk_fma_f32 v[160:161], v[160:161], v[30:31], v[194:195]
	v_pk_fma_f32 v[154:155], v[154:155], v[236:237], v[238:239]
	v_pk_fma_f32 v[156:157], v[156:157], v[32:33], v[196:197]
	v_cvt_pk_bf16_f32 v30, v158, v159
	v_cvt_pk_bf16_f32 v31, v160, v161
	v_cvt_pk_bf16_f32 v32, v154, v155
	v_cvt_pk_bf16_f32 v33, v156, v157
	v_lshlrev_b32_e32 v194, 16, v198
	global_store_dwordx4 v[230:231], v[30:33], off
	v_and_b32_e32 v195, 0xffff0000, v198
	s_nop 0
	v_lshlrev_b32_e32 v30, 16, v202
	v_and_b32_e32 v31, 0xffff0000, v202
	v_pk_fma_f32 v[30:31], v[150:151], v[194:195], v[30:31]
	v_lshlrev_b32_e32 v32, 16, v199
	v_and_b32_e32 v33, 0xffff0000, v199
	v_lshlrev_b32_e32 v150, 16, v203
	v_and_b32_e32 v151, 0xffff0000, v203
	v_pk_fma_f32 v[32:33], v[152:153], v[32:33], v[150:151]
	v_cvt_pk_bf16_f32 v30, v30, v31
	v_cvt_pk_bf16_f32 v31, v32, v33
	v_lshlrev_b32_e32 v32, 16, v200
	v_and_b32_e32 v33, 0xffff0000, v200
	v_lshlrev_b32_e32 v150, 16, v204
	v_and_b32_e32 v151, 0xffff0000, v204
	v_pk_fma_f32 v[32:33], v[142:143], v[32:33], v[150:151]
	v_lshlrev_b32_e32 v142, 16, v201
	v_and_b32_e32 v143, 0xffff0000, v201
	v_lshlrev_b32_e32 v150, 16, v205
	v_and_b32_e32 v151, 0xffff0000, v205
	v_pk_fma_f32 v[142:143], v[144:145], v[142:143], v[150:151]
	v_cvt_pk_bf16_f32 v32, v32, v33
	v_cvt_pk_bf16_f32 v33, v142, v143
	global_store_dwordx4 v[230:231], v[30:33], off offset:256
	v_lshlrev_b32_e32 v144, 16, v211
	v_and_b32_e32 v145, 0xffff0000, v211
	v_lshlrev_b32_e32 v30, 16, v206
	v_and_b32_e32 v31, 0xffff0000, v206
	v_lshlrev_b32_e32 v32, 16, v210
	v_and_b32_e32 v33, 0xffff0000, v210
	v_pk_fma_f32 v[30:31], v[146:147], v[30:31], v[32:33]
	v_lshlrev_b32_e32 v32, 16, v207
	v_and_b32_e32 v33, 0xffff0000, v207
	v_pk_fma_f32 v[32:33], v[148:149], v[32:33], v[144:145]
	v_cvt_pk_bf16_f32 v30, v30, v31
	v_cvt_pk_bf16_f32 v31, v32, v33
	v_lshlrev_b32_e32 v32, 16, v208
	v_and_b32_e32 v33, 0xffff0000, v208
	v_lshlrev_b32_e32 v144, 16, v212
	v_and_b32_e32 v145, 0xffff0000, v212
	v_pk_fma_f32 v[32:33], v[138:139], v[32:33], v[144:145]
	v_lshlrev_b32_e32 v138, 16, v209
	v_and_b32_e32 v139, 0xffff0000, v209
; #define PG8_GAS __attribute__((address_space(1)))
; __device__ __forceinline__ unsigned cvt_pk_bf16(float lo, float hi) { const f32x2c v = {lo, hi}; return __builtin_bit_cast(unsigned, __builtin_convertvector(v, bf16x2c)); }
; __device__ __forceinline__ float bf_lo(unsigned w) { return __uint_as_float(w << 16); }
; __device__ __forceinline__ float bf_hi(unsigned w) { return __uint_as_float(w & 0xffff0000u); }
;     __device__ __forceinline__ void operator()(const f32x4 (&acc)[2][2][4][2], const Unit& un, int wr, int wc, int fr, int fq) const {
;     ...
;                 for (int bj = 0; bj < 2; ++bj) { const u32x4 g = gg[m][bj], p = pp[m][bj]; const f32x4 v0 = acc[ai][bj][m][0], v1 = acc[ai][bj][m][1];
;                     u32x4 w; w.x = cvt_pk_bf16(v0[0] * bf_lo(g.x) + bf_lo(p.x), v0[1] * bf_hi(g.x) + bf_hi(p.x)); w.y = cvt_pk_bf16(v0[2] * bf_lo(g.y) + bf_lo(p.y), v0[3] * bf_hi(g.y) + bf_hi(p.y));
;                     w.z = cvt_pk_bf16(v1[0] * bf_lo(g.z) + bf_lo(p.z), v1[1] * bf_hi(g.z) + bf_hi(p.z)); w.w = cvt_pk_bf16(v1[2] * bf_lo(g.w) + bf_lo(p.w), v1[3] * bf_hi(g.w) + bf_hi(p.w));
;                     *(PG8_GAS u32x4*)(sa + (size_t)(row0 + ai * HALF + m * 16) * 4096 + col0 + bj * HALF) = w; }
	v_lshlrev_b32_e32 v144, 16, v213
	v_and_b32_e32 v145, 0xffff0000, v213
	v_lshlrev_b64 v[142:143], 13, v[184:185]
	v_pk_fma_f32 v[138:139], v[140:141], v[138:139], v[144:145]
	v_cvt_pk_bf16_f32 v32, v32, v33
	v_cvt_pk_bf16_f32 v33, v138, v139
	v_lshl_add_u64 v[138:139], s[10:11], 0, v[142:143]
	v_lshl_add_u64 v[138:139], v[138:139], 0, v[178:179]
	global_store_dwordx4 v[138:139], v[30:33], off
	s_nop 1
	v_lshlrev_b32_e32 v30, 16, v222
	v_and_b32_e32 v31, 0xffff0000, v222
	v_lshlrev_b32_e32 v32, 16, v226
	v_and_b32_e32 v33, 0xffff0000, v226
	v_pk_fma_f32 v[30:31], v[134:135], v[30:31], v[32:33]
	v_lshlrev_b32_e32 v32, 16, v223
	v_and_b32_e32 v33, 0xffff0000, v223
	v_lshlrev_b32_e32 v134, 16, v227
	v_and_b32_e32 v135, 0xffff0000, v227
	v_pk_fma_f32 v[32:33], v[136:137], v[32:33], v[134:135]
	v_cvt_pk_bf16_f32 v30, v30, v31
	v_cvt_pk_bf16_f32 v31, v32, v33
	v_lshlrev_b32_e32 v32, 16, v224
	v_and_b32_e32 v33, 0xffff0000, v224
	v_lshlrev_b32_e32 v134, 16, v228
	v_and_b32_e32 v135, 0xffff0000, v228
	v_pk_fma_f32 v[32:33], v[126:127], v[32:33], v[134:135]
	v_lshlrev_b32_e32 v126, 16, v225
	v_and_b32_e32 v127, 0xffff0000, v225
	v_lshlrev_b32_e32 v134, 16, v229
	v_and_b32_e32 v135, 0xffff0000, v229
	v_pk_fma_f32 v[126:127], v[128:129], v[126:127], v[134:135]
	v_cvt_pk_bf16_f32 v32, v32, v33
	v_cvt_pk_bf16_f32 v33, v126, v127
	global_store_dwordx4 v[138:139], v[30:33], off offset:256
	v_lshlrev_b32_e32 v126, 16, v219
	v_and_b32_e32 v127, 0xffff0000, v219
	v_lshlrev_b64 v[32:33], 13, v[28:29]
	v_lshlrev_b32_e32 v28, 16, v214
	v_and_b32_e32 v29, 0xffff0000, v214
	v_lshlrev_b32_e32 v30, 16, v218
	v_and_b32_e32 v31, 0xffff0000, v218
	v_pk_fma_f32 v[28:29], v[130:131], v[28:29], v[30:31]
	v_lshlrev_b32_e32 v30, 16, v215
	v_and_b32_e32 v31, 0xffff0000, v215
	v_pk_fma_f32 v[30:31], v[132:133], v[30:31], v[126:127]
	v_cvt_pk_bf16_f32 v28, v28, v29
	v_cvt_pk_bf16_f32 v29, v30, v31
	v_lshlrev_b32_e32 v30, 16, v216
	v_and_b32_e32 v31, 0xffff0000, v216
	v_lshlrev_b32_e32 v126, 16, v220
	v_and_b32_e32 v127, 0xffff0000, v220
	v_pk_fma_f32 v[30:31], v[122:123], v[30:31], v[126:127]
	v_lshlrev_b32_e32 v122, 16, v217
	v_and_b32_e32 v123, 0xffff0000, v217
	v_lshlrev_b32_e32 v126, 16, v221
	v_and_b32_e32 v127, 0xffff0000, v221
	v_pk_fma_f32 v[122:123], v[124:125], v[122:123], v[126:127]
	v_lshl_add_u64 v[32:33], s[10:11], 0, v[32:33]
	v_cvt_pk_bf16_f32 v30, v30, v31
	v_cvt_pk_bf16_f32 v31, v122, v123
	v_lshl_add_u64 v[32:33], v[32:33], 0, v[178:179]
	global_store_dwordx4 v[32:33], v[28:31], off
	v_add_u32_e32 v132, 0x80, v182
	v_ashrrev_i32_e32 v133, 31, v132
	v_lshlrev_b32_e32 v28, 16, v22
	v_and_b32_e32 v29, 0xffff0000, v22
	v_lshlrev_b32_e32 v30, 16, v18
	v_and_b32_e32 v31, 0xffff0000, v18
	v_pk_fma_f32 v[28:29], v[118:119], v[28:29], v[30:31]
	v_lshlrev_b32_e32 v22, 16, v23
	v_cvt_pk_bf16_f32 v18, v28, v29
	v_and_b32_e32 v23, 0xffff0000, v23
	v_lshlrev_b32_e32 v28, 16, v19
	v_and_b32_e32 v29, 0xffff0000, v19
	v_pk_fma_f32 v[22:23], v[120:121], v[22:23], v[28:29]
	v_lshlrev_b32_e32 v28, 16, v20
	v_cvt_pk_bf16_f32 v19, v22, v23
	v_lshlrev_b32_e32 v22, 16, v24
	v_and_b32_e32 v23, 0xffff0000, v24
	v_and_b32_e32 v29, 0xffff0000, v20
	v_pk_fma_f32 v[22:23], v[110:111], v[22:23], v[28:29]
	v_lshlrev_b32_e32 v24, 16, v21
	v_cvt_pk_bf16_f32 v20, v22, v23
	v_lshlrev_b32_e32 v22, 16, v25
	v_and_b32_e32 v23, 0xffff0000, v25
	v_and_b32_e32 v25, 0xffff0000, v21
	v_pk_fma_f32 v[22:23], v[112:113], v[22:23], v[24:25]
	v_add_u32_e32 v134, 0x90, v182
	v_cvt_pk_bf16_f32 v21, v22, v23
	global_store_dwordx4 v[32:33], v[18:21], off offset:256
	v_lshlrev_b32_e32 v22, 16, v10
	v_and_b32_e32 v23, 0xffff0000, v10
	v_lshlrev_b32_e32 v20, 16, v14
	v_and_b32_e32 v21, 0xffff0000, v14
	v_pk_fma_f32 v[20:21], v[114:115], v[20:21], v[22:23]
	v_lshlrev_b32_e32 v14, 16, v15
	v_cvt_pk_bf16_f32 v10, v20, v21
	v_and_b32_e32 v15, 0xffff0000, v15
	v_lshlrev_b32_e32 v20, 16, v11
	v_and_b32_e32 v21, 0xffff0000, v11
	v_pk_fma_f32 v[14:15], v[116:117], v[14:15], v[20:21]
	v_lshlrev_b32_e32 v20, 16, v12
	v_cvt_pk_bf16_f32 v11, v14, v15
	v_lshlrev_b32_e32 v14, 16, v16
	v_and_b32_e32 v15, 0xffff0000, v16
	v_and_b32_e32 v21, 0xffff0000, v12
	v_pk_fma_f32 v[14:15], v[106:107], v[14:15], v[20:21]
	v_lshlrev_b32_e32 v16, 16, v13
	v_cvt_pk_bf16_f32 v12, v14, v15
	v_lshlrev_b32_e32 v14, 16, v17
	v_and_b32_e32 v15, 0xffff0000, v17
	v_and_b32_e32 v17, 0xffff0000, v13
	v_lshlrev_b64 v[18:19], 13, v[26:27]
	v_pk_fma_f32 v[14:15], v[108:109], v[14:15], v[16:17]
	v_ashrrev_i32_e32 v135, 31, v134
	v_cvt_pk_bf16_f32 v13, v14, v15
	v_lshl_add_u64 v[14:15], s[10:11], 0, v[18:19]
	v_lshl_add_u64 v[14:15], v[14:15], 0, v[178:179]
	global_store_dwordx4 v[14:15], v[10:13], off
	v_add_u32_e32 v136, 0xa0, v182
	v_ashrrev_i32_e32 v137, 31, v136
	v_lshlrev_b32_e32 v10, 16, v6
	v_and_b32_e32 v11, 0xffff0000, v6
	v_lshlrev_b32_e32 v12, 16, v2
	v_and_b32_e32 v13, 0xffff0000, v2
	v_pk_fma_f32 v[10:11], v[102:103], v[10:11], v[12:13]
	v_lshlrev_b32_e32 v6, 16, v7
	v_cvt_pk_bf16_f32 v2, v10, v11
	v_and_b32_e32 v7, 0xffff0000, v7
	v_lshlrev_b32_e32 v10, 16, v3
	v_and_b32_e32 v11, 0xffff0000, v3
	v_pk_fma_f32 v[6:7], v[104:105], v[6:7], v[10:11]
	v_lshlrev_b32_e32 v10, 16, v4
	v_cvt_pk_bf16_f32 v3, v6, v7
	v_lshlrev_b32_e32 v6, 16, v8
	v_and_b32_e32 v7, 0xffff0000, v8
	v_and_b32_e32 v11, 0xffff0000, v4
	v_pk_fma_f32 v[6:7], v[98:99], v[6:7], v[10:11]
	v_lshlrev_b32_e32 v8, 16, v5
	v_cvt_pk_bf16_f32 v4, v6, v7
	v_lshlrev_b32_e32 v6, 16, v9
	v_and_b32_e32 v7, 0xffff0000, v9
	v_and_b32_e32 v9, 0xffff0000, v5
	v_pk_fma_f32 v[6:7], v[100:101], v[6:7], v[8:9]
	v_add_u32_e32 v98, 0xb0, v182
	v_cvt_pk_bf16_f32 v5, v6, v7
; #define PG8_GAS __attribute__((address_space(1)))
; __device__ __forceinline__ unsigned cvt_pk_bf16(float lo, float hi) { const f32x2c v = {lo, hi}; return __builtin_bit_cast(unsigned, __builtin_convertvector(v, bf16x2c)); }
; __device__ __forceinline__ float bf_lo(unsigned w) { return __uint_as_float(w << 16); }
; __device__ __forceinline__ float bf_hi(unsigned w) { return __uint_as_float(w & 0xffff0000u); }
;     __device__ __forceinline__ void operator()(const f32x4 (&acc)[2][2][4][2], const Unit& un, int wr, int wc, int fr, int fq) const {
;     ...
;             for (int m = 0; m < 4; ++m)
; #pragma unroll
;                 for (int bj = 0; bj < 2; ++bj) { const size_t off = (size_t)(row0 + ai * HALF + m * 16) * 4096 + col0 + bj * HALF; gg[m][bj] = *(const PG8_GAS u32x4*)(sa + off); pp[m][bj] = *(const PG8_GAS u32x4*)(P + off); }
;             asm volatile("" ::: "memory");
; #pragma unroll
;             for (int m = 0; m < 4; ++m)
; #pragma unroll
;                 for (int bj = 0; bj < 2; ++bj) { const u32x4 g = gg[m][bj], p = pp[m][bj]; const f32x4 v0 = acc[ai][bj][m][0], v1 = acc[ai][bj][m][1];
;                     u32x4 w; w.x = cvt_pk_bf16(v0[0] * bf_lo(g.x) + bf_lo(p.x), v0[1] * bf_hi(g.x) + bf_hi(p.x)); w.y = cvt_pk_bf16(v0[2] * bf_lo(g.y) + bf_lo(p.y), v0[3] * bf_hi(g.y) + bf_hi(p.y));
;                     w.z = cvt_pk_bf16(v1[0] * bf_lo(g.z) + bf_lo(p.z), v1[1] * bf_hi(g.z) + bf_hi(p.z)); w.w = cvt_pk_bf16(v1[2] * bf_lo(g.w) + bf_lo(p.w), v1[3] * bf_hi(g.w) + bf_hi(p.w));
;                     *(PG8_GAS u32x4*)(sa + (size_t)(row0 + ai * HALF + m * 16) * 4096 + col0 + bj * HALF) = w; }
	global_store_dwordx4 v[14:15], v[2:5], off offset:256
	v_ashrrev_i32_e32 v99, 31, v98
	s_nop 0
	v_lshlrev_b64 v[2:3], 12, v[132:133]
	v_lshl_add_u64 v[2:3], v[2:3], 0, v[180:181]
	v_lshlrev_b64 v[2:3], 1, v[2:3]
	v_lshl_add_u64 v[4:5], s[10:11], 0, v[2:3]
	global_load_dwordx4 v[100:103], v[4:5], off
	v_lshl_add_u64 v[4:5], s[12:13], 0, v[2:3]
	global_load_dwordx4 v[104:107], v[4:5], off
	v_or_b32_e32 v2, 0x100, v2
	v_lshl_add_u64 v[4:5], s[10:11], 0, v[2:3]
	v_lshl_add_u64 v[2:3], s[12:13], 0, v[2:3]
	global_load_dwordx4 v[108:111], v[4:5], off
	global_load_dwordx4 v[112:115], v[2:3], off
	v_lshlrev_b64 v[2:3], 12, v[134:135]
	v_lshl_add_u64 v[2:3], v[2:3], 0, v[180:181]
	v_lshlrev_b64 v[2:3], 1, v[2:3]
	v_lshl_add_u64 v[4:5], s[10:11], 0, v[2:3]
	v_lshl_add_u64 v[6:7], s[12:13], 0, v[2:3]
	global_load_dwordx4 v[116:119], v[4:5], off
	global_load_dwordx4 v[120:123], v[6:7], off
	v_or_b32_e32 v2, 0x100, v2
	v_lshl_add_u64 v[4:5], s[10:11], 0, v[2:3]
	v_lshl_add_u64 v[2:3], s[12:13], 0, v[2:3]
	global_load_dwordx4 v[124:127], v[4:5], off
	global_load_dwordx4 v[128:131], v[2:3], off
	v_lshlrev_b64 v[2:3], 12, v[136:137]
	v_lshl_add_u64 v[2:3], v[2:3], 0, v[180:181]
	v_lshlrev_b64 v[2:3], 1, v[2:3]
	v_lshl_add_u64 v[4:5], s[10:11], 0, v[2:3]
	v_lshl_add_u64 v[6:7], s[12:13], 0, v[2:3]
	global_load_dwordx4 v[30:33], v[4:5], off
	global_load_dwordx4 v[26:29], v[6:7], off
	v_or_b32_e32 v2, 0x100, v2
	v_lshl_add_u64 v[4:5], s[10:11], 0, v[2:3]
	v_lshl_add_u64 v[2:3], s[12:13], 0, v[2:3]
	global_load_dwordx4 v[22:25], v[4:5], off
	global_load_dwordx4 v[18:21], v[2:3], off
	v_lshlrev_b64 v[2:3], 12, v[98:99]
	v_lshl_add_u64 v[2:3], v[2:3], 0, v[180:181]
	v_lshlrev_b64 v[2:3], 1, v[2:3]
	v_lshl_add_u64 v[4:5], s[10:11], 0, v[2:3]
	v_lshl_add_u64 v[6:7], s[12:13], 0, v[2:3]
	global_load_dwordx4 v[14:17], v[4:5], off
	global_load_dwordx4 v[10:13], v[6:7], off
	v_or_b32_e32 v2, 0x100, v2
	v_lshl_add_u64 v[4:5], s[10:11], 0, v[2:3]
	v_lshl_add_u64 v[2:3], s[12:13], 0, v[2:3]
	global_load_dwordx4 v[6:9], v[4:5], off
	s_nop 0
	global_load_dwordx4 v[2:5], v[2:3], off
	v_lshlrev_b64 v[132:133], 13, v[132:133]
	s_waitcnt vmcnt(15)
	v_lshlrev_b32_e32 v138, 16, v100
	v_and_b32_e32 v139, 0xffff0000, v100
	s_waitcnt vmcnt(14)
	v_lshlrev_b32_e32 v140, 16, v104
	v_and_b32_e32 v141, 0xffff0000, v104
	v_lshlrev_b32_e32 v100, 16, v101
	v_and_b32_e32 v101, 0xffff0000, v101
	v_lshlrev_b32_e32 v104, 16, v105
	v_and_b32_e32 v105, 0xffff0000, v105
	v_pk_fma_f32 v[94:95], v[94:95], v[138:139], v[140:141]
	v_pk_fma_f32 v[96:97], v[96:97], v[100:101], v[104:105]
	v_cvt_pk_bf16_f32 v94, v94, v95
	v_cvt_pk_bf16_f32 v95, v96, v97
	v_lshlrev_b32_e32 v96, 16, v102
	v_and_b32_e32 v97, 0xffff0000, v102
	v_lshlrev_b32_e32 v100, 16, v106
	v_and_b32_e32 v101, 0xffff0000, v106
	v_pk_fma_f32 v[90:91], v[90:91], v[96:97], v[100:101]
	v_lshlrev_b32_e32 v100, 16, v107
	v_cvt_pk_bf16_f32 v96, v90, v91
	v_lshlrev_b32_e32 v90, 16, v103
	v_and_b32_e32 v91, 0xffff0000, v103
	v_and_b32_e32 v101, 0xffff0000, v107
	v_pk_fma_f32 v[90:91], v[92:93], v[90:91], v[100:101]
	s_waitcnt vmcnt(13)
	v_lshlrev_b32_e32 v92, 16, v108
	v_cvt_pk_bf16_f32 v97, v90, v91
	v_lshl_add_u64 v[90:91], s[10:11], 0, v[132:133]
	v_lshl_add_u64 v[90:91], v[90:91], 0, v[178:179]
	global_store_dwordx4 v[90:91], v[94:97], off
	v_and_b32_e32 v93, 0xffff0000, v108
	s_waitcnt vmcnt(13)
	v_lshlrev_b32_e32 v94, 16, v112
	v_and_b32_e32 v95, 0xffff0000, v112
	v_pk_fma_f32 v[86:87], v[86:87], v[92:93], v[94:95]
	v_lshlrev_b32_e32 v92, 16, v109
	v_and_b32_e32 v93, 0xffff0000, v109
	v_lshlrev_b32_e32 v94, 16, v113
	v_and_b32_e32 v95, 0xffff0000, v113
	v_pk_fma_f32 v[88:89], v[88:89], v[92:93], v[94:95]
	v_cvt_pk_bf16_f32 v86, v86, v87
	v_cvt_pk_bf16_f32 v87, v88, v89
	v_lshlrev_b32_e32 v88, 16, v110
	v_and_b32_e32 v89, 0xffff0000, v110
	v_lshlrev_b32_e32 v92, 16, v114
	v_and_b32_e32 v93, 0xffff0000, v114
	v_pk_fma_f32 v[78:79], v[78:79], v[88:89], v[92:93]
	v_lshlrev_b32_e32 v92, 16, v115
	v_cvt_pk_bf16_f32 v88, v78, v79
	v_lshlrev_b32_e32 v78, 16, v111
	v_and_b32_e32 v79, 0xffff0000, v111
	v_and_b32_e32 v93, 0xffff0000, v115
	v_pk_fma_f32 v[78:79], v[80:81], v[78:79], v[92:93]
	s_waitcnt vmcnt(11)
	v_lshlrev_b32_e32 v80, 16, v120
	v_cvt_pk_bf16_f32 v89, v78, v79
	v_lshlrev_b32_e32 v78, 16, v116
	v_and_b32_e32 v79, 0xffff0000, v116
	v_and_b32_e32 v81, 0xffff0000, v120
	v_pk_fma_f32 v[78:79], v[82:83], v[78:79], v[80:81]
	v_lshlrev_b32_e32 v80, 16, v117
	v_and_b32_e32 v81, 0xffff0000, v117
	v_lshlrev_b32_e32 v82, 16, v121
	v_and_b32_e32 v83, 0xffff0000, v121
	v_pk_fma_f32 v[80:81], v[84:85], v[80:81], v[82:83]
	v_cvt_pk_bf16_f32 v78, v78, v79
	v_cvt_pk_bf16_f32 v79, v80, v81
	v_lshlrev_b32_e32 v80, 16, v118
	v_and_b32_e32 v81, 0xffff0000, v118
	v_lshlrev_b32_e32 v82, 16, v122
	v_and_b32_e32 v83, 0xffff0000, v122
	v_pk_fma_f32 v[74:75], v[74:75], v[80:81], v[82:83]
	v_lshlrev_b32_e32 v82, 16, v123
	v_cvt_pk_bf16_f32 v80, v74, v75
	v_lshlrev_b32_e32 v74, 16, v119
	v_and_b32_e32 v75, 0xffff0000, v119
	v_and_b32_e32 v83, 0xffff0000, v123
	global_store_dwordx4 v[90:91], v[86:89], off offset:256
	v_pk_fma_f32 v[74:75], v[76:77], v[74:75], v[82:83]
	s_waitcnt vmcnt(11)
	v_lshlrev_b32_e32 v76, 16, v124
	v_lshlrev_b64 v[86:87], 13, v[134:135]
	v_cvt_pk_bf16_f32 v81, v74, v75
	v_lshl_add_u64 v[74:75], s[10:11], 0, v[86:87]
	v_lshl_add_u64 v[74:75], v[74:75], 0, v[178:179]
	global_store_dwordx4 v[74:75], v[78:81], off
	v_and_b32_e32 v77, 0xffff0000, v124
	s_waitcnt vmcnt(11)
; #define PG8_GAS __attribute__((address_space(1)))
; __device__ __forceinline__ unsigned cvt_pk_bf16(float lo, float hi) { const f32x2c v = {lo, hi}; return __builtin_bit_cast(unsigned, __builtin_convertvector(v, bf16x2c)); }
; __device__ __forceinline__ float bf_lo(unsigned w) { return __uint_as_float(w << 16); }
; __device__ __forceinline__ float bf_hi(unsigned w) { return __uint_as_float(w & 0xffff0000u); }
; #define PG8_WAIT_V(n) asm volatile("s_waitcnt vmcnt(" #n ")" ::: "memory")
; #define PG8_BAR __builtin_amdgcn_s_barrier()
;     __device__ __forceinline__ void operator()(const f32x4 (&acc)[2][2][4][2], const Unit& un, int wr, int wc, int fr, int fq) const {
;     ...
;                 for (int bj = 0; bj < 2; ++bj) { const u32x4 g = gg[m][bj], p = pp[m][bj]; const f32x4 v0 = acc[ai][bj][m][0], v1 = acc[ai][bj][m][1];
;                     u32x4 w; w.x = cvt_pk_bf16(v0[0] * bf_lo(g.x) + bf_lo(p.x), v0[1] * bf_hi(g.x) + bf_hi(p.x)); w.y = cvt_pk_bf16(v0[2] * bf_lo(g.y) + bf_lo(p.y), v0[3] * bf_hi(g.y) + bf_hi(p.y));
;                     w.z = cvt_pk_bf16(v1[0] * bf_lo(g.z) + bf_lo(p.z), v1[1] * bf_hi(g.z) + bf_hi(p.z)); w.w = cvt_pk_bf16(v1[2] * bf_lo(g.w) + bf_lo(p.w), v1[3] * bf_hi(g.w) + bf_hi(p.w));
;                     *(PG8_GAS u32x4*)(sa + (size_t)(row0 + ai * HALF + m * 16) * 4096 + col0 + bj * HALF) = w; }
; template <class Epi, class Sched, bool ALIGN_EPI = false, bool SP2 = false, bool F8 = false>
; __device__ __forceinline__ void gemm_phase(PG8_LAS unsigned char* lds, const Gemm g, const Sched& S, const Epi& E) {
;     ...
;         if (!has_next) break;
; #pragma unroll
;         for (int a = 0; a < 2; ++a)
; #pragma unroll
;             for (int b = 0; b < 2; ++b)
; #pragma unroll
;                 for (int m = 0; m < 4; ++m)
; #pragma unroll
;                     for (int n = 0; n < 2; ++n) acc[a][b][m][n] = (f32x4){0.f, 0.f, 0.f, 0.f};
;         cur = nxt; cA = nA; cB = nB; ++ui;
;         if constexpr (ALIGN_EPI) { if (wr == 1) PG8_BAR; }
;     }
;     PG8_WAIT_V(0);
;     if constexpr (!ALIGN_EPI) { if (wr == 0) PG8_BAR; }
	v_lshlrev_b32_e32 v78, 16, v128
	v_and_b32_e32 v79, 0xffff0000, v128
	v_pk_fma_f32 v[70:71], v[70:71], v[76:77], v[78:79]
	v_lshlrev_b32_e32 v76, 16, v125
	v_and_b32_e32 v77, 0xffff0000, v125
	v_lshlrev_b32_e32 v78, 16, v129
	v_and_b32_e32 v79, 0xffff0000, v129
	v_pk_fma_f32 v[72:73], v[72:73], v[76:77], v[78:79]
	v_cvt_pk_bf16_f32 v70, v70, v71
	v_cvt_pk_bf16_f32 v71, v72, v73
	v_lshlrev_b32_e32 v72, 16, v126
	v_and_b32_e32 v73, 0xffff0000, v126
	v_lshlrev_b32_e32 v76, 16, v130
	v_and_b32_e32 v77, 0xffff0000, v130
	v_pk_fma_f32 v[62:63], v[62:63], v[72:73], v[76:77]
	v_lshlrev_b32_e32 v76, 16, v131
	v_cvt_pk_bf16_f32 v72, v62, v63
	v_lshlrev_b32_e32 v62, 16, v127
	v_and_b32_e32 v63, 0xffff0000, v127
	v_and_b32_e32 v77, 0xffff0000, v131
	v_pk_fma_f32 v[62:63], v[64:65], v[62:63], v[76:77]
	s_waitcnt vmcnt(10)
	v_lshlrev_b32_e32 v64, 16, v30
	v_cvt_pk_bf16_f32 v73, v62, v63
	global_store_dwordx4 v[74:75], v[70:73], off offset:256
	v_and_b32_e32 v65, 0xffff0000, v30
	v_lshlrev_b32_e32 v30, 16, v31
	s_waitcnt vmcnt(10)
	v_lshlrev_b32_e32 v70, 16, v26
	v_and_b32_e32 v71, 0xffff0000, v26
	v_pk_fma_f32 v[64:65], v[66:67], v[64:65], v[70:71]
	v_and_b32_e32 v31, 0xffff0000, v31
	v_cvt_pk_bf16_f32 v26, v64, v65
	v_lshlrev_b32_e32 v64, 16, v27
	v_and_b32_e32 v65, 0xffff0000, v27
	v_pk_fma_f32 v[30:31], v[68:69], v[30:31], v[64:65]
	v_lshlrev_b32_e32 v64, 16, v28
	v_cvt_pk_bf16_f32 v27, v30, v31
	v_lshlrev_b32_e32 v30, 16, v32
	v_and_b32_e32 v31, 0xffff0000, v32
	v_and_b32_e32 v65, 0xffff0000, v28
	v_pk_fma_f32 v[30:31], v[58:59], v[30:31], v[64:65]
	v_lshlrev_b32_e32 v32, 16, v29
	v_cvt_pk_bf16_f32 v28, v30, v31
	v_lshlrev_b32_e32 v30, 16, v33
	v_and_b32_e32 v31, 0xffff0000, v33
	v_and_b32_e32 v33, 0xffff0000, v29
	v_lshlrev_b64 v[62:63], 13, v[136:137]
	v_pk_fma_f32 v[30:31], v[60:61], v[30:31], v[32:33]
	s_nop 0
	v_cvt_pk_bf16_f32 v29, v30, v31
	v_lshl_add_u64 v[30:31], s[10:11], 0, v[62:63]
	v_lshl_add_u64 v[30:31], v[30:31], 0, v[178:179]
	global_store_dwordx4 v[30:31], v[26:29], off
	s_waitcnt vmcnt(10)
	s_nop 0
	v_lshlrev_b32_e32 v26, 16, v22
	v_and_b32_e32 v27, 0xffff0000, v22
	s_waitcnt vmcnt(9)
	v_lshlrev_b32_e32 v28, 16, v18
	v_and_b32_e32 v29, 0xffff0000, v18
	v_pk_fma_f32 v[26:27], v[54:55], v[26:27], v[28:29]
	v_lshlrev_b32_e32 v22, 16, v23
	v_cvt_pk_bf16_f32 v18, v26, v27
	v_and_b32_e32 v23, 0xffff0000, v23
	v_lshlrev_b32_e32 v26, 16, v19
	v_and_b32_e32 v27, 0xffff0000, v19
	v_pk_fma_f32 v[22:23], v[56:57], v[22:23], v[26:27]
	v_lshlrev_b32_e32 v26, 16, v20
	v_cvt_pk_bf16_f32 v19, v22, v23
	v_lshlrev_b32_e32 v22, 16, v24
	v_and_b32_e32 v23, 0xffff0000, v24
	v_and_b32_e32 v27, 0xffff0000, v20
	v_pk_fma_f32 v[22:23], v[46:47], v[22:23], v[26:27]
	v_lshlrev_b32_e32 v24, 16, v21
	v_cvt_pk_bf16_f32 v20, v22, v23
	v_lshlrev_b32_e32 v22, 16, v25
	v_and_b32_e32 v23, 0xffff0000, v25
	v_and_b32_e32 v25, 0xffff0000, v21
	v_pk_fma_f32 v[22:23], v[48:49], v[22:23], v[24:25]
	s_nop 0
	v_cvt_pk_bf16_f32 v21, v22, v23
	global_store_dwordx4 v[30:31], v[18:21], off offset:256
	s_waitcnt vmcnt(8)
	v_lshlrev_b32_e32 v22, 16, v10
	v_and_b32_e32 v23, 0xffff0000, v10
	v_lshlrev_b32_e32 v20, 16, v14
	v_and_b32_e32 v21, 0xffff0000, v14
	v_pk_fma_f32 v[20:21], v[50:51], v[20:21], v[22:23]
	v_lshlrev_b32_e32 v14, 16, v15
	v_cvt_pk_bf16_f32 v10, v20, v21
	v_and_b32_e32 v15, 0xffff0000, v15
	v_lshlrev_b32_e32 v20, 16, v11
	v_and_b32_e32 v21, 0xffff0000, v11
	v_pk_fma_f32 v[14:15], v[52:53], v[14:15], v[20:21]
	v_lshlrev_b32_e32 v20, 16, v12
	v_cvt_pk_bf16_f32 v11, v14, v15
	v_lshlrev_b32_e32 v14, 16, v16
	v_and_b32_e32 v15, 0xffff0000, v16
	v_and_b32_e32 v21, 0xffff0000, v12
	v_pk_fma_f32 v[14:15], v[42:43], v[14:15], v[20:21]
	v_lshlrev_b32_e32 v16, 16, v13
	v_cvt_pk_bf16_f32 v12, v14, v15
	v_lshlrev_b32_e32 v14, 16, v17
	v_and_b32_e32 v15, 0xffff0000, v17
	v_and_b32_e32 v17, 0xffff0000, v13
	v_lshlrev_b64 v[18:19], 13, v[98:99]
	v_pk_fma_f32 v[14:15], v[44:45], v[14:15], v[16:17]
	s_nop 0
	v_cvt_pk_bf16_f32 v13, v14, v15
	v_lshl_add_u64 v[14:15], s[10:11], 0, v[18:19]
	v_lshl_add_u64 v[14:15], v[14:15], 0, v[178:179]
	global_store_dwordx4 v[14:15], v[10:13], off
	s_waitcnt vmcnt(8)
	s_nop 0
	v_lshlrev_b32_e32 v10, 16, v6
	v_and_b32_e32 v11, 0xffff0000, v6
	s_waitcnt vmcnt(7)
	v_lshlrev_b32_e32 v12, 16, v2
	v_and_b32_e32 v13, 0xffff0000, v2
	v_pk_fma_f32 v[10:11], v[38:39], v[10:11], v[12:13]
	v_lshlrev_b32_e32 v6, 16, v7
	v_cvt_pk_bf16_f32 v2, v10, v11
	v_and_b32_e32 v7, 0xffff0000, v7
	v_lshlrev_b32_e32 v10, 16, v3
	v_and_b32_e32 v11, 0xffff0000, v3
	v_pk_fma_f32 v[6:7], v[40:41], v[6:7], v[10:11]
	v_lshlrev_b32_e32 v10, 16, v4
	v_cvt_pk_bf16_f32 v3, v6, v7
	v_lshlrev_b32_e32 v6, 16, v8
	v_and_b32_e32 v7, 0xffff0000, v8
	v_and_b32_e32 v11, 0xffff0000, v4
	v_pk_fma_f32 v[6:7], v[34:35], v[6:7], v[10:11]
	v_lshlrev_b32_e32 v8, 16, v5
	v_cvt_pk_bf16_f32 v4, v6, v7
	v_lshlrev_b32_e32 v6, 16, v9
	v_and_b32_e32 v7, 0xffff0000, v9
	v_and_b32_e32 v9, 0xffff0000, v5
	v_pk_fma_f32 v[6:7], v[36:37], v[6:7], v[8:9]
	s_nop 0
	v_cvt_pk_bf16_f32 v5, v6, v7
	global_store_dwordx4 v[14:15], v[2:5], off offset:256
	s_cbranch_vccz .LBB0_627
	s_waitcnt vmcnt(0)
	s_cmpk_gt_u32 s4, 0xff
	s_cbranch_scc1 .LBB0_634
	s_barrier

; #define PG8_STAGE(bufoff, gbase, voff) do { _Pragma("unroll") for (int _i = 0; _i < 2; ++_i) \
;         __builtin_amdgcn_global_load_lds((const unsigned*)((const char*)(gbase) + (voff)[_i]), (PG8_LAS unsigned*)(lds + (bufoff) + ldsw + _i * 8192), 16, 0, 0); } while (0)
; #define PG8_LDA(dst, b, h) do { _Pragma("unroll") for (int m = 0; m < 4; ++m) _Pragma("unroll") for (int k = 0; k < 2; ++k) dst[m][k] = *(const PG8_LAS bf16x8*)(lds + PG8_SA(b, h) + aoff + m * 2048 + k * 1024); } while (0)
; #define PG8_LDB(dst, b, h) do { _Pragma("unroll") for (int n = 0; n < 2; ++n) _Pragma("unroll") for (int k = 0; k < 2; ++k) dst[n][k] = *(const PG8_LAS bf16x8*)(lds + PG8_SB(b, h) + boff + n * 2048 + k * 1024); } while (0)
; #define PG8_WAIT_V(n) asm volatile("s_waitcnt vmcnt(" #n ")" ::: "memory")
; #define PG8_WAIT_L(n) asm volatile("s_waitcnt lgkmcnt(" #n ")" ::: "memory")
; #define PG8_BAR __builtin_amdgcn_s_barrier()
; #define PG8_SCHED __builtin_amdgcn_sched_barrier(0)
; template <class Epi, class Sched, bool ALIGN_EPI = false, bool SP2 = false, bool F8 = false>
; __device__ __forceinline__ void gemm_phase(PG8_LAS unsigned char* lds, const Gemm g, const Sched& S, const Epi& E) {
;     ...
;             PG8_LDB(B0, 0, 0); PG8_LDB(B1, 0, 1); PG8_SCHED; PG8_LDA(At, 0, 0); PG8_STAGE(PG8_SA(1, 1), a1 + hA, voffA);
;             PG8_WAIT_V(8); PG8_WAIT_L(0); PG8_BAR; PG8_MMA(0, 0, At, B0); PG8_MMA(0, 1, At, B1); PG8_BAR; PG8_SCHED;
;             PG8_LDA(At, 0, 1); PG8_STAGE(PG8_SB(0, 0), b2, voffB); PG8_STAGE(PG8_SB(0, 1), b2 + hB, voffB); PG8_STAGE(PG8_SA(0, 0), a2, voffA);
;             PG8_WAIT_V(8); PG8_WAIT_L(0); PG8_BAR; PG8_MMA(1, 0, At, B0); PG8_MMA(1, 1, At, B1); PG8_BAR; PG8_SCHED;
.LBB0_689:
	ds_read_b128 v[130:133], v210
	ds_read_b128 v[134:137], v210 offset:1024
	ds_read_b128 v[138:141], v210 offset:2048
	ds_read_b128 v[142:145], v210 offset:3072
	ds_read_b128 v[146:149], v211
	ds_read_b128 v[150:153], v211 offset:1024
	ds_read_b128 v[154:157], v211 offset:2048
	ds_read_b128 v[158:161], v211 offset:3072
	s_add_u32 s38, s36, 0xfff00080
	s_addc_u32 s39, s37, -1
	s_cmp_eq_u32 s61, 60
	s_cselect_b32 s41, s17, s39
	s_cselect_b32 s40, s20, s38
	s_cselect_b32 s39, s25, s60
	s_cselect_b32 s38, s27, s35
	v_lshl_add_u64 v[218:219], s[36:37], 0, v[188:189]
	s_add_i32 m0, s33, 0xc000
	ds_read_b128 v[162:165], v212
	ds_read_b128 v[166:169], v212 offset:1024
	ds_read_b128 v[170:173], v212 offset:2048
	ds_read_b128 v[174:177], v212 offset:3072
	ds_read_b128 v[194:197], v212 offset:4096
	ds_read_b128 v[198:201], v212 offset:5120
	ds_read_b128 v[202:205], v212 offset:6144
	ds_read_b128 v[214:217], v212 offset:7168
	global_load_lds_dwordx4 v[218:219], off
	v_lshl_add_u64 v[218:219], s[36:37], 0, v[186:187]
	s_add_i32 m0, s33, 0xe000
	s_nop 0
	global_load_lds_dwordx4 v[218:219], off
	s_waitcnt vmcnt(8) lgkmcnt(0)
	s_setprio 1
	s_barrier
	v_mfma_f32_16x16x32_bf16 v[126:129], v[130:133], v[162:165], v[126:129]
	v_mfma_f32_16x16x32_bf16 v[122:125], v[138:141], v[162:165], v[122:125]
	v_mfma_f32_16x16x32_bf16 v[110:113], v[130:133], v[170:173], v[110:113]
	v_mfma_f32_16x16x32_bf16 v[106:109], v[138:141], v[170:173], v[106:109]
	v_mfma_f32_16x16x32_bf16 v[94:97], v[130:133], v[194:197], v[94:97]
	v_mfma_f32_16x16x32_bf16 v[90:93], v[138:141], v[194:197], v[90:93]
	v_mfma_f32_16x16x32_bf16 v[78:81], v[130:133], v[202:205], v[78:81]
	v_mfma_f32_16x16x32_bf16 v[74:77], v[138:141], v[202:205], v[74:77]
	v_mfma_f32_16x16x32_bf16 v[126:129], v[134:137], v[166:169], v[126:129]
	v_mfma_f32_16x16x32_bf16 v[122:125], v[142:145], v[166:169], v[122:125]
	v_mfma_f32_16x16x32_bf16 v[110:113], v[134:137], v[174:177], v[110:113]
	v_mfma_f32_16x16x32_bf16 v[106:109], v[142:145], v[174:177], v[106:109]
	v_mfma_f32_16x16x32_bf16 v[94:97], v[134:137], v[198:201], v[94:97]
	v_mfma_f32_16x16x32_bf16 v[90:93], v[142:145], v[198:201], v[90:93]
	v_mfma_f32_16x16x32_bf16 v[78:81], v[134:137], v[214:217], v[78:81]
	v_mfma_f32_16x16x32_bf16 v[74:77], v[142:145], v[214:217], v[74:77]
	v_mfma_f32_16x16x32_bf16 v[118:121], v[146:149], v[162:165], v[118:121]
	v_mfma_f32_16x16x32_bf16 v[114:117], v[154:157], v[162:165], v[114:117]
	v_mfma_f32_16x16x32_bf16 v[102:105], v[146:149], v[170:173], v[102:105]
	v_mfma_f32_16x16x32_bf16 v[98:101], v[154:157], v[170:173], v[98:101]
	v_mfma_f32_16x16x32_bf16 v[86:89], v[146:149], v[194:197], v[86:89]
	v_mfma_f32_16x16x32_bf16 v[82:85], v[154:157], v[194:197], v[82:85]
	v_mfma_f32_16x16x32_bf16 v[70:73], v[146:149], v[202:205], v[70:73]
	v_mfma_f32_16x16x32_bf16 v[66:69], v[154:157], v[202:205], v[66:69]
	v_mfma_f32_16x16x32_bf16 v[118:121], v[150:153], v[166:169], v[118:121]
	v_mfma_f32_16x16x32_bf16 v[114:117], v[158:161], v[166:169], v[114:117]
	v_mfma_f32_16x16x32_bf16 v[102:105], v[150:153], v[174:177], v[102:105]
	v_mfma_f32_16x16x32_bf16 v[98:101], v[158:161], v[174:177], v[98:101]
	v_mfma_f32_16x16x32_bf16 v[86:89], v[150:153], v[198:201], v[86:89]
	v_mfma_f32_16x16x32_bf16 v[82:85], v[158:161], v[198:201], v[82:85]
	v_mfma_f32_16x16x32_bf16 v[70:73], v[150:153], v[214:217], v[70:73]
	v_mfma_f32_16x16x32_bf16 v[66:69], v[158:161], v[214:217], v[66:69]
	s_barrier
	s_setprio 0
	s_add_i32 s62, s56, s19
	v_lshl_add_u64 v[218:219], s[38:39], 0, v[180:181]
	s_mov_b32 m0, s62
	ds_read_b128 v[162:165], v212 offset:16384
	ds_read_b128 v[166:169], v212 offset:17408
	ds_read_b128 v[170:173], v212 offset:18432
	ds_read_b128 v[174:177], v212 offset:19456
	ds_read_b128 v[194:197], v212 offset:20480
	ds_read_b128 v[198:201], v212 offset:21504
	ds_read_b128 v[202:205], v212 offset:22528
	ds_read_b128 v[214:217], v212 offset:23552
	global_load_lds_dwordx4 v[218:219], off
	s_add_i32 m0, s62, 0x2000
	s_add_u32 s62, s38, 0x100000
	v_lshl_add_u64 v[220:221], s[38:39], 0, v[184:185]
	s_addc_u32 s63, s39, 0
	s_add_i32 s64, s57, s19
	global_load_lds_dwordx4 v[220:221], off
	v_lshl_add_u64 v[222:223], s[62:63], 0, v[180:181]
	s_mov_b32 m0, s64
	v_lshl_add_u64 v[224:225], s[40:41], 0, v[182:183]
	global_load_lds_dwordx4 v[222:223], off
	v_lshl_add_u64 v[222:223], s[62:63], 0, v[184:185]
	s_add_i32 m0, s64, 0x2000
	s_nop 0
	global_load_lds_dwordx4 v[222:223], off
	v_lshl_add_u64 v[222:223], s[40:41], 0, v[178:179]
	s_mov_b32 m0, s33
	s_nop 0
	global_load_lds_dwordx4 v[222:223], off
	s_mov_b32 m0, s42
	s_nop 0
	global_load_lds_dwordx4 v[224:225], off
	s_waitcnt vmcnt(8) lgkmcnt(0)
	s_setprio 1
	s_barrier
; #define PG8_STAGE(bufoff, gbase, voff) do { _Pragma("unroll") for (int _i = 0; _i < 2; ++_i) \
;         __builtin_amdgcn_global_load_lds((const unsigned*)((const char*)(gbase) + (voff)[_i]), (PG8_LAS unsigned*)(lds + (bufoff) + ldsw + _i * 8192), 16, 0, 0); } while (0)
; #define PG8_LDA(dst, b, h) do { _Pragma("unroll") for (int m = 0; m < 4; ++m) _Pragma("unroll") for (int k = 0; k < 2; ++k) dst[m][k] = *(const PG8_LAS bf16x8*)(lds + PG8_SA(b, h) + aoff + m * 2048 + k * 1024); } while (0)
; #define PG8_LDB(dst, b, h) do { _Pragma("unroll") for (int n = 0; n < 2; ++n) _Pragma("unroll") for (int k = 0; k < 2; ++k) dst[n][k] = *(const PG8_LAS bf16x8*)(lds + PG8_SB(b, h) + boff + n * 2048 + k * 1024); } while (0)
; #define PG8_WAIT_V(n) asm volatile("s_waitcnt vmcnt(" #n ")" ::: "memory")
; #define PG8_WAIT_L(n) asm volatile("s_waitcnt lgkmcnt(" #n ")" ::: "memory")
; #define PG8_BAR __builtin_amdgcn_s_barrier()
; #define PG8_SCHED __builtin_amdgcn_sched_barrier(0)
; template <class Epi, class Sched, bool ALIGN_EPI = false, bool SP2 = false, bool F8 = false>
; __device__ __forceinline__ void gemm_phase(PG8_LAS unsigned char* lds, const Gemm g, const Sched& S, const Epi& E) {
;     ...
;             PG8_WAIT_V(8); PG8_WAIT_L(0); PG8_BAR; PG8_MMA(1, 0, At, B0); PG8_MMA(1, 1, At, B1); PG8_BAR; PG8_SCHED;
;             PG8_LDB(B0, 1, 0); PG8_LDB(B1, 1, 1); PG8_SCHED; PG8_LDA(At, 1, 0); PG8_STAGE(PG8_SA(0, 1), a2 + hA, voffA);
;             PG8_WAIT_V(8); PG8_WAIT_L(0); PG8_BAR; PG8_MMA(0, 0, At, B0); PG8_MMA(0, 1, At, B1); PG8_BAR; PG8_SCHED;
	v_mfma_f32_16x16x32_bf16 v[62:65], v[130:133], v[162:165], v[62:65]
	v_mfma_f32_16x16x32_bf16 v[58:61], v[138:141], v[162:165], v[58:61]
	v_mfma_f32_16x16x32_bf16 v[46:49], v[130:133], v[170:173], v[46:49]
	v_mfma_f32_16x16x32_bf16 v[42:45], v[138:141], v[170:173], v[42:45]
	v_mfma_f32_16x16x32_bf16 v[30:33], v[130:133], v[194:197], v[30:33]
	v_mfma_f32_16x16x32_bf16 v[26:29], v[138:141], v[194:197], v[26:29]
	v_mfma_f32_16x16x32_bf16 v[14:17], v[130:133], v[202:205], v[14:17]
	v_mfma_f32_16x16x32_bf16 v[10:13], v[138:141], v[202:205], v[10:13]
	v_mfma_f32_16x16x32_bf16 v[62:65], v[134:137], v[166:169], v[62:65]
	v_mfma_f32_16x16x32_bf16 v[58:61], v[142:145], v[166:169], v[58:61]
	v_mfma_f32_16x16x32_bf16 v[46:49], v[134:137], v[174:177], v[46:49]
	v_mfma_f32_16x16x32_bf16 v[42:45], v[142:145], v[174:177], v[42:45]
	v_mfma_f32_16x16x32_bf16 v[30:33], v[134:137], v[198:201], v[30:33]
	v_mfma_f32_16x16x32_bf16 v[26:29], v[142:145], v[198:201], v[26:29]
	v_mfma_f32_16x16x32_bf16 v[14:17], v[134:137], v[214:217], v[14:17]
	v_mfma_f32_16x16x32_bf16 v[10:13], v[142:145], v[214:217], v[10:13]
	v_mfma_f32_16x16x32_bf16 v[54:57], v[146:149], v[162:165], v[54:57]
	v_mfma_f32_16x16x32_bf16 v[50:53], v[154:157], v[162:165], v[50:53]
	v_mfma_f32_16x16x32_bf16 v[38:41], v[146:149], v[170:173], v[38:41]
	v_mfma_f32_16x16x32_bf16 v[34:37], v[154:157], v[170:173], v[34:37]
	v_mfma_f32_16x16x32_bf16 v[22:25], v[146:149], v[194:197], v[22:25]
	v_mfma_f32_16x16x32_bf16 v[18:21], v[154:157], v[194:197], v[18:21]
	v_mfma_f32_16x16x32_bf16 v[6:9], v[146:149], v[202:205], v[6:9]
	v_mfma_f32_16x16x32_bf16 v[2:5], v[154:157], v[202:205], v[2:5]
	v_mfma_f32_16x16x32_bf16 v[54:57], v[150:153], v[166:169], v[54:57]
	v_mfma_f32_16x16x32_bf16 v[50:53], v[158:161], v[166:169], v[50:53]
	v_mfma_f32_16x16x32_bf16 v[38:41], v[150:153], v[174:177], v[38:41]
	v_mfma_f32_16x16x32_bf16 v[34:37], v[158:161], v[174:177], v[34:37]
	v_mfma_f32_16x16x32_bf16 v[22:25], v[150:153], v[198:201], v[22:25]
	v_mfma_f32_16x16x32_bf16 v[18:21], v[158:161], v[198:201], v[18:21]
	v_mfma_f32_16x16x32_bf16 v[6:9], v[150:153], v[214:217], v[6:9]
	v_mfma_f32_16x16x32_bf16 v[2:5], v[158:161], v[214:217], v[2:5]
	s_barrier
	s_setprio 0
	s_add_i32 s62, 0, 0x18000
	s_add_i32 s63, 0, 0x1c000
	v_add_u32_e32 v142, s62, v207
	v_add_u32_e32 v158, s63, v207
	ds_read_b128 v[130:133], v142
	ds_read_b128 v[134:137], v142 offset:1024
	ds_read_b128 v[138:141], v142 offset:2048
	ds_read_b128 v[142:145], v142 offset:3072
	ds_read_b128 v[146:149], v158
	ds_read_b128 v[150:153], v158 offset:1024
	ds_read_b128 v[154:157], v158 offset:2048
	ds_read_b128 v[158:161], v158 offset:3072
	s_add_u32 s40, s40, 0x100000
	s_addc_u32 s41, s41, 0
	s_mov_b32 m0, s43
	v_lshl_add_u64 v[226:227], s[40:41], 0, v[178:179]
	ds_read_b128 v[162:165], v212 offset:32768
	ds_read_b128 v[166:169], v212 offset:33792
	ds_read_b128 v[170:173], v212 offset:34816
	ds_read_b128 v[174:177], v212 offset:35840
	ds_read_b128 v[194:197], v212 offset:36864
	ds_read_b128 v[198:201], v212 offset:37888
	ds_read_b128 v[202:205], v212 offset:38912
	ds_read_b128 v[214:217], v212 offset:39936
	global_load_lds_dwordx4 v[226:227], off
	v_lshl_add_u64 v[226:227], s[40:41], 0, v[182:183]
	s_mov_b32 m0, s44
	s_nop 0
	global_load_lds_dwordx4 v[226:227], off
	s_waitcnt vmcnt(8) lgkmcnt(0)
	s_setprio 1
	s_barrier
	v_mfma_f32_16x16x32_bf16 v[126:129], v[130:133], v[162:165], v[126:129]
	v_mfma_f32_16x16x32_bf16 v[122:125], v[138:141], v[162:165], v[122:125]
	v_mfma_f32_16x16x32_bf16 v[110:113], v[130:133], v[170:173], v[110:113]
	v_mfma_f32_16x16x32_bf16 v[106:109], v[138:141], v[170:173], v[106:109]
	v_mfma_f32_16x16x32_bf16 v[94:97], v[130:133], v[194:197], v[94:97]
	v_mfma_f32_16x16x32_bf16 v[90:93], v[138:141], v[194:197], v[90:93]
	v_mfma_f32_16x16x32_bf16 v[78:81], v[130:133], v[202:205], v[78:81]
	v_mfma_f32_16x16x32_bf16 v[74:77], v[138:141], v[202:205], v[74:77]
	v_mfma_f32_16x16x32_bf16 v[126:129], v[134:137], v[166:169], v[126:129]
	v_mfma_f32_16x16x32_bf16 v[122:125], v[142:145], v[166:169], v[122:125]
	v_mfma_f32_16x16x32_bf16 v[110:113], v[134:137], v[174:177], v[110:113]
	v_mfma_f32_16x16x32_bf16 v[106:109], v[142:145], v[174:177], v[106:109]
	v_mfma_f32_16x16x32_bf16 v[94:97], v[134:137], v[198:201], v[94:97]
	v_mfma_f32_16x16x32_bf16 v[90:93], v[142:145], v[198:201], v[90:93]
	v_mfma_f32_16x16x32_bf16 v[78:81], v[134:137], v[214:217], v[78:81]
	v_mfma_f32_16x16x32_bf16 v[74:77], v[142:145], v[214:217], v[74:77]
	v_mfma_f32_16x16x32_bf16 v[118:121], v[146:149], v[162:165], v[118:121]
	v_mfma_f32_16x16x32_bf16 v[114:117], v[154:157], v[162:165], v[114:117]
	v_mfma_f32_16x16x32_bf16 v[102:105], v[146:149], v[170:173], v[102:105]
	v_mfma_f32_16x16x32_bf16 v[98:101], v[154:157], v[170:173], v[98:101]
	v_mfma_f32_16x16x32_bf16 v[86:89], v[146:149], v[194:197], v[86:89]
	v_mfma_f32_16x16x32_bf16 v[82:85], v[154:157], v[194:197], v[82:85]
	v_mfma_f32_16x16x32_bf16 v[70:73], v[146:149], v[202:205], v[70:73]
	v_mfma_f32_16x16x32_bf16 v[66:69], v[154:157], v[202:205], v[66:69]
	v_mfma_f32_16x16x32_bf16 v[118:121], v[150:153], v[166:169], v[118:121]
	v_mfma_f32_16x16x32_bf16 v[114:117], v[158:161], v[166:169], v[114:117]
	v_mfma_f32_16x16x32_bf16 v[102:105], v[150:153], v[174:177], v[102:105]
	v_mfma_f32_16x16x32_bf16 v[98:101], v[158:161], v[174:177], v[98:101]
	v_mfma_f32_16x16x32_bf16 v[86:89], v[150:153], v[198:201], v[86:89]
	v_mfma_f32_16x16x32_bf16 v[82:85], v[158:161], v[198:201], v[82:85]
	v_mfma_f32_16x16x32_bf16 v[70:73], v[150:153], v[214:217], v[70:73]
	v_mfma_f32_16x16x32_bf16 v[66:69], v[158:161], v[214:217], v[66:69]
	s_barrier
; #define PG8_STAGE(bufoff, gbase, voff) do { _Pragma("unroll") for (int _i = 0; _i < 2; ++_i) \
;         __builtin_amdgcn_global_load_lds((const unsigned*)((const char*)(gbase) + (voff)[_i]), (PG8_LAS unsigned*)(lds + (bufoff) + ldsw + _i * 8192), 16, 0, 0); } while (0)
; #define PG8_LDA(dst, b, h) do { _Pragma("unroll") for (int m = 0; m < 4; ++m) _Pragma("unroll") for (int k = 0; k < 2; ++k) dst[m][k] = *(const PG8_LAS bf16x8*)(lds + PG8_SA(b, h) + aoff + m * 2048 + k * 1024); } while (0)
; #define PG8_WAIT_V(n) asm volatile("s_waitcnt vmcnt(" #n ")" ::: "memory")
; #define PG8_WAIT_L(n) asm volatile("s_waitcnt lgkmcnt(" #n ")" ::: "memory")
; #define PG8_BAR __builtin_amdgcn_s_barrier()
; #define PG8_SCHED __builtin_amdgcn_sched_barrier(0)
;     __device__ __forceinline__ void run(const f32x4 (&acc)[2][2][4][2], const Unit& un, int wr, int wc, int fr, int fq, PG8_LAS unsigned char* xl) const {
;     ...
;         const float* bs = un.pm < split_pm ? base + (size_t)un.pm * BM * 4096 : base2 + (size_t)(un.pm - split_pm) * BM * 4096;
; template <class Epi, class Sched, bool ALIGN_EPI = false, bool SP2 = false, bool F8 = false>
; __device__ __forceinline__ void gemm_phase(PG8_LAS unsigned char* lds, const Gemm g, const Sched& S, const Epi& E) {
;     ...
;             PG8_LDA(At, 1, 1); PG8_STAGE(PG8_SB(1, 0), b3, voffB); PG8_STAGE(PG8_SB(1, 1), b3 + hB, voffB); PG8_STAGE(PG8_SA(1, 0), a3, voffA);
;             PG8_WAIT_V(8); PG8_WAIT_L(0); PG8_BAR; PG8_MMA(1, 0, At, B0); PG8_MMA(1, 1, At, B1); PG8_BAR; PG8_SCHED;
	s_setprio 0
	s_add_i32 s40, s62, s19
	v_lshl_add_u64 v[218:219], v[218:219], 0, s[22:23]
	s_mov_b32 m0, s40
	ds_read_b128 v[162:165], v212 offset:49152
	ds_read_b128 v[166:169], v212 offset:50176
	ds_read_b128 v[170:173], v212 offset:51200
	ds_read_b128 v[174:177], v212 offset:52224
	ds_read_b128 v[194:197], v212 offset:53248
	ds_read_b128 v[198:201], v212 offset:54272
	ds_read_b128 v[202:205], v212 offset:55296
	ds_read_b128 v[214:217], v212 offset:56320
	global_load_lds_dwordx4 v[218:219], off
	s_add_i32 m0, s40, 0x2000
	s_add_u32 s38, s38, 0x100080
	v_lshl_add_u64 v[218:219], v[220:221], 0, s[22:23]
	s_addc_u32 s39, s39, 0
	s_add_i32 s40, s63, s19
	global_load_lds_dwordx4 v[218:219], off
	v_lshl_add_u64 v[218:219], s[38:39], 0, v[180:181]
	s_mov_b32 m0, s40
	s_nop 0
	global_load_lds_dwordx4 v[218:219], off
	v_lshl_add_u64 v[218:219], s[38:39], 0, v[184:185]
	s_add_i32 m0, s40, 0x2000
	s_nop 0
	global_load_lds_dwordx4 v[218:219], off
	v_lshl_add_u64 v[218:219], v[222:223], 0, s[22:23]
	s_mov_b32 m0, s50
	s_nop 0
	global_load_lds_dwordx4 v[218:219], off
	v_lshl_add_u64 v[218:219], v[224:225], 0, s[22:23]
	s_mov_b32 m0, s51
	s_nop 0
	global_load_lds_dwordx4 v[218:219], off
	s_waitcnt vmcnt(8) lgkmcnt(0)
	s_setprio 1
	s_barrier
	v_mfma_f32_16x16x32_bf16 v[62:65], v[130:133], v[162:165], v[62:65]
	v_mfma_f32_16x16x32_bf16 v[58:61], v[138:141], v[162:165], v[58:61]
	v_mfma_f32_16x16x32_bf16 v[46:49], v[130:133], v[170:173], v[46:49]
	v_mfma_f32_16x16x32_bf16 v[42:45], v[138:141], v[170:173], v[42:45]
	v_mfma_f32_16x16x32_bf16 v[30:33], v[130:133], v[194:197], v[30:33]
	v_mfma_f32_16x16x32_bf16 v[26:29], v[138:141], v[194:197], v[26:29]
	v_mfma_f32_16x16x32_bf16 v[14:17], v[130:133], v[202:205], v[14:17]
	v_mfma_f32_16x16x32_bf16 v[10:13], v[138:141], v[202:205], v[10:13]
	v_mfma_f32_16x16x32_bf16 v[62:65], v[134:137], v[166:169], v[62:65]
	v_mfma_f32_16x16x32_bf16 v[58:61], v[142:145], v[166:169], v[58:61]
	v_mfma_f32_16x16x32_bf16 v[46:49], v[134:137], v[174:177], v[46:49]
	v_mfma_f32_16x16x32_bf16 v[42:45], v[142:145], v[174:177], v[42:45]
	v_mfma_f32_16x16x32_bf16 v[30:33], v[134:137], v[198:201], v[30:33]
	v_mfma_f32_16x16x32_bf16 v[26:29], v[142:145], v[198:201], v[26:29]
	v_mfma_f32_16x16x32_bf16 v[14:17], v[134:137], v[214:217], v[14:17]
	v_mfma_f32_16x16x32_bf16 v[10:13], v[142:145], v[214:217], v[10:13]
	v_mfma_f32_16x16x32_bf16 v[54:57], v[146:149], v[162:165], v[54:57]
	v_mfma_f32_16x16x32_bf16 v[50:53], v[154:157], v[162:165], v[50:53]
	v_mfma_f32_16x16x32_bf16 v[38:41], v[146:149], v[170:173], v[38:41]
	v_mfma_f32_16x16x32_bf16 v[34:37], v[154:157], v[170:173], v[34:37]
	v_mfma_f32_16x16x32_bf16 v[22:25], v[146:149], v[194:197], v[22:25]
	v_mfma_f32_16x16x32_bf16 v[18:21], v[154:157], v[194:197], v[18:21]
	v_mfma_f32_16x16x32_bf16 v[6:9], v[146:149], v[202:205], v[6:9]
	v_mfma_f32_16x16x32_bf16 v[2:5], v[154:157], v[202:205], v[2:5]
	v_mfma_f32_16x16x32_bf16 v[54:57], v[150:153], v[166:169], v[54:57]
	v_mfma_f32_16x16x32_bf16 v[50:53], v[158:161], v[166:169], v[50:53]
	v_mfma_f32_16x16x32_bf16 v[38:41], v[150:153], v[174:177], v[38:41]
	v_mfma_f32_16x16x32_bf16 v[34:37], v[158:161], v[174:177], v[34:37]
	v_mfma_f32_16x16x32_bf16 v[22:25], v[150:153], v[198:201], v[22:25]
	v_mfma_f32_16x16x32_bf16 v[18:21], v[158:161], v[198:201], v[18:21]
	v_mfma_f32_16x16x32_bf16 v[6:9], v[150:153], v[214:217], v[6:9]
	v_mfma_f32_16x16x32_bf16 v[2:5], v[158:161], v[214:217], v[2:5]
	s_barrier
	s_setprio 0
	s_add_i32 s61, s61, 2
	s_add_u32 s35, s35, 0x100
	s_addc_u32 s60, s60, 0
	s_add_u32 s36, s36, 0x100
	s_addc_u32 s37, s37, 0
	s_cmp_gt_u32 s61, 61
	s_cbranch_scc0 .LBB0_689
	v_mov_b32_e32 v214, v206
	s_cmp_gt_i32 s16, 63
	s_mov_b64 s[38:39], -1
	s_cbranch_scc0 .LBB0_692
	s_sub_i32 s20, s16, 64
	s_lshl_b64 s[36:37], s[20:21], 22
	s_add_u32 s36, s14, s36
	s_addc_u32 s37, s15, s37
	s_mov_b32 s17, s21
	s_mov_b64 s[38:39], 0

; #define PG8_STAGE(bufoff, gbase, voff) do { _Pragma("unroll") for (int _i = 0; _i < 2; ++_i) \
;         __builtin_amdgcn_global_load_lds((const unsigned*)((const char*)(gbase) + (voff)[_i]), (PG8_LAS unsigned*)(lds + (bufoff) + ldsw + _i * 8192), 16, 0, 0); } while (0)
; #define PG8_LDA(dst, b, h) do { _Pragma("unroll") for (int m = 0; m < 4; ++m) _Pragma("unroll") for (int k = 0; k < 2; ++k) dst[m][k] = *(const PG8_LAS bf16x8*)(lds + PG8_SA(b, h) + aoff + m * 2048 + k * 1024); } while (0)
; #define PG8_LDB(dst, b, h) do { _Pragma("unroll") for (int n = 0; n < 2; ++n) _Pragma("unroll") for (int k = 0; k < 2; ++k) dst[n][k] = *(const PG8_LAS bf16x8*)(lds + PG8_SB(b, h) + boff + n * 2048 + k * 1024); } while (0)
; #define PG8_WAIT_V(n) asm volatile("s_waitcnt vmcnt(" #n ")" ::: "memory")
; #define PG8_WAIT_L(n) asm volatile("s_waitcnt lgkmcnt(" #n ")" ::: "memory")
; #define PG8_BAR __builtin_amdgcn_s_barrier()
; #define PG8_SCHED __builtin_amdgcn_sched_barrier(0)
; template <class Epi, class Sched, bool ALIGN_EPI = false, bool SP2 = false, bool F8 = false>
; __device__ __forceinline__ void gemm_phase(PG8_LAS unsigned char* lds, const Gemm g, const Sched& S, const Epi& E) {
;     ...
;             PG8_LDB(B0, 0, 0); PG8_LDB(B1, 0, 1); PG8_SCHED; PG8_LDA(At, 0, 0); PG8_STAGE(PG8_SA(1, 1), a1 + hA, voffA);
;             PG8_WAIT_V(8); PG8_WAIT_L(0); PG8_BAR; PG8_MMA(0, 0, At, B0); PG8_MMA(0, 1, At, B1); PG8_BAR; PG8_SCHED;
;             PG8_LDA(At, 0, 1); PG8_STAGE(PG8_SB(0, 0), b2, voffB); PG8_STAGE(PG8_SB(0, 1), b2 + hB, voffB); PG8_STAGE(PG8_SA(0, 0), a2, voffA);
;             PG8_WAIT_V(8); PG8_WAIT_L(0); PG8_BAR; PG8_MMA(1, 0, At, B0); PG8_MMA(1, 1, At, B1); PG8_BAR; PG8_SCHED;
.LBB0_770:
	ds_read_b128 v[130:133], v241
	ds_read_b128 v[134:137], v241 offset:1024
	ds_read_b128 v[138:141], v241 offset:2048
	ds_read_b128 v[142:145], v241 offset:3072
	ds_read_b128 v[146:149], v242
	ds_read_b128 v[150:153], v242 offset:1024
	ds_read_b128 v[154:157], v242 offset:2048
	ds_read_b128 v[158:161], v242 offset:3072
	s_add_u32 s14, s12, 0xfff00080
	s_addc_u32 s15, s13, -1
	s_cmp_eq_u32 s80, 60
	s_cselect_b32 s17, s11, s15
	s_cselect_b32 s16, s63, s14
	s_cselect_b32 s15, s61, s79
	s_cselect_b32 s14, s77, s78
	v_lshl_add_u64 v[208:209], s[12:13], 0, v[188:189]
	s_add_i32 m0, s7, 0xc000
	ds_read_b128 v[162:165], v243
	ds_read_b128 v[166:169], v243 offset:1024
	ds_read_b128 v[170:173], v243 offset:2048
	ds_read_b128 v[174:177], v243 offset:3072
	ds_read_b128 v[192:195], v243 offset:4096
	ds_read_b128 v[196:199], v243 offset:5120
	ds_read_b128 v[200:203], v243 offset:6144
	ds_read_b128 v[204:207], v243 offset:7168
	global_load_lds_dwordx4 v[208:209], off
	v_lshl_add_u64 v[208:209], s[12:13], 0, v[186:187]
	s_add_i32 m0, s7, 0xe000
	s_nop 0
	global_load_lds_dwordx4 v[208:209], off
	s_waitcnt vmcnt(8) lgkmcnt(0)
	s_setprio 1
	s_barrier
	v_mfma_f32_16x16x32_bf16 v[126:129], v[130:133], v[162:165], v[126:129]
	v_mfma_f32_16x16x32_bf16 v[90:93], v[138:141], v[162:165], v[90:93]
	v_mfma_f32_16x16x32_bf16 v[110:113], v[130:133], v[170:173], v[110:113]
	v_mfma_f32_16x16x32_bf16 v[86:89], v[138:141], v[170:173], v[86:89]
	v_mfma_f32_16x16x32_bf16 v[106:109], v[130:133], v[192:195], v[106:109]
	v_mfma_f32_16x16x32_bf16 v[82:85], v[138:141], v[192:195], v[82:85]
	v_mfma_f32_16x16x32_bf16 v[118:121], v[130:133], v[200:203], v[118:121]
	v_mfma_f32_16x16x32_bf16 v[122:125], v[138:141], v[200:203], v[122:125]
	v_mfma_f32_16x16x32_bf16 v[126:129], v[134:137], v[166:169], v[126:129]
	v_mfma_f32_16x16x32_bf16 v[90:93], v[142:145], v[166:169], v[90:93]
	v_mfma_f32_16x16x32_bf16 v[110:113], v[134:137], v[174:177], v[110:113]
	v_mfma_f32_16x16x32_bf16 v[86:89], v[142:145], v[174:177], v[86:89]
	v_mfma_f32_16x16x32_bf16 v[106:109], v[134:137], v[196:199], v[106:109]
	v_mfma_f32_16x16x32_bf16 v[82:85], v[142:145], v[196:199], v[82:85]
	v_mfma_f32_16x16x32_bf16 v[118:121], v[134:137], v[204:207], v[118:121]
	v_mfma_f32_16x16x32_bf16 v[122:125], v[142:145], v[204:207], v[122:125]
	v_mfma_f32_16x16x32_bf16 v[94:97], v[146:149], v[162:165], v[94:97]
	v_mfma_f32_16x16x32_bf16 v[66:69], v[154:157], v[162:165], v[66:69]
	v_mfma_f32_16x16x32_bf16 v[102:105], v[146:149], v[170:173], v[102:105]
	v_mfma_f32_16x16x32_bf16 v[78:81], v[154:157], v[170:173], v[78:81]
	v_mfma_f32_16x16x32_bf16 v[98:101], v[146:149], v[192:195], v[98:101]
	v_mfma_f32_16x16x32_bf16 v[74:77], v[154:157], v[192:195], v[74:77]
	v_mfma_f32_16x16x32_bf16 v[70:73], v[146:149], v[200:203], v[70:73]
	v_mfma_f32_16x16x32_bf16 v[58:61], v[154:157], v[200:203], v[58:61]
	v_mfma_f32_16x16x32_bf16 v[94:97], v[150:153], v[166:169], v[94:97]
	v_mfma_f32_16x16x32_bf16 v[66:69], v[158:161], v[166:169], v[66:69]
	v_mfma_f32_16x16x32_bf16 v[102:105], v[150:153], v[174:177], v[102:105]
	v_mfma_f32_16x16x32_bf16 v[78:81], v[158:161], v[174:177], v[78:81]
	v_mfma_f32_16x16x32_bf16 v[98:101], v[150:153], v[196:199], v[98:101]
	v_mfma_f32_16x16x32_bf16 v[74:77], v[158:161], v[196:199], v[74:77]
	v_mfma_f32_16x16x32_bf16 v[70:73], v[150:153], v[204:207], v[70:73]
	v_mfma_f32_16x16x32_bf16 v[58:61], v[158:161], v[204:207], v[58:61]
	s_barrier
	s_setprio 0
	s_add_i32 s81, s97, s6
	v_lshl_add_u64 v[208:209], s[14:15], 0, v[180:181]
	s_mov_b32 m0, s81
	ds_read_b128 v[162:165], v243 offset:16384
	ds_read_b128 v[166:169], v243 offset:17408
	ds_read_b128 v[170:173], v243 offset:18432
	ds_read_b128 v[174:177], v243 offset:19456
	ds_read_b128 v[192:195], v243 offset:20480
	ds_read_b128 v[196:199], v243 offset:21504
	ds_read_b128 v[200:203], v243 offset:22528
	ds_read_b128 v[204:207], v243 offset:23552
	global_load_lds_dwordx4 v[208:209], off
	s_add_i32 m0, s81, 0x2000
	s_add_u32 vcc_lo, s14, 0x100000
	v_lshl_add_u64 v[210:211], s[14:15], 0, v[184:185]
	s_addc_u32 vcc_hi, s15, 0
	s_add_i32 s81, s86, s6
	global_load_lds_dwordx4 v[210:211], off
	v_lshl_add_u64 v[212:213], vcc, 0, v[180:181]
	s_mov_b32 m0, s81
	v_lshl_add_u64 v[214:215], s[16:17], 0, v[182:183]
	global_load_lds_dwordx4 v[212:213], off
	v_lshl_add_u64 v[212:213], vcc, 0, v[184:185]
	s_add_i32 m0, s81, 0x2000
	s_nop 0
	global_load_lds_dwordx4 v[212:213], off
	v_lshl_add_u64 v[212:213], s[16:17], 0, v[178:179]
	s_mov_b32 m0, s7
	s_nop 0
	global_load_lds_dwordx4 v[212:213], off
	s_mov_b32 m0, s18
	s_nop 0
	global_load_lds_dwordx4 v[214:215], off
	s_waitcnt vmcnt(8) lgkmcnt(0)
	s_setprio 1
	s_barrier
; #define PG8_STAGE(bufoff, gbase, voff) do { _Pragma("unroll") for (int _i = 0; _i < 2; ++_i) \
;         __builtin_amdgcn_global_load_lds((const unsigned*)((const char*)(gbase) + (voff)[_i]), (PG8_LAS unsigned*)(lds + (bufoff) + ldsw + _i * 8192), 16, 0, 0); } while (0)
; #define PG8_LDA(dst, b, h) do { _Pragma("unroll") for (int m = 0; m < 4; ++m) _Pragma("unroll") for (int k = 0; k < 2; ++k) dst[m][k] = *(const PG8_LAS bf16x8*)(lds + PG8_SA(b, h) + aoff + m * 2048 + k * 1024); } while (0)
; #define PG8_LDB(dst, b, h) do { _Pragma("unroll") for (int n = 0; n < 2; ++n) _Pragma("unroll") for (int k = 0; k < 2; ++k) dst[n][k] = *(const PG8_LAS bf16x8*)(lds + PG8_SB(b, h) + boff + n * 2048 + k * 1024); } while (0)
; #define PG8_WAIT_V(n) asm volatile("s_waitcnt vmcnt(" #n ")" ::: "memory")
; #define PG8_WAIT_L(n) asm volatile("s_waitcnt lgkmcnt(" #n ")" ::: "memory")
; #define PG8_BAR __builtin_amdgcn_s_barrier()
; #define PG8_SCHED __builtin_amdgcn_sched_barrier(0)
; template <class Epi, class Sched, bool ALIGN_EPI = false, bool SP2 = false, bool F8 = false>
; __device__ __forceinline__ void gemm_phase(PG8_LAS unsigned char* lds, const Gemm g, const Sched& S, const Epi& E) {
;     ...
;             PG8_WAIT_V(8); PG8_WAIT_L(0); PG8_BAR; PG8_MMA(1, 0, At, B0); PG8_MMA(1, 1, At, B1); PG8_BAR; PG8_SCHED;
;             PG8_LDB(B0, 1, 0); PG8_LDB(B1, 1, 1); PG8_SCHED; PG8_LDA(At, 1, 0); PG8_STAGE(PG8_SA(0, 1), a2 + hA, voffA);
;             PG8_WAIT_V(8); PG8_WAIT_L(0); PG8_BAR; PG8_MMA(0, 0, At, B0); PG8_MMA(0, 1, At, B1); PG8_BAR; PG8_SCHED;
	v_mfma_f32_16x16x32_bf16 v[62:65], v[130:133], v[162:165], v[62:65]
	v_mfma_f32_16x16x32_bf16 v[38:41], v[138:141], v[162:165], v[38:41]
	v_mfma_f32_16x16x32_bf16 v[42:45], v[130:133], v[170:173], v[42:45]
	v_mfma_f32_16x16x32_bf16 v[14:17], v[138:141], v[170:173], v[14:17]
	v_mfma_f32_16x16x32_bf16 v[34:37], v[130:133], v[192:195], v[34:37]
	v_mfma_f32_16x16x32_bf16 v[10:13], v[138:141], v[192:195], v[10:13]
	v_mfma_f32_16x16x32_bf16 v[50:53], v[130:133], v[200:203], v[50:53]
	v_mfma_f32_16x16x32_bf16 v[114:117], v[138:141], v[200:203], v[114:117]
	v_mfma_f32_16x16x32_bf16 v[62:65], v[134:137], v[166:169], v[62:65]
	v_mfma_f32_16x16x32_bf16 v[38:41], v[142:145], v[166:169], v[38:41]
	v_mfma_f32_16x16x32_bf16 v[42:45], v[134:137], v[174:177], v[42:45]
	v_mfma_f32_16x16x32_bf16 v[14:17], v[142:145], v[174:177], v[14:17]
	v_mfma_f32_16x16x32_bf16 v[34:37], v[134:137], v[196:199], v[34:37]
	v_mfma_f32_16x16x32_bf16 v[10:13], v[142:145], v[196:199], v[10:13]
	v_mfma_f32_16x16x32_bf16 v[50:53], v[134:137], v[204:207], v[50:53]
	v_mfma_f32_16x16x32_bf16 v[114:117], v[142:145], v[204:207], v[114:117]
	v_mfma_f32_16x16x32_bf16 v[46:49], v[146:149], v[162:165], v[46:49]
	v_mfma_f32_16x16x32_bf16 v[22:25], v[154:157], v[162:165], v[22:25]
	v_mfma_f32_16x16x32_bf16 v[30:33], v[146:149], v[170:173], v[30:33]
	v_mfma_f32_16x16x32_bf16 v[6:9], v[154:157], v[170:173], v[6:9]
	v_mfma_f32_16x16x32_bf16 v[26:29], v[146:149], v[192:195], v[26:29]
	v_mfma_f32_16x16x32_bf16 v[2:5], v[154:157], v[192:195], v[2:5]
	v_mfma_f32_16x16x32_bf16 v[54:57], v[146:149], v[200:203], v[54:57]
	v_mfma_f32_16x16x32_bf16 v[18:21], v[154:157], v[200:203], v[18:21]
	v_mfma_f32_16x16x32_bf16 v[46:49], v[150:153], v[166:169], v[46:49]
	v_mfma_f32_16x16x32_bf16 v[22:25], v[158:161], v[166:169], v[22:25]
	v_mfma_f32_16x16x32_bf16 v[30:33], v[150:153], v[174:177], v[30:33]
	v_mfma_f32_16x16x32_bf16 v[6:9], v[158:161], v[174:177], v[6:9]
	v_mfma_f32_16x16x32_bf16 v[26:29], v[150:153], v[196:199], v[26:29]
	v_mfma_f32_16x16x32_bf16 v[2:5], v[158:161], v[196:199], v[2:5]
	v_mfma_f32_16x16x32_bf16 v[54:57], v[150:153], v[204:207], v[54:57]
	v_mfma_f32_16x16x32_bf16 v[18:21], v[158:161], v[204:207], v[18:21]
	s_barrier
	s_setprio 0
	s_add_i32 s81, 0, 0x18000
	s_add_i32 vcc_lo, 0, 0x1c000
	v_add_u32_e32 v142, s81, v240
	v_add_u32_e32 v158, vcc_lo, v240
	ds_read_b128 v[130:133], v142
	ds_read_b128 v[134:137], v142 offset:1024
	ds_read_b128 v[138:141], v142 offset:2048
	ds_read_b128 v[142:145], v142 offset:3072
	ds_read_b128 v[146:149], v158
	ds_read_b128 v[150:153], v158 offset:1024
	ds_read_b128 v[154:157], v158 offset:2048
	ds_read_b128 v[158:161], v158 offset:3072
	s_add_u32 s16, s16, 0x100000
	s_addc_u32 s17, s17, 0
	s_mov_b32 m0, s19
	v_lshl_add_u64 v[216:217], s[16:17], 0, v[178:179]
	ds_read_b128 v[162:165], v243 offset:32768
	ds_read_b128 v[166:169], v243 offset:33792
	ds_read_b128 v[170:173], v243 offset:34816
	ds_read_b128 v[174:177], v243 offset:35840
	ds_read_b128 v[192:195], v243 offset:36864
	ds_read_b128 v[196:199], v243 offset:37888
	ds_read_b128 v[200:203], v243 offset:38912
	ds_read_b128 v[204:207], v243 offset:39936
	global_load_lds_dwordx4 v[216:217], off
	v_lshl_add_u64 v[216:217], s[16:17], 0, v[182:183]
	s_mov_b32 m0, s33
	s_nop 0
	global_load_lds_dwordx4 v[216:217], off
	s_waitcnt vmcnt(8) lgkmcnt(0)
	s_setprio 1
	s_barrier
	v_mfma_f32_16x16x32_bf16 v[126:129], v[130:133], v[162:165], v[126:129]
	v_mfma_f32_16x16x32_bf16 v[90:93], v[138:141], v[162:165], v[90:93]
	v_mfma_f32_16x16x32_bf16 v[110:113], v[130:133], v[170:173], v[110:113]
	v_mfma_f32_16x16x32_bf16 v[86:89], v[138:141], v[170:173], v[86:89]
	v_mfma_f32_16x16x32_bf16 v[106:109], v[130:133], v[192:195], v[106:109]
	v_mfma_f32_16x16x32_bf16 v[82:85], v[138:141], v[192:195], v[82:85]
	v_mfma_f32_16x16x32_bf16 v[118:121], v[130:133], v[200:203], v[118:121]
	v_mfma_f32_16x16x32_bf16 v[122:125], v[138:141], v[200:203], v[122:125]
	v_mfma_f32_16x16x32_bf16 v[126:129], v[134:137], v[166:169], v[126:129]
	v_mfma_f32_16x16x32_bf16 v[90:93], v[142:145], v[166:169], v[90:93]
	v_mfma_f32_16x16x32_bf16 v[110:113], v[134:137], v[174:177], v[110:113]
	v_mfma_f32_16x16x32_bf16 v[86:89], v[142:145], v[174:177], v[86:89]
	v_mfma_f32_16x16x32_bf16 v[106:109], v[134:137], v[196:199], v[106:109]
	v_mfma_f32_16x16x32_bf16 v[82:85], v[142:145], v[196:199], v[82:85]
	v_mfma_f32_16x16x32_bf16 v[118:121], v[134:137], v[204:207], v[118:121]
	v_mfma_f32_16x16x32_bf16 v[122:125], v[142:145], v[204:207], v[122:125]
	v_mfma_f32_16x16x32_bf16 v[94:97], v[146:149], v[162:165], v[94:97]
	v_mfma_f32_16x16x32_bf16 v[66:69], v[154:157], v[162:165], v[66:69]
	v_mfma_f32_16x16x32_bf16 v[102:105], v[146:149], v[170:173], v[102:105]
	v_mfma_f32_16x16x32_bf16 v[78:81], v[154:157], v[170:173], v[78:81]
	v_mfma_f32_16x16x32_bf16 v[98:101], v[146:149], v[192:195], v[98:101]
	v_mfma_f32_16x16x32_bf16 v[74:77], v[154:157], v[192:195], v[74:77]
	v_mfma_f32_16x16x32_bf16 v[70:73], v[146:149], v[200:203], v[70:73]
	v_mfma_f32_16x16x32_bf16 v[58:61], v[154:157], v[200:203], v[58:61]
	v_mfma_f32_16x16x32_bf16 v[94:97], v[150:153], v[166:169], v[94:97]
	v_mfma_f32_16x16x32_bf16 v[66:69], v[158:161], v[166:169], v[66:69]
	v_mfma_f32_16x16x32_bf16 v[102:105], v[150:153], v[174:177], v[102:105]
	v_mfma_f32_16x16x32_bf16 v[78:81], v[158:161], v[174:177], v[78:81]
	v_mfma_f32_16x16x32_bf16 v[98:101], v[150:153], v[196:199], v[98:101]
	v_mfma_f32_16x16x32_bf16 v[74:77], v[158:161], v[196:199], v[74:77]
	v_mfma_f32_16x16x32_bf16 v[70:73], v[150:153], v[204:207], v[70:73]
	v_mfma_f32_16x16x32_bf16 v[58:61], v[158:161], v[204:207], v[58:61]
	s_barrier
; #define PG8_STAGE(bufoff, gbase, voff) do { _Pragma("unroll") for (int _i = 0; _i < 2; ++_i) \
;         __builtin_amdgcn_global_load_lds((const unsigned*)((const char*)(gbase) + (voff)[_i]), (PG8_LAS unsigned*)(lds + (bufoff) + ldsw + _i * 8192), 16, 0, 0); } while (0)
; #define PG8_LDA(dst, b, h) do { _Pragma("unroll") for (int m = 0; m < 4; ++m) _Pragma("unroll") for (int k = 0; k < 2; ++k) dst[m][k] = *(const PG8_LAS bf16x8*)(lds + PG8_SA(b, h) + aoff + m * 2048 + k * 1024); } while (0)
; #define PG8_WAIT_V(n) asm volatile("s_waitcnt vmcnt(" #n ")" ::: "memory")
; #define PG8_WAIT_L(n) asm volatile("s_waitcnt lgkmcnt(" #n ")" ::: "memory")
; #define PG8_BAR __builtin_amdgcn_s_barrier()
; #define PG8_SCHED __builtin_amdgcn_sched_barrier(0)
; template <class Epi, class Sched, bool ALIGN_EPI = false, bool SP2 = false, bool F8 = false>
; __device__ __forceinline__ void gemm_phase(PG8_LAS unsigned char* lds, const Gemm g, const Sched& S, const Epi& E) {
;     ...
;             PG8_LDA(At, 1, 1); PG8_STAGE(PG8_SB(1, 0), b3, voffB); PG8_STAGE(PG8_SB(1, 1), b3 + hB, voffB); PG8_STAGE(PG8_SA(1, 0), a3, voffA);
;             PG8_WAIT_V(8); PG8_WAIT_L(0); PG8_BAR; PG8_MMA(1, 0, At, B0); PG8_MMA(1, 1, At, B1); PG8_BAR; PG8_SCHED;
;     ...
;         if constexpr (ALIGN_EPI) { if (wr == 0) PG8_BAR; }
	s_setprio 0
	s_add_i32 s16, s81, s6
	v_lshl_add_u64 v[208:209], v[208:209], 0, s[36:37]
	s_mov_b32 m0, s16
	ds_read_b128 v[162:165], v243 offset:49152
	ds_read_b128 v[166:169], v243 offset:50176
	ds_read_b128 v[170:173], v243 offset:51200
	ds_read_b128 v[174:177], v243 offset:52224
	ds_read_b128 v[192:195], v243 offset:53248
	ds_read_b128 v[196:199], v243 offset:54272
	ds_read_b128 v[200:203], v243 offset:55296
	ds_read_b128 v[204:207], v243 offset:56320
	global_load_lds_dwordx4 v[208:209], off
	s_add_i32 m0, s16, 0x2000
	s_add_u32 s14, s14, 0x100080
	v_lshl_add_u64 v[208:209], v[210:211], 0, s[36:37]
	s_addc_u32 s15, s15, 0
	s_add_i32 s16, vcc_lo, s6
	global_load_lds_dwordx4 v[208:209], off
	v_lshl_add_u64 v[208:209], s[14:15], 0, v[180:181]
	s_mov_b32 m0, s16
	s_nop 0
	global_load_lds_dwordx4 v[208:209], off
	v_lshl_add_u64 v[208:209], s[14:15], 0, v[184:185]
	s_add_i32 m0, s16, 0x2000
	s_nop 0
	global_load_lds_dwordx4 v[208:209], off
	v_lshl_add_u64 v[208:209], v[212:213], 0, s[36:37]
	s_mov_b32 m0, s71
	s_nop 0
	global_load_lds_dwordx4 v[208:209], off
	v_lshl_add_u64 v[208:209], v[214:215], 0, s[36:37]
	s_mov_b32 m0, s74
	s_nop 0
	global_load_lds_dwordx4 v[208:209], off
	s_waitcnt vmcnt(8) lgkmcnt(0)
	s_setprio 1
	s_barrier
	v_mfma_f32_16x16x32_bf16 v[62:65], v[130:133], v[162:165], v[62:65]
	v_mfma_f32_16x16x32_bf16 v[38:41], v[138:141], v[162:165], v[38:41]
	v_mfma_f32_16x16x32_bf16 v[42:45], v[130:133], v[170:173], v[42:45]
	v_mfma_f32_16x16x32_bf16 v[14:17], v[138:141], v[170:173], v[14:17]
	v_mfma_f32_16x16x32_bf16 v[34:37], v[130:133], v[192:195], v[34:37]
	v_mfma_f32_16x16x32_bf16 v[10:13], v[138:141], v[192:195], v[10:13]
	v_mfma_f32_16x16x32_bf16 v[50:53], v[130:133], v[200:203], v[50:53]
	v_mfma_f32_16x16x32_bf16 v[114:117], v[138:141], v[200:203], v[114:117]
	v_mfma_f32_16x16x32_bf16 v[62:65], v[134:137], v[166:169], v[62:65]
	v_mfma_f32_16x16x32_bf16 v[38:41], v[142:145], v[166:169], v[38:41]
	v_mfma_f32_16x16x32_bf16 v[42:45], v[134:137], v[174:177], v[42:45]
	v_mfma_f32_16x16x32_bf16 v[14:17], v[142:145], v[174:177], v[14:17]
	v_mfma_f32_16x16x32_bf16 v[34:37], v[134:137], v[196:199], v[34:37]
	v_mfma_f32_16x16x32_bf16 v[10:13], v[142:145], v[196:199], v[10:13]
	v_mfma_f32_16x16x32_bf16 v[50:53], v[134:137], v[204:207], v[50:53]
	v_mfma_f32_16x16x32_bf16 v[114:117], v[142:145], v[204:207], v[114:117]
	v_mfma_f32_16x16x32_bf16 v[46:49], v[146:149], v[162:165], v[46:49]
	v_mfma_f32_16x16x32_bf16 v[22:25], v[154:157], v[162:165], v[22:25]
	v_mfma_f32_16x16x32_bf16 v[30:33], v[146:149], v[170:173], v[30:33]
	v_mfma_f32_16x16x32_bf16 v[6:9], v[154:157], v[170:173], v[6:9]
	v_mfma_f32_16x16x32_bf16 v[26:29], v[146:149], v[192:195], v[26:29]
	v_mfma_f32_16x16x32_bf16 v[2:5], v[154:157], v[192:195], v[2:5]
	v_mfma_f32_16x16x32_bf16 v[54:57], v[146:149], v[200:203], v[54:57]
	v_mfma_f32_16x16x32_bf16 v[18:21], v[154:157], v[200:203], v[18:21]
	v_mfma_f32_16x16x32_bf16 v[46:49], v[150:153], v[166:169], v[46:49]
	v_mfma_f32_16x16x32_bf16 v[22:25], v[158:161], v[166:169], v[22:25]
	v_mfma_f32_16x16x32_bf16 v[30:33], v[150:153], v[174:177], v[30:33]
	v_mfma_f32_16x16x32_bf16 v[6:9], v[158:161], v[174:177], v[6:9]
	v_mfma_f32_16x16x32_bf16 v[26:29], v[150:153], v[196:199], v[26:29]
	v_mfma_f32_16x16x32_bf16 v[2:5], v[158:161], v[196:199], v[2:5]
	v_mfma_f32_16x16x32_bf16 v[54:57], v[150:153], v[204:207], v[54:57]
	v_mfma_f32_16x16x32_bf16 v[18:21], v[158:161], v[204:207], v[18:21]
	s_barrier
	s_setprio 0
	s_add_i32 s80, s80, 2
	s_add_u32 s78, s78, 0x100
	s_addc_u32 s79, s79, 0
	s_add_u32 s12, s12, 0x100
	s_addc_u32 s13, s13, 0
	s_cmp_gt_u32 s80, 61
	s_cbranch_scc0 .LBB0_770
	s_and_b64 vcc, exec, s[38:39]
	s_cbranch_vccz .LBB0_773
	s_barrier

; #define PG8_STAGE(bufoff, gbase, voff) do { _Pragma("unroll") for (int _i = 0; _i < 2; ++_i) \
;         __builtin_amdgcn_global_load_lds((const unsigned*)((const char*)(gbase) + (voff)[_i]), (PG8_LAS unsigned*)(lds + (bufoff) + ldsw + _i * 8192), 16, 0, 0); } while (0)
; #define PG8_LDA(dst, b, h) do { _Pragma("unroll") for (int m = 0; m < 4; ++m) _Pragma("unroll") for (int k = 0; k < 2; ++k) dst[m][k] = *(const PG8_LAS bf16x8*)(lds + PG8_SA(b, h) + aoff + m * 2048 + k * 1024); } while (0)
; #define PG8_LDB(dst, b, h) do { _Pragma("unroll") for (int n = 0; n < 2; ++n) _Pragma("unroll") for (int k = 0; k < 2; ++k) dst[n][k] = *(const PG8_LAS bf16x8*)(lds + PG8_SB(b, h) + boff + n * 2048 + k * 1024); } while (0)
; #define PG8_WAIT_V(n) asm volatile("s_waitcnt vmcnt(" #n ")" ::: "memory")
; #define PG8_WAIT_L(n) asm volatile("s_waitcnt lgkmcnt(" #n ")" ::: "memory")
; #define PG8_BAR __builtin_amdgcn_s_barrier()
; #define PG8_SCHED __builtin_amdgcn_sched_barrier(0)
; template <class Epi, class Sched, bool ALIGN_EPI = false, bool SP2 = false, bool F8 = false>
; __device__ __forceinline__ void gemm_phase(PG8_LAS unsigned char* lds, const Gemm g, const Sched& S, const Epi& E) {
;     ...
;             PG8_LDB(B0, 0, 0); PG8_LDB(B1, 0, 1); PG8_SCHED; PG8_LDA(At, 0, 0); PG8_STAGE(PG8_SA(1, 1), a1 + hA, voffA);
;             PG8_WAIT_V(8); PG8_WAIT_L(0); PG8_BAR; PG8_MMA(0, 0, At, B0); PG8_MMA(0, 1, At, B1); PG8_BAR; PG8_SCHED;
;             PG8_LDA(At, 0, 1); PG8_STAGE(PG8_SB(0, 0), b2, voffB); PG8_STAGE(PG8_SB(0, 1), b2 + hB, voffB); PG8_STAGE(PG8_SA(0, 0), a2, voffA);
;             PG8_WAIT_V(8); PG8_WAIT_L(0); PG8_BAR; PG8_MMA(1, 0, At, B0); PG8_MMA(1, 1, At, B1); PG8_BAR; PG8_SCHED;
.LBB0_825:
	ds_read_b128 v[130:133], v241
	ds_read_b128 v[134:137], v241 offset:1024
	ds_read_b128 v[138:141], v241 offset:2048
	ds_read_b128 v[142:145], v241 offset:3072
	ds_read_b128 v[146:149], v242
	ds_read_b128 v[150:153], v242 offset:1024
	ds_read_b128 v[154:157], v242 offset:2048
	ds_read_b128 v[158:161], v242 offset:3072
	s_add_u32 s14, s12, 0xfff00080
	s_addc_u32 s15, s13, -1
	s_cmp_eq_u32 s82, 60
	s_cselect_b32 s17, s11, s15
	s_cselect_b32 s16, s63, s14
	s_cselect_b32 s15, s65, s81
	s_cselect_b32 s14, s79, s80
	v_lshl_add_u64 v[208:209], s[12:13], 0, v[188:189]
	s_add_i32 m0, s7, 0xc000
	ds_read_b128 v[162:165], v243
	ds_read_b128 v[166:169], v243 offset:1024
	ds_read_b128 v[170:173], v243 offset:2048
	ds_read_b128 v[174:177], v243 offset:3072
	ds_read_b128 v[192:195], v243 offset:4096
	ds_read_b128 v[196:199], v243 offset:5120
	ds_read_b128 v[200:203], v243 offset:6144
	ds_read_b128 v[204:207], v243 offset:7168
	global_load_lds_dwordx4 v[208:209], off
	v_lshl_add_u64 v[208:209], s[12:13], 0, v[186:187]
	s_add_i32 m0, s7, 0xe000
	s_nop 0
	global_load_lds_dwordx4 v[208:209], off
	s_waitcnt vmcnt(8) lgkmcnt(0)
	s_setprio 1
	s_barrier
	v_mfma_f32_16x16x32_bf16 v[126:129], v[130:133], v[162:165], v[126:129]
	v_mfma_f32_16x16x32_bf16 v[90:93], v[138:141], v[162:165], v[90:93]
	v_mfma_f32_16x16x32_bf16 v[110:113], v[130:133], v[170:173], v[110:113]
	v_mfma_f32_16x16x32_bf16 v[86:89], v[138:141], v[170:173], v[86:89]
	v_mfma_f32_16x16x32_bf16 v[106:109], v[130:133], v[192:195], v[106:109]
	v_mfma_f32_16x16x32_bf16 v[82:85], v[138:141], v[192:195], v[82:85]
	v_mfma_f32_16x16x32_bf16 v[118:121], v[130:133], v[200:203], v[118:121]
	v_mfma_f32_16x16x32_bf16 v[122:125], v[138:141], v[200:203], v[122:125]
	v_mfma_f32_16x16x32_bf16 v[126:129], v[134:137], v[166:169], v[126:129]
	v_mfma_f32_16x16x32_bf16 v[90:93], v[142:145], v[166:169], v[90:93]
	v_mfma_f32_16x16x32_bf16 v[110:113], v[134:137], v[174:177], v[110:113]
	v_mfma_f32_16x16x32_bf16 v[86:89], v[142:145], v[174:177], v[86:89]
	v_mfma_f32_16x16x32_bf16 v[106:109], v[134:137], v[196:199], v[106:109]
	v_mfma_f32_16x16x32_bf16 v[82:85], v[142:145], v[196:199], v[82:85]
	v_mfma_f32_16x16x32_bf16 v[118:121], v[134:137], v[204:207], v[118:121]
	v_mfma_f32_16x16x32_bf16 v[122:125], v[142:145], v[204:207], v[122:125]
	v_mfma_f32_16x16x32_bf16 v[94:97], v[146:149], v[162:165], v[94:97]
	v_mfma_f32_16x16x32_bf16 v[66:69], v[154:157], v[162:165], v[66:69]
	v_mfma_f32_16x16x32_bf16 v[102:105], v[146:149], v[170:173], v[102:105]
	v_mfma_f32_16x16x32_bf16 v[78:81], v[154:157], v[170:173], v[78:81]
	v_mfma_f32_16x16x32_bf16 v[98:101], v[146:149], v[192:195], v[98:101]
	v_mfma_f32_16x16x32_bf16 v[74:77], v[154:157], v[192:195], v[74:77]
	v_mfma_f32_16x16x32_bf16 v[70:73], v[146:149], v[200:203], v[70:73]
	v_mfma_f32_16x16x32_bf16 v[58:61], v[154:157], v[200:203], v[58:61]
	v_mfma_f32_16x16x32_bf16 v[94:97], v[150:153], v[166:169], v[94:97]
	v_mfma_f32_16x16x32_bf16 v[66:69], v[158:161], v[166:169], v[66:69]
	v_mfma_f32_16x16x32_bf16 v[102:105], v[150:153], v[174:177], v[102:105]
	v_mfma_f32_16x16x32_bf16 v[78:81], v[158:161], v[174:177], v[78:81]
	v_mfma_f32_16x16x32_bf16 v[98:101], v[150:153], v[196:199], v[98:101]
	v_mfma_f32_16x16x32_bf16 v[74:77], v[158:161], v[196:199], v[74:77]
	v_mfma_f32_16x16x32_bf16 v[70:73], v[150:153], v[204:207], v[70:73]
	v_mfma_f32_16x16x32_bf16 v[58:61], v[158:161], v[204:207], v[58:61]
	s_barrier
	s_setprio 0
	s_add_i32 s83, s30, s5
	v_lshl_add_u64 v[208:209], s[14:15], 0, v[180:181]
	s_mov_b32 m0, s83
	ds_read_b128 v[162:165], v243 offset:16384
	ds_read_b128 v[166:169], v243 offset:17408
	ds_read_b128 v[170:173], v243 offset:18432
	ds_read_b128 v[174:177], v243 offset:19456
	ds_read_b128 v[192:195], v243 offset:20480
	ds_read_b128 v[196:199], v243 offset:21504
	ds_read_b128 v[200:203], v243 offset:22528
	ds_read_b128 v[204:207], v243 offset:23552
	global_load_lds_dwordx4 v[208:209], off
	s_add_i32 m0, s83, 0x2000
	s_add_u32 vcc_lo, s14, 0x100000
	v_lshl_add_u64 v[210:211], s[14:15], 0, v[184:185]
	s_addc_u32 vcc_hi, s15, 0
	s_add_i32 s83, s86, s5
	global_load_lds_dwordx4 v[210:211], off
	v_lshl_add_u64 v[212:213], vcc, 0, v[180:181]
	s_mov_b32 m0, s83
	v_lshl_add_u64 v[214:215], s[16:17], 0, v[182:183]
	global_load_lds_dwordx4 v[212:213], off
	v_lshl_add_u64 v[212:213], vcc, 0, v[184:185]
	s_add_i32 m0, s83, 0x2000
	s_nop 0
	global_load_lds_dwordx4 v[212:213], off
	v_lshl_add_u64 v[212:213], s[16:17], 0, v[178:179]
	s_mov_b32 m0, s7
	s_nop 0
	global_load_lds_dwordx4 v[212:213], off
	s_mov_b32 m0, s18
	s_nop 0
	global_load_lds_dwordx4 v[214:215], off
	s_waitcnt vmcnt(8) lgkmcnt(0)
	s_setprio 1
	s_barrier
; #define PG8_STAGE(bufoff, gbase, voff) do { _Pragma("unroll") for (int _i = 0; _i < 2; ++_i) \
;         __builtin_amdgcn_global_load_lds((const unsigned*)((const char*)(gbase) + (voff)[_i]), (PG8_LAS unsigned*)(lds + (bufoff) + ldsw + _i * 8192), 16, 0, 0); } while (0)
; #define PG8_LDA(dst, b, h) do { _Pragma("unroll") for (int m = 0; m < 4; ++m) _Pragma("unroll") for (int k = 0; k < 2; ++k) dst[m][k] = *(const PG8_LAS bf16x8*)(lds + PG8_SA(b, h) + aoff + m * 2048 + k * 1024); } while (0)
; #define PG8_LDB(dst, b, h) do { _Pragma("unroll") for (int n = 0; n < 2; ++n) _Pragma("unroll") for (int k = 0; k < 2; ++k) dst[n][k] = *(const PG8_LAS bf16x8*)(lds + PG8_SB(b, h) + boff + n * 2048 + k * 1024); } while (0)
; #define PG8_WAIT_V(n) asm volatile("s_waitcnt vmcnt(" #n ")" ::: "memory")
; #define PG8_WAIT_L(n) asm volatile("s_waitcnt lgkmcnt(" #n ")" ::: "memory")
; #define PG8_BAR __builtin_amdgcn_s_barrier()
; #define PG8_SCHED __builtin_amdgcn_sched_barrier(0)
; template <class Epi, class Sched, bool ALIGN_EPI = false, bool SP2 = false, bool F8 = false>
; __device__ __forceinline__ void gemm_phase(PG8_LAS unsigned char* lds, const Gemm g, const Sched& S, const Epi& E) {
;     ...
;             PG8_WAIT_V(8); PG8_WAIT_L(0); PG8_BAR; PG8_MMA(1, 0, At, B0); PG8_MMA(1, 1, At, B1); PG8_BAR; PG8_SCHED;
;             PG8_LDB(B0, 1, 0); PG8_LDB(B1, 1, 1); PG8_SCHED; PG8_LDA(At, 1, 0); PG8_STAGE(PG8_SA(0, 1), a2 + hA, voffA);
;             PG8_WAIT_V(8); PG8_WAIT_L(0); PG8_BAR; PG8_MMA(0, 0, At, B0); PG8_MMA(0, 1, At, B1); PG8_BAR; PG8_SCHED;
	v_mfma_f32_16x16x32_bf16 v[62:65], v[130:133], v[162:165], v[62:65]
	v_mfma_f32_16x16x32_bf16 v[38:41], v[138:141], v[162:165], v[38:41]
	v_mfma_f32_16x16x32_bf16 v[42:45], v[130:133], v[170:173], v[42:45]
	v_mfma_f32_16x16x32_bf16 v[14:17], v[138:141], v[170:173], v[14:17]
	v_mfma_f32_16x16x32_bf16 v[34:37], v[130:133], v[192:195], v[34:37]
	v_mfma_f32_16x16x32_bf16 v[10:13], v[138:141], v[192:195], v[10:13]
	v_mfma_f32_16x16x32_bf16 v[50:53], v[130:133], v[200:203], v[50:53]
	v_mfma_f32_16x16x32_bf16 v[114:117], v[138:141], v[200:203], v[114:117]
	v_mfma_f32_16x16x32_bf16 v[62:65], v[134:137], v[166:169], v[62:65]
	v_mfma_f32_16x16x32_bf16 v[38:41], v[142:145], v[166:169], v[38:41]
	v_mfma_f32_16x16x32_bf16 v[42:45], v[134:137], v[174:177], v[42:45]
	v_mfma_f32_16x16x32_bf16 v[14:17], v[142:145], v[174:177], v[14:17]
	v_mfma_f32_16x16x32_bf16 v[34:37], v[134:137], v[196:199], v[34:37]
	v_mfma_f32_16x16x32_bf16 v[10:13], v[142:145], v[196:199], v[10:13]
	v_mfma_f32_16x16x32_bf16 v[50:53], v[134:137], v[204:207], v[50:53]
	v_mfma_f32_16x16x32_bf16 v[114:117], v[142:145], v[204:207], v[114:117]
	v_mfma_f32_16x16x32_bf16 v[46:49], v[146:149], v[162:165], v[46:49]
	v_mfma_f32_16x16x32_bf16 v[22:25], v[154:157], v[162:165], v[22:25]
	v_mfma_f32_16x16x32_bf16 v[30:33], v[146:149], v[170:173], v[30:33]
	v_mfma_f32_16x16x32_bf16 v[6:9], v[154:157], v[170:173], v[6:9]
	v_mfma_f32_16x16x32_bf16 v[26:29], v[146:149], v[192:195], v[26:29]
	v_mfma_f32_16x16x32_bf16 v[2:5], v[154:157], v[192:195], v[2:5]
	v_mfma_f32_16x16x32_bf16 v[54:57], v[146:149], v[200:203], v[54:57]
	v_mfma_f32_16x16x32_bf16 v[18:21], v[154:157], v[200:203], v[18:21]
	v_mfma_f32_16x16x32_bf16 v[46:49], v[150:153], v[166:169], v[46:49]
	v_mfma_f32_16x16x32_bf16 v[22:25], v[158:161], v[166:169], v[22:25]
	v_mfma_f32_16x16x32_bf16 v[30:33], v[150:153], v[174:177], v[30:33]
	v_mfma_f32_16x16x32_bf16 v[6:9], v[158:161], v[174:177], v[6:9]
	v_mfma_f32_16x16x32_bf16 v[26:29], v[150:153], v[196:199], v[26:29]
	v_mfma_f32_16x16x32_bf16 v[2:5], v[158:161], v[196:199], v[2:5]
	v_mfma_f32_16x16x32_bf16 v[54:57], v[150:153], v[204:207], v[54:57]
	v_mfma_f32_16x16x32_bf16 v[18:21], v[158:161], v[204:207], v[18:21]
	s_barrier
	s_setprio 0
	s_add_i32 s83, 0, 0x18000
	s_add_i32 vcc_lo, 0, 0x1c000
	v_add_u32_e32 v142, s83, v240
	v_add_u32_e32 v158, vcc_lo, v240
	ds_read_b128 v[130:133], v142
	ds_read_b128 v[134:137], v142 offset:1024
	ds_read_b128 v[138:141], v142 offset:2048
	ds_read_b128 v[142:145], v142 offset:3072
	ds_read_b128 v[146:149], v158
	ds_read_b128 v[150:153], v158 offset:1024
	ds_read_b128 v[154:157], v158 offset:2048
	ds_read_b128 v[158:161], v158 offset:3072
	s_add_u32 s16, s16, 0x100000
	s_addc_u32 s17, s17, 0
	s_mov_b32 m0, s19
	v_lshl_add_u64 v[216:217], s[16:17], 0, v[178:179]
	ds_read_b128 v[162:165], v243 offset:32768
	ds_read_b128 v[166:169], v243 offset:33792
	ds_read_b128 v[170:173], v243 offset:34816
	ds_read_b128 v[174:177], v243 offset:35840
	ds_read_b128 v[192:195], v243 offset:36864
	ds_read_b128 v[196:199], v243 offset:37888
	ds_read_b128 v[200:203], v243 offset:38912
	ds_read_b128 v[204:207], v243 offset:39936
	global_load_lds_dwordx4 v[216:217], off
	v_lshl_add_u64 v[216:217], s[16:17], 0, v[182:183]
	s_mov_b32 m0, s29
	s_nop 0
	global_load_lds_dwordx4 v[216:217], off
	s_waitcnt vmcnt(8) lgkmcnt(0)
	s_setprio 1
	s_barrier
	v_mfma_f32_16x16x32_bf16 v[126:129], v[130:133], v[162:165], v[126:129]
	v_mfma_f32_16x16x32_bf16 v[90:93], v[138:141], v[162:165], v[90:93]
	v_mfma_f32_16x16x32_bf16 v[110:113], v[130:133], v[170:173], v[110:113]
	v_mfma_f32_16x16x32_bf16 v[86:89], v[138:141], v[170:173], v[86:89]
	v_mfma_f32_16x16x32_bf16 v[106:109], v[130:133], v[192:195], v[106:109]
	v_mfma_f32_16x16x32_bf16 v[82:85], v[138:141], v[192:195], v[82:85]
	v_mfma_f32_16x16x32_bf16 v[118:121], v[130:133], v[200:203], v[118:121]
	v_mfma_f32_16x16x32_bf16 v[122:125], v[138:141], v[200:203], v[122:125]
	v_mfma_f32_16x16x32_bf16 v[126:129], v[134:137], v[166:169], v[126:129]
	v_mfma_f32_16x16x32_bf16 v[90:93], v[142:145], v[166:169], v[90:93]
	v_mfma_f32_16x16x32_bf16 v[110:113], v[134:137], v[174:177], v[110:113]
	v_mfma_f32_16x16x32_bf16 v[86:89], v[142:145], v[174:177], v[86:89]
	v_mfma_f32_16x16x32_bf16 v[106:109], v[134:137], v[196:199], v[106:109]
	v_mfma_f32_16x16x32_bf16 v[82:85], v[142:145], v[196:199], v[82:85]
	v_mfma_f32_16x16x32_bf16 v[118:121], v[134:137], v[204:207], v[118:121]
	v_mfma_f32_16x16x32_bf16 v[122:125], v[142:145], v[204:207], v[122:125]
	v_mfma_f32_16x16x32_bf16 v[94:97], v[146:149], v[162:165], v[94:97]
	v_mfma_f32_16x16x32_bf16 v[66:69], v[154:157], v[162:165], v[66:69]
	v_mfma_f32_16x16x32_bf16 v[102:105], v[146:149], v[170:173], v[102:105]
	v_mfma_f32_16x16x32_bf16 v[78:81], v[154:157], v[170:173], v[78:81]
	v_mfma_f32_16x16x32_bf16 v[98:101], v[146:149], v[192:195], v[98:101]
	v_mfma_f32_16x16x32_bf16 v[74:77], v[154:157], v[192:195], v[74:77]
	v_mfma_f32_16x16x32_bf16 v[70:73], v[146:149], v[200:203], v[70:73]
	v_mfma_f32_16x16x32_bf16 v[58:61], v[154:157], v[200:203], v[58:61]
	v_mfma_f32_16x16x32_bf16 v[94:97], v[150:153], v[166:169], v[94:97]
	v_mfma_f32_16x16x32_bf16 v[66:69], v[158:161], v[166:169], v[66:69]
	v_mfma_f32_16x16x32_bf16 v[102:105], v[150:153], v[174:177], v[102:105]
	v_mfma_f32_16x16x32_bf16 v[78:81], v[158:161], v[174:177], v[78:81]
	v_mfma_f32_16x16x32_bf16 v[98:101], v[150:153], v[196:199], v[98:101]
	v_mfma_f32_16x16x32_bf16 v[74:77], v[158:161], v[196:199], v[74:77]
	v_mfma_f32_16x16x32_bf16 v[70:73], v[150:153], v[204:207], v[70:73]
	v_mfma_f32_16x16x32_bf16 v[58:61], v[158:161], v[204:207], v[58:61]
	s_barrier
; #define PG8_STAGE(bufoff, gbase, voff) do { _Pragma("unroll") for (int _i = 0; _i < 2; ++_i) \
;         __builtin_amdgcn_global_load_lds((const unsigned*)((const char*)(gbase) + (voff)[_i]), (PG8_LAS unsigned*)(lds + (bufoff) + ldsw + _i * 8192), 16, 0, 0); } while (0)
; #define PG8_LDA(dst, b, h) do { _Pragma("unroll") for (int m = 0; m < 4; ++m) _Pragma("unroll") for (int k = 0; k < 2; ++k) dst[m][k] = *(const PG8_LAS bf16x8*)(lds + PG8_SA(b, h) + aoff + m * 2048 + k * 1024); } while (0)
; #define PG8_WAIT_V(n) asm volatile("s_waitcnt vmcnt(" #n ")" ::: "memory")
; #define PG8_WAIT_L(n) asm volatile("s_waitcnt lgkmcnt(" #n ")" ::: "memory")
; #define PG8_BAR __builtin_amdgcn_s_barrier()
; #define PG8_SCHED __builtin_amdgcn_sched_barrier(0)
; template <class Epi, class Sched, bool ALIGN_EPI = false, bool SP2 = false, bool F8 = false>
; __device__ __forceinline__ void gemm_phase(PG8_LAS unsigned char* lds, const Gemm g, const Sched& S, const Epi& E) {
;     ...
;             PG8_LDA(At, 1, 1); PG8_STAGE(PG8_SB(1, 0), b3, voffB); PG8_STAGE(PG8_SB(1, 1), b3 + hB, voffB); PG8_STAGE(PG8_SA(1, 0), a3, voffA);
;             PG8_WAIT_V(8); PG8_WAIT_L(0); PG8_BAR; PG8_MMA(1, 0, At, B0); PG8_MMA(1, 1, At, B1); PG8_BAR; PG8_SCHED;
;     ...
;         if constexpr (ALIGN_EPI) { if (wr == 0) PG8_BAR; }
	s_setprio 0
	s_add_i32 s16, s83, s5
	v_lshl_add_u64 v[208:209], v[208:209], 0, s[38:39]
	s_mov_b32 m0, s16
	ds_read_b128 v[162:165], v243 offset:49152
	ds_read_b128 v[166:169], v243 offset:50176
	ds_read_b128 v[170:173], v243 offset:51200
	ds_read_b128 v[174:177], v243 offset:52224
	ds_read_b128 v[192:195], v243 offset:53248
	ds_read_b128 v[196:199], v243 offset:54272
	ds_read_b128 v[200:203], v243 offset:55296
	ds_read_b128 v[204:207], v243 offset:56320
	global_load_lds_dwordx4 v[208:209], off
	s_add_i32 m0, s16, 0x2000
	s_add_u32 s14, s14, 0x100080
	v_lshl_add_u64 v[208:209], v[210:211], 0, s[38:39]
	s_addc_u32 s15, s15, 0
	s_add_i32 s16, vcc_lo, s5
	global_load_lds_dwordx4 v[208:209], off
	v_lshl_add_u64 v[208:209], s[14:15], 0, v[180:181]
	s_mov_b32 m0, s16
	s_nop 0
	global_load_lds_dwordx4 v[208:209], off
	v_lshl_add_u64 v[208:209], s[14:15], 0, v[184:185]
	s_add_i32 m0, s16, 0x2000
	s_nop 0
	global_load_lds_dwordx4 v[208:209], off
	v_lshl_add_u64 v[208:209], v[212:213], 0, s[38:39]
	s_mov_b32 m0, s70
	s_nop 0
	global_load_lds_dwordx4 v[208:209], off
	v_lshl_add_u64 v[208:209], v[214:215], 0, s[38:39]
	s_mov_b32 m0, s71
	s_nop 0
	global_load_lds_dwordx4 v[208:209], off
	s_waitcnt vmcnt(8) lgkmcnt(0)
	s_setprio 1
	s_barrier
	v_mfma_f32_16x16x32_bf16 v[62:65], v[130:133], v[162:165], v[62:65]
	v_mfma_f32_16x16x32_bf16 v[38:41], v[138:141], v[162:165], v[38:41]
	v_mfma_f32_16x16x32_bf16 v[42:45], v[130:133], v[170:173], v[42:45]
	v_mfma_f32_16x16x32_bf16 v[14:17], v[138:141], v[170:173], v[14:17]
	v_mfma_f32_16x16x32_bf16 v[34:37], v[130:133], v[192:195], v[34:37]
	v_mfma_f32_16x16x32_bf16 v[10:13], v[138:141], v[192:195], v[10:13]
	v_mfma_f32_16x16x32_bf16 v[50:53], v[130:133], v[200:203], v[50:53]
	v_mfma_f32_16x16x32_bf16 v[114:117], v[138:141], v[200:203], v[114:117]
	v_mfma_f32_16x16x32_bf16 v[62:65], v[134:137], v[166:169], v[62:65]
	v_mfma_f32_16x16x32_bf16 v[38:41], v[142:145], v[166:169], v[38:41]
	v_mfma_f32_16x16x32_bf16 v[42:45], v[134:137], v[174:177], v[42:45]
	v_mfma_f32_16x16x32_bf16 v[14:17], v[142:145], v[174:177], v[14:17]
	v_mfma_f32_16x16x32_bf16 v[34:37], v[134:137], v[196:199], v[34:37]
	v_mfma_f32_16x16x32_bf16 v[10:13], v[142:145], v[196:199], v[10:13]
	v_mfma_f32_16x16x32_bf16 v[50:53], v[134:137], v[204:207], v[50:53]
	v_mfma_f32_16x16x32_bf16 v[114:117], v[142:145], v[204:207], v[114:117]
	v_mfma_f32_16x16x32_bf16 v[46:49], v[146:149], v[162:165], v[46:49]
	v_mfma_f32_16x16x32_bf16 v[22:25], v[154:157], v[162:165], v[22:25]
	v_mfma_f32_16x16x32_bf16 v[30:33], v[146:149], v[170:173], v[30:33]
	v_mfma_f32_16x16x32_bf16 v[6:9], v[154:157], v[170:173], v[6:9]
	v_mfma_f32_16x16x32_bf16 v[26:29], v[146:149], v[192:195], v[26:29]
	v_mfma_f32_16x16x32_bf16 v[2:5], v[154:157], v[192:195], v[2:5]
	v_mfma_f32_16x16x32_bf16 v[54:57], v[146:149], v[200:203], v[54:57]
	v_mfma_f32_16x16x32_bf16 v[18:21], v[154:157], v[200:203], v[18:21]
	v_mfma_f32_16x16x32_bf16 v[46:49], v[150:153], v[166:169], v[46:49]
	v_mfma_f32_16x16x32_bf16 v[22:25], v[158:161], v[166:169], v[22:25]
	v_mfma_f32_16x16x32_bf16 v[30:33], v[150:153], v[174:177], v[30:33]
	v_mfma_f32_16x16x32_bf16 v[6:9], v[158:161], v[174:177], v[6:9]
	v_mfma_f32_16x16x32_bf16 v[26:29], v[150:153], v[196:199], v[26:29]
	v_mfma_f32_16x16x32_bf16 v[2:5], v[158:161], v[196:199], v[2:5]
	v_mfma_f32_16x16x32_bf16 v[54:57], v[150:153], v[204:207], v[54:57]
	v_mfma_f32_16x16x32_bf16 v[18:21], v[158:161], v[204:207], v[18:21]
	s_barrier
	s_setprio 0
	s_add_i32 s82, s82, 2
	s_add_u32 s80, s80, 0x100
	s_addc_u32 s81, s81, 0
	s_add_u32 s12, s12, 0x100
	s_addc_u32 s13, s13, 0
	s_cmp_gt_u32 s82, 61
	s_cbranch_scc0 .LBB0_825
	s_and_b64 vcc, exec, s[40:41]
	s_cbranch_vccz .LBB0_828
	s_barrier

; #define PG8_STAGE(bufoff, gbase, voff) do { _Pragma("unroll") for (int _i = 0; _i < 2; ++_i) \
;         __builtin_amdgcn_global_load_lds((const unsigned*)((const char*)(gbase) + (voff)[_i]), (PG8_LAS unsigned*)(lds + (bufoff) + ldsw + _i * 8192), 16, 0, 0); } while (0)
; #define PG8_LDA(dst, b, h) do { _Pragma("unroll") for (int m = 0; m < 4; ++m) _Pragma("unroll") for (int k = 0; k < 2; ++k) dst[m][k] = *(const PG8_LAS bf16x8*)(lds + PG8_SA(b, h) + aoff + m * 2048 + k * 1024); } while (0)
; #define PG8_LDB(dst, b, h) do { _Pragma("unroll") for (int n = 0; n < 2; ++n) _Pragma("unroll") for (int k = 0; k < 2; ++k) dst[n][k] = *(const PG8_LAS bf16x8*)(lds + PG8_SB(b, h) + boff + n * 2048 + k * 1024); } while (0)
; #define PG8_WAIT_V(n) asm volatile("s_waitcnt vmcnt(" #n ")" ::: "memory")
; #define PG8_WAIT_L(n) asm volatile("s_waitcnt lgkmcnt(" #n ")" ::: "memory")
; #define PG8_BAR __builtin_amdgcn_s_barrier()
; #define PG8_SCHED __builtin_amdgcn_sched_barrier(0)
; template <class Epi, class Sched, bool ALIGN_EPI = false, bool SP2 = false, bool F8 = false>
; __device__ __forceinline__ void gemm_phase(PG8_LAS unsigned char* lds, const Gemm g, const Sched& S, const Epi& E) {
;     ...
;             PG8_LDB(B0, 0, 0); PG8_LDB(B1, 0, 1); PG8_SCHED; PG8_LDA(At, 0, 0); PG8_STAGE(PG8_SA(1, 1), a1 + hA, voffA);
;             PG8_WAIT_V(8); PG8_WAIT_L(0); PG8_BAR; PG8_MMA(0, 0, At, B0); PG8_MMA(0, 1, At, B1); PG8_BAR; PG8_SCHED;
;             PG8_LDA(At, 0, 1); PG8_STAGE(PG8_SB(0, 0), b2, voffB); PG8_STAGE(PG8_SB(0, 1), b2 + hB, voffB); PG8_STAGE(PG8_SA(0, 0), a2, voffA);
;             PG8_WAIT_V(8); PG8_WAIT_L(0); PG8_BAR; PG8_MMA(1, 0, At, B0); PG8_MMA(1, 1, At, B1); PG8_BAR; PG8_SCHED;
.LBB0_883:
	ds_read_b128 v[130:133], v247
	ds_read_b128 v[134:137], v247 offset:1024
	ds_read_b128 v[138:141], v247 offset:2048
	ds_read_b128 v[142:145], v247 offset:3072
	ds_read_b128 v[146:149], v248
	ds_read_b128 v[150:153], v248 offset:1024
	ds_read_b128 v[154:157], v248 offset:2048
	ds_read_b128 v[158:161], v248 offset:3072
	s_add_u32 s14, s10, 0xfff00080
	s_addc_u32 s15, s11, -1
	s_cmp_eq_u32 s88, 12
	s_cselect_b32 s17, s13, s15
	s_cselect_b32 s16, s77, s14
	s_cselect_b32 s15, s79, s87
	s_cselect_b32 s14, s85, s86
	v_lshl_add_u64 v[212:213], s[10:11], 0, v[194:195]
	s_add_i32 m0, s6, 0xc000
	ds_read_b128 v[162:165], v249
	ds_read_b128 v[166:169], v249 offset:1024
	ds_read_b128 v[170:173], v249 offset:2048
	ds_read_b128 v[174:177], v249 offset:3072
	ds_read_b128 v[178:181], v249 offset:4096
	ds_read_b128 v[200:203], v249 offset:5120
	ds_read_b128 v[204:207], v249 offset:6144
	ds_read_b128 v[208:211], v249 offset:7168
	global_load_lds_dwordx4 v[212:213], off
	v_lshl_add_u64 v[212:213], s[10:11], 0, v[192:193]
	s_add_i32 m0, s6, 0xe000
	s_nop 0
	global_load_lds_dwordx4 v[212:213], off
	s_waitcnt vmcnt(8) lgkmcnt(0)
	s_setprio 1
	s_barrier
	v_mfma_f32_16x16x32_bf16 v[126:129], v[130:133], v[162:165], v[126:129]
	v_mfma_f32_16x16x32_bf16 v[122:125], v[138:141], v[162:165], v[122:125]
	v_mfma_f32_16x16x32_bf16 v[118:121], v[130:133], v[170:173], v[118:121]
	v_mfma_f32_16x16x32_bf16 v[114:117], v[138:141], v[170:173], v[114:117]
	v_mfma_f32_16x16x32_bf16 v[110:113], v[130:133], v[178:181], v[110:113]
	v_mfma_f32_16x16x32_bf16 v[106:109], v[138:141], v[178:181], v[106:109]
	v_mfma_f32_16x16x32_bf16 v[102:105], v[130:133], v[204:207], v[102:105]
	v_mfma_f32_16x16x32_bf16 v[98:101], v[138:141], v[204:207], v[98:101]
	v_mfma_f32_16x16x32_bf16 v[126:129], v[134:137], v[166:169], v[126:129]
	v_mfma_f32_16x16x32_bf16 v[122:125], v[142:145], v[166:169], v[122:125]
	v_mfma_f32_16x16x32_bf16 v[118:121], v[134:137], v[174:177], v[118:121]
	v_mfma_f32_16x16x32_bf16 v[114:117], v[142:145], v[174:177], v[114:117]
	v_mfma_f32_16x16x32_bf16 v[110:113], v[134:137], v[200:203], v[110:113]
	v_mfma_f32_16x16x32_bf16 v[106:109], v[142:145], v[200:203], v[106:109]
	v_mfma_f32_16x16x32_bf16 v[102:105], v[134:137], v[208:211], v[102:105]
	v_mfma_f32_16x16x32_bf16 v[98:101], v[142:145], v[208:211], v[98:101]
	v_mfma_f32_16x16x32_bf16 v[82:85], v[146:149], v[162:165], v[82:85]
	v_mfma_f32_16x16x32_bf16 v[74:77], v[154:157], v[162:165], v[74:77]
	v_mfma_f32_16x16x32_bf16 v[94:97], v[146:149], v[170:173], v[94:97]
	v_mfma_f32_16x16x32_bf16 v[90:93], v[154:157], v[170:173], v[90:93]
	v_mfma_f32_16x16x32_bf16 v[86:89], v[146:149], v[178:181], v[86:89]
	v_mfma_f32_16x16x32_bf16 v[78:81], v[154:157], v[178:181], v[78:81]
	v_mfma_f32_16x16x32_bf16 v[70:73], v[146:149], v[204:207], v[70:73]
	v_mfma_f32_16x16x32_bf16 v[62:65], v[154:157], v[204:207], v[62:65]
	v_mfma_f32_16x16x32_bf16 v[82:85], v[150:153], v[166:169], v[82:85]
	v_mfma_f32_16x16x32_bf16 v[74:77], v[158:161], v[166:169], v[74:77]
	v_mfma_f32_16x16x32_bf16 v[94:97], v[150:153], v[174:177], v[94:97]
	v_mfma_f32_16x16x32_bf16 v[90:93], v[158:161], v[174:177], v[90:93]
	v_mfma_f32_16x16x32_bf16 v[86:89], v[150:153], v[200:203], v[86:89]
	v_mfma_f32_16x16x32_bf16 v[78:81], v[158:161], v[200:203], v[78:81]
	v_mfma_f32_16x16x32_bf16 v[70:73], v[150:153], v[208:211], v[70:73]
	v_mfma_f32_16x16x32_bf16 v[62:65], v[158:161], v[208:211], v[62:65]
	s_barrier
	s_setprio 0
	s_add_i32 s89, s54, s96
	v_lshl_add_u64 v[212:213], s[14:15], 0, v[184:185]
	s_mov_b32 m0, s89
	ds_read_b128 v[162:165], v249 offset:16384
	ds_read_b128 v[166:169], v249 offset:17408
	ds_read_b128 v[170:173], v249 offset:18432
	ds_read_b128 v[174:177], v249 offset:19456
	ds_read_b128 v[178:181], v249 offset:20480
	ds_read_b128 v[200:203], v249 offset:21504
	ds_read_b128 v[204:207], v249 offset:22528
	ds_read_b128 v[208:211], v249 offset:23552
	global_load_lds_dwordx4 v[212:213], off
	s_add_i32 m0, s89, 0x2000
	s_add_u32 s90, s14, 0x100000
	v_lshl_add_u64 v[214:215], s[14:15], 0, v[188:189]
	s_addc_u32 s91, s15, 0
	s_add_i32 s89, s55, s96
	global_load_lds_dwordx4 v[214:215], off
	v_lshl_add_u64 v[216:217], s[90:91], 0, v[184:185]
	s_mov_b32 m0, s89
	v_lshl_add_u64 v[218:219], s[16:17], 0, v[186:187]
	global_load_lds_dwordx4 v[216:217], off
	v_lshl_add_u64 v[216:217], s[90:91], 0, v[188:189]
	s_add_i32 m0, s89, 0x2000
	s_nop 0
	global_load_lds_dwordx4 v[216:217], off
	v_lshl_add_u64 v[216:217], s[16:17], 0, v[182:183]
	s_mov_b32 m0, s6
	s_nop 0
	global_load_lds_dwordx4 v[216:217], off
	s_mov_b32 m0, s7
	s_nop 0
	global_load_lds_dwordx4 v[218:219], off
	s_waitcnt vmcnt(8) lgkmcnt(0)
	s_setprio 1
	s_barrier
; #define PG8_STAGE(bufoff, gbase, voff) do { _Pragma("unroll") for (int _i = 0; _i < 2; ++_i) \
;         __builtin_amdgcn_global_load_lds((const unsigned*)((const char*)(gbase) + (voff)[_i]), (PG8_LAS unsigned*)(lds + (bufoff) + ldsw + _i * 8192), 16, 0, 0); } while (0)
; #define PG8_LDA(dst, b, h) do { _Pragma("unroll") for (int m = 0; m < 4; ++m) _Pragma("unroll") for (int k = 0; k < 2; ++k) dst[m][k] = *(const PG8_LAS bf16x8*)(lds + PG8_SA(b, h) + aoff + m * 2048 + k * 1024); } while (0)
; #define PG8_LDB(dst, b, h) do { _Pragma("unroll") for (int n = 0; n < 2; ++n) _Pragma("unroll") for (int k = 0; k < 2; ++k) dst[n][k] = *(const PG8_LAS bf16x8*)(lds + PG8_SB(b, h) + boff + n * 2048 + k * 1024); } while (0)
; #define PG8_WAIT_V(n) asm volatile("s_waitcnt vmcnt(" #n ")" ::: "memory")
; #define PG8_WAIT_L(n) asm volatile("s_waitcnt lgkmcnt(" #n ")" ::: "memory")
; #define PG8_BAR __builtin_amdgcn_s_barrier()
; #define PG8_SCHED __builtin_amdgcn_sched_barrier(0)
; template <class Epi, class Sched, bool ALIGN_EPI = false, bool SP2 = false, bool F8 = false>
; __device__ __forceinline__ void gemm_phase(PG8_LAS unsigned char* lds, const Gemm g, const Sched& S, const Epi& E) {
;     ...
;             PG8_WAIT_V(8); PG8_WAIT_L(0); PG8_BAR; PG8_MMA(1, 0, At, B0); PG8_MMA(1, 1, At, B1); PG8_BAR; PG8_SCHED;
;             PG8_LDB(B0, 1, 0); PG8_LDB(B1, 1, 1); PG8_SCHED; PG8_LDA(At, 1, 0); PG8_STAGE(PG8_SA(0, 1), a2 + hA, voffA);
;             PG8_WAIT_V(8); PG8_WAIT_L(0); PG8_BAR; PG8_MMA(0, 0, At, B0); PG8_MMA(0, 1, At, B1); PG8_BAR; PG8_SCHED;
	v_mfma_f32_16x16x32_bf16 v[66:69], v[130:133], v[162:165], v[66:69]
	v_mfma_f32_16x16x32_bf16 v[58:61], v[138:141], v[162:165], v[58:61]
	v_mfma_f32_16x16x32_bf16 v[54:57], v[130:133], v[170:173], v[54:57]
	v_mfma_f32_16x16x32_bf16 v[50:53], v[138:141], v[170:173], v[50:53]
	v_mfma_f32_16x16x32_bf16 v[46:49], v[130:133], v[178:181], v[46:49]
	v_mfma_f32_16x16x32_bf16 v[42:45], v[138:141], v[178:181], v[42:45]
	v_mfma_f32_16x16x32_bf16 v[38:41], v[130:133], v[204:207], v[38:41]
	v_mfma_f32_16x16x32_bf16 v[34:37], v[138:141], v[204:207], v[34:37]
	v_mfma_f32_16x16x32_bf16 v[66:69], v[134:137], v[166:169], v[66:69]
	v_mfma_f32_16x16x32_bf16 v[58:61], v[142:145], v[166:169], v[58:61]
	v_mfma_f32_16x16x32_bf16 v[54:57], v[134:137], v[174:177], v[54:57]
	v_mfma_f32_16x16x32_bf16 v[50:53], v[142:145], v[174:177], v[50:53]
	v_mfma_f32_16x16x32_bf16 v[46:49], v[134:137], v[200:203], v[46:49]
	v_mfma_f32_16x16x32_bf16 v[42:45], v[142:145], v[200:203], v[42:45]
	v_mfma_f32_16x16x32_bf16 v[38:41], v[134:137], v[208:211], v[38:41]
	v_mfma_f32_16x16x32_bf16 v[34:37], v[142:145], v[208:211], v[34:37]
	v_mfma_f32_16x16x32_bf16 v[30:33], v[146:149], v[162:165], v[30:33]
	v_mfma_f32_16x16x32_bf16 v[18:21], v[154:157], v[162:165], v[18:21]
	v_mfma_f32_16x16x32_bf16 v[26:29], v[146:149], v[170:173], v[26:29]
	v_mfma_f32_16x16x32_bf16 v[22:25], v[154:157], v[170:173], v[22:25]
	v_mfma_f32_16x16x32_bf16 v[14:17], v[146:149], v[178:181], v[14:17]
	v_mfma_f32_16x16x32_bf16 v[10:13], v[154:157], v[178:181], v[10:13]
	v_mfma_f32_16x16x32_bf16 v[6:9], v[146:149], v[204:207], v[6:9]
	v_mfma_f32_16x16x32_bf16 v[2:5], v[154:157], v[204:207], v[2:5]
	v_mfma_f32_16x16x32_bf16 v[30:33], v[150:153], v[166:169], v[30:33]
	v_mfma_f32_16x16x32_bf16 v[18:21], v[158:161], v[166:169], v[18:21]
	v_mfma_f32_16x16x32_bf16 v[26:29], v[150:153], v[174:177], v[26:29]
	v_mfma_f32_16x16x32_bf16 v[22:25], v[158:161], v[174:177], v[22:25]
	v_mfma_f32_16x16x32_bf16 v[14:17], v[150:153], v[200:203], v[14:17]
	v_mfma_f32_16x16x32_bf16 v[10:13], v[158:161], v[200:203], v[10:13]
	v_mfma_f32_16x16x32_bf16 v[6:9], v[150:153], v[208:211], v[6:9]
	v_mfma_f32_16x16x32_bf16 v[2:5], v[158:161], v[208:211], v[2:5]
	s_barrier
	s_setprio 0
	s_add_i32 s89, 0, 0x18000
	s_add_i32 s90, 0, 0x1c000
	v_add_u32_e32 v142, s89, v245
	v_add_u32_e32 v158, s90, v245
	ds_read_b128 v[130:133], v142
	ds_read_b128 v[134:137], v142 offset:1024
	ds_read_b128 v[138:141], v142 offset:2048
	ds_read_b128 v[142:145], v142 offset:3072
	ds_read_b128 v[146:149], v158
	ds_read_b128 v[150:153], v158 offset:1024
	ds_read_b128 v[154:157], v158 offset:2048
	ds_read_b128 v[158:161], v158 offset:3072
	s_add_u32 s16, s16, 0x100000
	s_addc_u32 s17, s17, 0
	s_mov_b32 m0, s5
	v_lshl_add_u64 v[220:221], s[16:17], 0, v[182:183]
	ds_read_b128 v[162:165], v249 offset:32768
	ds_read_b128 v[166:169], v249 offset:33792
	ds_read_b128 v[170:173], v249 offset:34816
	ds_read_b128 v[174:177], v249 offset:35840
	ds_read_b128 v[178:181], v249 offset:36864
	ds_read_b128 v[200:203], v249 offset:37888
	ds_read_b128 v[204:207], v249 offset:38912
	ds_read_b128 v[208:211], v249 offset:39936
	global_load_lds_dwordx4 v[220:221], off
	v_lshl_add_u64 v[220:221], s[16:17], 0, v[186:187]
	s_mov_b32 m0, s18
	s_nop 0
	global_load_lds_dwordx4 v[220:221], off
	s_waitcnt vmcnt(8) lgkmcnt(0)
	s_setprio 1
	s_barrier
	v_mfma_f32_16x16x32_bf16 v[126:129], v[130:133], v[162:165], v[126:129]
	v_mfma_f32_16x16x32_bf16 v[122:125], v[138:141], v[162:165], v[122:125]
	v_mfma_f32_16x16x32_bf16 v[118:121], v[130:133], v[170:173], v[118:121]
	v_mfma_f32_16x16x32_bf16 v[114:117], v[138:141], v[170:173], v[114:117]
	v_mfma_f32_16x16x32_bf16 v[110:113], v[130:133], v[178:181], v[110:113]
	v_mfma_f32_16x16x32_bf16 v[106:109], v[138:141], v[178:181], v[106:109]
	v_mfma_f32_16x16x32_bf16 v[102:105], v[130:133], v[204:207], v[102:105]
	v_mfma_f32_16x16x32_bf16 v[98:101], v[138:141], v[204:207], v[98:101]
	v_mfma_f32_16x16x32_bf16 v[126:129], v[134:137], v[166:169], v[126:129]
	v_mfma_f32_16x16x32_bf16 v[122:125], v[142:145], v[166:169], v[122:125]
	v_mfma_f32_16x16x32_bf16 v[118:121], v[134:137], v[174:177], v[118:121]
	v_mfma_f32_16x16x32_bf16 v[114:117], v[142:145], v[174:177], v[114:117]
	v_mfma_f32_16x16x32_bf16 v[110:113], v[134:137], v[200:203], v[110:113]
	v_mfma_f32_16x16x32_bf16 v[106:109], v[142:145], v[200:203], v[106:109]
	v_mfma_f32_16x16x32_bf16 v[102:105], v[134:137], v[208:211], v[102:105]
	v_mfma_f32_16x16x32_bf16 v[98:101], v[142:145], v[208:211], v[98:101]
	v_mfma_f32_16x16x32_bf16 v[82:85], v[146:149], v[162:165], v[82:85]
	v_mfma_f32_16x16x32_bf16 v[74:77], v[154:157], v[162:165], v[74:77]
	v_mfma_f32_16x16x32_bf16 v[94:97], v[146:149], v[170:173], v[94:97]
	v_mfma_f32_16x16x32_bf16 v[90:93], v[154:157], v[170:173], v[90:93]
	v_mfma_f32_16x16x32_bf16 v[86:89], v[146:149], v[178:181], v[86:89]
	v_mfma_f32_16x16x32_bf16 v[78:81], v[154:157], v[178:181], v[78:81]
	v_mfma_f32_16x16x32_bf16 v[70:73], v[146:149], v[204:207], v[70:73]
	v_mfma_f32_16x16x32_bf16 v[62:65], v[154:157], v[204:207], v[62:65]
	v_mfma_f32_16x16x32_bf16 v[82:85], v[150:153], v[166:169], v[82:85]
	v_mfma_f32_16x16x32_bf16 v[74:77], v[158:161], v[166:169], v[74:77]
	v_mfma_f32_16x16x32_bf16 v[94:97], v[150:153], v[174:177], v[94:97]
	v_mfma_f32_16x16x32_bf16 v[90:93], v[158:161], v[174:177], v[90:93]
	v_mfma_f32_16x16x32_bf16 v[86:89], v[150:153], v[200:203], v[86:89]
	v_mfma_f32_16x16x32_bf16 v[78:81], v[158:161], v[200:203], v[78:81]
	v_mfma_f32_16x16x32_bf16 v[70:73], v[150:153], v[208:211], v[70:73]
	v_mfma_f32_16x16x32_bf16 v[62:65], v[158:161], v[208:211], v[62:65]
	s_barrier
; #define PG8_STAGE(bufoff, gbase, voff) do { _Pragma("unroll") for (int _i = 0; _i < 2; ++_i) \
;         __builtin_amdgcn_global_load_lds((const unsigned*)((const char*)(gbase) + (voff)[_i]), (PG8_LAS unsigned*)(lds + (bufoff) + ldsw + _i * 8192), 16, 0, 0); } while (0)
; #define PG8_LDA(dst, b, h) do { _Pragma("unroll") for (int m = 0; m < 4; ++m) _Pragma("unroll") for (int k = 0; k < 2; ++k) dst[m][k] = *(const PG8_LAS bf16x8*)(lds + PG8_SA(b, h) + aoff + m * 2048 + k * 1024); } while (0)
; #define PG8_WAIT_V(n) asm volatile("s_waitcnt vmcnt(" #n ")" ::: "memory")
; #define PG8_WAIT_L(n) asm volatile("s_waitcnt lgkmcnt(" #n ")" ::: "memory")
; #define PG8_BAR __builtin_amdgcn_s_barrier()
; #define PG8_SCHED __builtin_amdgcn_sched_barrier(0)
; template <class Epi, class Sched, bool ALIGN_EPI = false, bool SP2 = false, bool F8 = false>
; __device__ __forceinline__ void gemm_phase(PG8_LAS unsigned char* lds, const Gemm g, const Sched& S, const Epi& E) {
;     ...
;             PG8_LDA(At, 1, 1); PG8_STAGE(PG8_SB(1, 0), b3, voffB); PG8_STAGE(PG8_SB(1, 1), b3 + hB, voffB); PG8_STAGE(PG8_SA(1, 0), a3, voffA);
;             PG8_WAIT_V(8); PG8_WAIT_L(0); PG8_BAR; PG8_MMA(1, 0, At, B0); PG8_MMA(1, 1, At, B1); PG8_BAR; PG8_SCHED;
;     ...
;         if constexpr (ALIGN_EPI) { if (wr == 0) PG8_BAR; }
	s_setprio 0
	s_add_i32 s16, s89, s96
	v_lshl_add_u64 v[212:213], v[212:213], 0, s[34:35]
	s_mov_b32 m0, s16
	ds_read_b128 v[162:165], v249 offset:49152
	ds_read_b128 v[166:169], v249 offset:50176
	ds_read_b128 v[170:173], v249 offset:51200
	ds_read_b128 v[174:177], v249 offset:52224
	ds_read_b128 v[178:181], v249 offset:53248
	ds_read_b128 v[200:203], v249 offset:54272
	ds_read_b128 v[204:207], v249 offset:55296
	ds_read_b128 v[208:211], v249 offset:56320
	global_load_lds_dwordx4 v[212:213], off
	s_add_i32 m0, s16, 0x2000
	s_add_u32 s14, s14, 0x100080
	v_lshl_add_u64 v[212:213], v[214:215], 0, s[34:35]
	s_addc_u32 s15, s15, 0
	s_add_i32 s16, s90, s96
	global_load_lds_dwordx4 v[212:213], off
	v_lshl_add_u64 v[212:213], s[14:15], 0, v[184:185]
	s_mov_b32 m0, s16
	s_nop 0
	global_load_lds_dwordx4 v[212:213], off
	v_lshl_add_u64 v[212:213], s[14:15], 0, v[188:189]
	s_add_i32 m0, s16, 0x2000
	s_nop 0
	global_load_lds_dwordx4 v[212:213], off
	v_lshl_add_u64 v[212:213], v[216:217], 0, s[34:35]
	s_mov_b32 m0, s31
	s_nop 0
	global_load_lds_dwordx4 v[212:213], off
	v_lshl_add_u64 v[212:213], v[218:219], 0, s[34:35]
	s_mov_b32 m0, s50
	s_nop 0
	global_load_lds_dwordx4 v[212:213], off
	s_waitcnt vmcnt(8) lgkmcnt(0)
	s_setprio 1
	s_barrier
	v_mfma_f32_16x16x32_bf16 v[66:69], v[130:133], v[162:165], v[66:69]
	v_mfma_f32_16x16x32_bf16 v[58:61], v[138:141], v[162:165], v[58:61]
	v_mfma_f32_16x16x32_bf16 v[54:57], v[130:133], v[170:173], v[54:57]
	v_mfma_f32_16x16x32_bf16 v[50:53], v[138:141], v[170:173], v[50:53]
	v_mfma_f32_16x16x32_bf16 v[46:49], v[130:133], v[178:181], v[46:49]
	v_mfma_f32_16x16x32_bf16 v[42:45], v[138:141], v[178:181], v[42:45]
	v_mfma_f32_16x16x32_bf16 v[38:41], v[130:133], v[204:207], v[38:41]
	v_mfma_f32_16x16x32_bf16 v[34:37], v[138:141], v[204:207], v[34:37]
	v_mfma_f32_16x16x32_bf16 v[66:69], v[134:137], v[166:169], v[66:69]
	v_mfma_f32_16x16x32_bf16 v[58:61], v[142:145], v[166:169], v[58:61]
	v_mfma_f32_16x16x32_bf16 v[54:57], v[134:137], v[174:177], v[54:57]
	v_mfma_f32_16x16x32_bf16 v[50:53], v[142:145], v[174:177], v[50:53]
	v_mfma_f32_16x16x32_bf16 v[46:49], v[134:137], v[200:203], v[46:49]
	v_mfma_f32_16x16x32_bf16 v[42:45], v[142:145], v[200:203], v[42:45]
	v_mfma_f32_16x16x32_bf16 v[38:41], v[134:137], v[208:211], v[38:41]
	v_mfma_f32_16x16x32_bf16 v[34:37], v[142:145], v[208:211], v[34:37]
	v_mfma_f32_16x16x32_bf16 v[30:33], v[146:149], v[162:165], v[30:33]
	v_mfma_f32_16x16x32_bf16 v[18:21], v[154:157], v[162:165], v[18:21]
	v_mfma_f32_16x16x32_bf16 v[26:29], v[146:149], v[170:173], v[26:29]
	v_mfma_f32_16x16x32_bf16 v[22:25], v[154:157], v[170:173], v[22:25]
	v_mfma_f32_16x16x32_bf16 v[14:17], v[146:149], v[178:181], v[14:17]
	v_mfma_f32_16x16x32_bf16 v[10:13], v[154:157], v[178:181], v[10:13]
	v_mfma_f32_16x16x32_bf16 v[6:9], v[146:149], v[204:207], v[6:9]
	v_mfma_f32_16x16x32_bf16 v[2:5], v[154:157], v[204:207], v[2:5]
	v_mfma_f32_16x16x32_bf16 v[30:33], v[150:153], v[166:169], v[30:33]
	v_mfma_f32_16x16x32_bf16 v[18:21], v[158:161], v[166:169], v[18:21]
	v_mfma_f32_16x16x32_bf16 v[26:29], v[150:153], v[174:177], v[26:29]
	v_mfma_f32_16x16x32_bf16 v[22:25], v[158:161], v[174:177], v[22:25]
	v_mfma_f32_16x16x32_bf16 v[14:17], v[150:153], v[200:203], v[14:17]
	v_mfma_f32_16x16x32_bf16 v[10:13], v[158:161], v[200:203], v[10:13]
	v_mfma_f32_16x16x32_bf16 v[6:9], v[150:153], v[208:211], v[6:9]
	v_mfma_f32_16x16x32_bf16 v[2:5], v[158:161], v[208:211], v[2:5]
	s_barrier
	s_setprio 0
	s_add_i32 s88, s88, 2
	s_add_u32 s86, s86, 0x100
	s_addc_u32 s87, s87, 0
	s_add_u32 s10, s10, 0x100
	s_addc_u32 s11, s11, 0
	s_cmp_gt_u32 s88, 13
	s_cbranch_scc0 .LBB0_883
	s_and_b64 vcc, exec, s[36:37]
	s_cbranch_vccz .LBB0_886
	s_barrier

; #define PG8_STAGE(bufoff, gbase, voff) do { _Pragma("unroll") for (int _i = 0; _i < 2; ++_i) \
;         __builtin_amdgcn_global_load_lds((const unsigned*)((const char*)(gbase) + (voff)[_i]), (PG8_LAS unsigned*)(lds + (bufoff) + ldsw + _i * 8192), 16, 0, 0); } while (0)
; #define PG8_LDA(dst, b, h) do { _Pragma("unroll") for (int m = 0; m < 4; ++m) _Pragma("unroll") for (int k = 0; k < 2; ++k) dst[m][k] = *(const PG8_LAS bf16x8*)(lds + PG8_SA(b, h) + aoff + m * 2048 + k * 1024); } while (0)
; #define PG8_LDB(dst, b, h) do { _Pragma("unroll") for (int n = 0; n < 2; ++n) _Pragma("unroll") for (int k = 0; k < 2; ++k) dst[n][k] = *(const PG8_LAS bf16x8*)(lds + PG8_SB(b, h) + boff + n * 2048 + k * 1024); } while (0)
; #define PG8_WAIT_V(n) asm volatile("s_waitcnt vmcnt(" #n ")" ::: "memory")
; #define PG8_WAIT_L(n) asm volatile("s_waitcnt lgkmcnt(" #n ")" ::: "memory")
; #define PG8_BAR __builtin_amdgcn_s_barrier()
; #define PG8_SCHED __builtin_amdgcn_sched_barrier(0)
; template <class Epi, class Sched, bool ALIGN_EPI = false, bool SP2 = false, bool F8 = false>
; __device__ __forceinline__ void gemm_phase(PG8_LAS unsigned char* lds, const Gemm g, const Sched& S, const Epi& E) {
;     ...
;             PG8_LDB(B0, 0, 0); PG8_LDB(B1, 0, 1); PG8_SCHED; PG8_LDA(At, 0, 0); PG8_STAGE(PG8_SA(1, 1), a1 + hA, voffA);
;             PG8_WAIT_V(8); PG8_WAIT_L(0); PG8_BAR; PG8_MMA(0, 0, At, B0); PG8_MMA(0, 1, At, B1); PG8_BAR; PG8_SCHED;
;             PG8_LDA(At, 0, 1); PG8_STAGE(PG8_SB(0, 0), b2, voffB); PG8_STAGE(PG8_SB(0, 1), b2 + hB, voffB); PG8_STAGE(PG8_SA(0, 0), a2, voffA);
;             PG8_WAIT_V(8); PG8_WAIT_L(0); PG8_BAR; PG8_MMA(1, 0, At, B0); PG8_MMA(1, 1, At, B1); PG8_BAR; PG8_SCHED;
.LBB0_1078:
	ds_read_b128 v[130:133], v197
	ds_read_b128 v[134:137], v197 offset:1024
	ds_read_b128 v[138:141], v197 offset:2048
	ds_read_b128 v[142:145], v197 offset:3072
	ds_read_b128 v[146:149], v198
	ds_read_b128 v[150:153], v198 offset:1024
	ds_read_b128 v[154:157], v198 offset:2048
	ds_read_b128 v[158:161], v198 offset:3072
	s_add_u32 s28, s26, 0x100
	s_addc_u32 s29, s27, 0
	s_cmpk_eq_i32 s55, 0xa8
	s_cselect_b32 s35, s7, s29
	s_cselect_b32 s34, s6, s28
	s_cselect_b32 s31, s9, s54
	s_cselect_b32 s30, s8, s53
	v_lshl_add_u64 v[216:217], s[26:27], 0, v[176:177]
	s_add_i32 m0, s39, 0xc000
	ds_read_b128 v[162:165], v199
	ds_read_b128 v[182:185], v199 offset:1024
	ds_read_b128 v[186:189], v199 offset:2048
	ds_read_b128 v[190:193], v199 offset:3072
	ds_read_b128 v[200:203], v199 offset:4096
	ds_read_b128 v[204:207], v199 offset:5120
	ds_read_b128 v[208:211], v199 offset:6144
	ds_read_b128 v[212:215], v199 offset:7168
	global_load_lds_dwordx4 v[216:217], off
	v_lshl_add_u64 v[216:217], s[26:27], 0, v[174:175]
	s_add_i32 m0, s39, 0xe000
	s_nop 0
	global_load_lds_dwordx4 v[216:217], off
	s_waitcnt vmcnt(8) lgkmcnt(0)
	s_setprio 1
	s_barrier
	v_mfma_f32_16x16x32_bf16 v[126:129], v[130:133], v[162:165], v[126:129]
	v_mfma_f32_16x16x32_bf16 v[122:125], v[138:141], v[162:165], v[122:125]
	v_mfma_f32_16x16x32_bf16 v[118:121], v[130:133], v[186:189], v[118:121]
	v_mfma_f32_16x16x32_bf16 v[106:109], v[138:141], v[186:189], v[106:109]
	v_mfma_f32_16x16x32_bf16 v[98:101], v[130:133], v[200:203], v[98:101]
	v_mfma_f32_16x16x32_bf16 v[90:93], v[138:141], v[200:203], v[90:93]
	v_mfma_f32_16x16x32_bf16 v[82:85], v[130:133], v[208:211], v[82:85]
	v_mfma_f32_16x16x32_bf16 v[74:77], v[138:141], v[208:211], v[74:77]
	v_mfma_f32_16x16x32_bf16 v[126:129], v[134:137], v[182:185], v[126:129]
	v_mfma_f32_16x16x32_bf16 v[122:125], v[142:145], v[182:185], v[122:125]
	v_mfma_f32_16x16x32_bf16 v[118:121], v[134:137], v[190:193], v[118:121]
	v_mfma_f32_16x16x32_bf16 v[106:109], v[142:145], v[190:193], v[106:109]
	v_mfma_f32_16x16x32_bf16 v[98:101], v[134:137], v[204:207], v[98:101]
	v_mfma_f32_16x16x32_bf16 v[90:93], v[142:145], v[204:207], v[90:93]
	v_mfma_f32_16x16x32_bf16 v[82:85], v[134:137], v[212:215], v[82:85]
	v_mfma_f32_16x16x32_bf16 v[74:77], v[142:145], v[212:215], v[74:77]
	v_mfma_f32_16x16x32_bf16 v[114:117], v[146:149], v[162:165], v[114:117]
	v_mfma_f32_16x16x32_bf16 v[110:113], v[154:157], v[162:165], v[110:113]
	v_mfma_f32_16x16x32_bf16 v[102:105], v[146:149], v[186:189], v[102:105]
	v_mfma_f32_16x16x32_bf16 v[94:97], v[154:157], v[186:189], v[94:97]
	v_mfma_f32_16x16x32_bf16 v[86:89], v[146:149], v[200:203], v[86:89]
	v_mfma_f32_16x16x32_bf16 v[78:81], v[154:157], v[200:203], v[78:81]
	v_mfma_f32_16x16x32_bf16 v[70:73], v[146:149], v[208:211], v[70:73]
	v_mfma_f32_16x16x32_bf16 v[66:69], v[154:157], v[208:211], v[66:69]
	v_mfma_f32_16x16x32_bf16 v[114:117], v[150:153], v[182:185], v[114:117]
	v_mfma_f32_16x16x32_bf16 v[110:113], v[158:161], v[182:185], v[110:113]
	v_mfma_f32_16x16x32_bf16 v[102:105], v[150:153], v[190:193], v[102:105]
	v_mfma_f32_16x16x32_bf16 v[94:97], v[158:161], v[190:193], v[94:97]
	v_mfma_f32_16x16x32_bf16 v[86:89], v[150:153], v[204:207], v[86:89]
	v_mfma_f32_16x16x32_bf16 v[78:81], v[158:161], v[204:207], v[78:81]
	v_mfma_f32_16x16x32_bf16 v[70:73], v[150:153], v[212:215], v[70:73]
	v_mfma_f32_16x16x32_bf16 v[66:69], v[158:161], v[212:215], v[66:69]
	s_barrier
	s_setprio 0
	s_add_i32 s26, s47, s36
	v_lshl_add_u64 v[216:217], s[30:31], 0, v[170:171]
	s_mov_b32 m0, s26
	ds_read_b128 v[162:165], v199 offset:16384
	ds_read_b128 v[182:185], v199 offset:17408
	ds_read_b128 v[186:189], v199 offset:18432
	ds_read_b128 v[190:193], v199 offset:19456
	ds_read_b128 v[200:203], v199 offset:20480
	ds_read_b128 v[204:207], v199 offset:21504
	ds_read_b128 v[208:211], v199 offset:22528
	ds_read_b128 v[212:215], v199 offset:23552
	global_load_lds_dwordx4 v[216:217], off
	s_add_i32 m0, s26, 0x2000
	s_add_u32 s26, s30, 0x2b0000
	v_lshl_add_u64 v[218:219], s[30:31], 0, v[166:167]
	s_addc_u32 s27, s31, 0
	s_add_i32 s56, s48, s36
	global_load_lds_dwordx4 v[218:219], off
	v_lshl_add_u64 v[220:221], s[26:27], 0, v[170:171]
	s_mov_b32 m0, s56
	v_lshl_add_u64 v[222:223], s[34:35], 0, v[168:169]
	global_load_lds_dwordx4 v[220:221], off
	v_lshl_add_u64 v[220:221], s[26:27], 0, v[166:167]
	s_add_i32 m0, s56, 0x2000
	s_nop 0
	global_load_lds_dwordx4 v[220:221], off
	v_lshl_add_u64 v[220:221], s[34:35], 0, v[172:173]
	s_mov_b32 m0, s39
	s_nop 0
	global_load_lds_dwordx4 v[220:221], off
	s_mov_b32 m0, s40
	s_nop 0
	global_load_lds_dwordx4 v[222:223], off
	s_waitcnt vmcnt(8) lgkmcnt(0)
	s_setprio 1
	s_barrier
; #define PG8_STAGE(bufoff, gbase, voff) do { _Pragma("unroll") for (int _i = 0; _i < 2; ++_i) \
;         __builtin_amdgcn_global_load_lds((const unsigned*)((const char*)(gbase) + (voff)[_i]), (PG8_LAS unsigned*)(lds + (bufoff) + ldsw + _i * 8192), 16, 0, 0); } while (0)
; #define PG8_LDA(dst, b, h) do { _Pragma("unroll") for (int m = 0; m < 4; ++m) _Pragma("unroll") for (int k = 0; k < 2; ++k) dst[m][k] = *(const PG8_LAS bf16x8*)(lds + PG8_SA(b, h) + aoff + m * 2048 + k * 1024); } while (0)
; #define PG8_LDB(dst, b, h) do { _Pragma("unroll") for (int n = 0; n < 2; ++n) _Pragma("unroll") for (int k = 0; k < 2; ++k) dst[n][k] = *(const PG8_LAS bf16x8*)(lds + PG8_SB(b, h) + boff + n * 2048 + k * 1024); } while (0)
; #define PG8_WAIT_V(n) asm volatile("s_waitcnt vmcnt(" #n ")" ::: "memory")
; #define PG8_WAIT_L(n) asm volatile("s_waitcnt lgkmcnt(" #n ")" ::: "memory")
; #define PG8_BAR __builtin_amdgcn_s_barrier()
; #define PG8_SCHED __builtin_amdgcn_sched_barrier(0)
; template <class Epi, class Sched, bool ALIGN_EPI = false, bool SP2 = false, bool F8 = false>
; __device__ __forceinline__ void gemm_phase(PG8_LAS unsigned char* lds, const Gemm g, const Sched& S, const Epi& E) {
;     ...
;             PG8_WAIT_V(8); PG8_WAIT_L(0); PG8_BAR; PG8_MMA(1, 0, At, B0); PG8_MMA(1, 1, At, B1); PG8_BAR; PG8_SCHED;
;             PG8_LDB(B0, 1, 0); PG8_LDB(B1, 1, 1); PG8_SCHED; PG8_LDA(At, 1, 0); PG8_STAGE(PG8_SA(0, 1), a2 + hA, voffA);
;             PG8_WAIT_V(8); PG8_WAIT_L(0); PG8_BAR; PG8_MMA(0, 0, At, B0); PG8_MMA(0, 1, At, B1); PG8_BAR; PG8_SCHED;
	v_mfma_f32_16x16x32_bf16 v[62:65], v[130:133], v[162:165], v[62:65]
	v_mfma_f32_16x16x32_bf16 v[58:61], v[138:141], v[162:165], v[58:61]
	v_mfma_f32_16x16x32_bf16 v[50:53], v[130:133], v[186:189], v[50:53]
	v_mfma_f32_16x16x32_bf16 v[42:45], v[138:141], v[186:189], v[42:45]
	v_mfma_f32_16x16x32_bf16 v[34:37], v[130:133], v[200:203], v[34:37]
	v_mfma_f32_16x16x32_bf16 v[26:29], v[138:141], v[200:203], v[26:29]
	v_mfma_f32_16x16x32_bf16 v[18:21], v[130:133], v[208:211], v[18:21]
	v_mfma_f32_16x16x32_bf16 v[10:13], v[138:141], v[208:211], v[10:13]
	v_mfma_f32_16x16x32_bf16 v[62:65], v[134:137], v[182:185], v[62:65]
	v_mfma_f32_16x16x32_bf16 v[58:61], v[142:145], v[182:185], v[58:61]
	v_mfma_f32_16x16x32_bf16 v[50:53], v[134:137], v[190:193], v[50:53]
	v_mfma_f32_16x16x32_bf16 v[42:45], v[142:145], v[190:193], v[42:45]
	v_mfma_f32_16x16x32_bf16 v[34:37], v[134:137], v[204:207], v[34:37]
	v_mfma_f32_16x16x32_bf16 v[26:29], v[142:145], v[204:207], v[26:29]
	v_mfma_f32_16x16x32_bf16 v[18:21], v[134:137], v[212:215], v[18:21]
	v_mfma_f32_16x16x32_bf16 v[10:13], v[142:145], v[212:215], v[10:13]
	v_mfma_f32_16x16x32_bf16 v[54:57], v[146:149], v[162:165], v[54:57]
	v_mfma_f32_16x16x32_bf16 v[46:49], v[154:157], v[162:165], v[46:49]
	v_mfma_f32_16x16x32_bf16 v[38:41], v[146:149], v[186:189], v[38:41]
	v_mfma_f32_16x16x32_bf16 v[30:33], v[154:157], v[186:189], v[30:33]
	v_mfma_f32_16x16x32_bf16 v[22:25], v[146:149], v[200:203], v[22:25]
	v_mfma_f32_16x16x32_bf16 v[14:17], v[154:157], v[200:203], v[14:17]
	v_mfma_f32_16x16x32_bf16 v[6:9], v[146:149], v[208:211], v[6:9]
	v_mfma_f32_16x16x32_bf16 v[2:5], v[154:157], v[208:211], v[2:5]
	v_mfma_f32_16x16x32_bf16 v[54:57], v[150:153], v[182:185], v[54:57]
	v_mfma_f32_16x16x32_bf16 v[46:49], v[158:161], v[182:185], v[46:49]
	v_mfma_f32_16x16x32_bf16 v[38:41], v[150:153], v[190:193], v[38:41]
	v_mfma_f32_16x16x32_bf16 v[30:33], v[158:161], v[190:193], v[30:33]
	v_mfma_f32_16x16x32_bf16 v[22:25], v[150:153], v[204:207], v[22:25]
	v_mfma_f32_16x16x32_bf16 v[14:17], v[158:161], v[204:207], v[14:17]
	v_mfma_f32_16x16x32_bf16 v[6:9], v[150:153], v[212:215], v[6:9]
	v_mfma_f32_16x16x32_bf16 v[2:5], v[158:161], v[212:215], v[2:5]
	s_barrier
	s_setprio 0
	s_add_i32 s56, 0, 0x18000
	s_add_i32 s57, 0, 0x1c000
	v_add_u32_e32 v142, s56, v195
	v_add_u32_e32 v158, s57, v195
	ds_read_b128 v[130:133], v142
	ds_read_b128 v[134:137], v142 offset:1024
	ds_read_b128 v[138:141], v142 offset:2048
	ds_read_b128 v[142:145], v142 offset:3072
	ds_read_b128 v[146:149], v158
	ds_read_b128 v[150:153], v158 offset:1024
	ds_read_b128 v[154:157], v158 offset:2048
	ds_read_b128 v[158:161], v158 offset:3072
	s_add_u32 s26, s34, 0x2b0000
	s_addc_u32 s27, s35, 0
	s_mov_b32 m0, s41
	v_lshl_add_u64 v[224:225], s[26:27], 0, v[172:173]
	ds_read_b128 v[162:165], v199 offset:32768
	ds_read_b128 v[182:185], v199 offset:33792
	ds_read_b128 v[186:189], v199 offset:34816
	ds_read_b128 v[190:193], v199 offset:35840
	ds_read_b128 v[200:203], v199 offset:36864
	ds_read_b128 v[204:207], v199 offset:37888
	ds_read_b128 v[208:211], v199 offset:38912
	ds_read_b128 v[212:215], v199 offset:39936
	global_load_lds_dwordx4 v[224:225], off
	v_lshl_add_u64 v[224:225], s[26:27], 0, v[168:169]
	s_mov_b32 m0, s42
	s_nop 0
	global_load_lds_dwordx4 v[224:225], off
	s_waitcnt vmcnt(8) lgkmcnt(0)
	s_setprio 1
	s_barrier
	v_mfma_f32_16x16x32_bf16 v[126:129], v[130:133], v[162:165], v[126:129]
	v_mfma_f32_16x16x32_bf16 v[122:125], v[138:141], v[162:165], v[122:125]
	v_mfma_f32_16x16x32_bf16 v[118:121], v[130:133], v[186:189], v[118:121]
	v_mfma_f32_16x16x32_bf16 v[106:109], v[138:141], v[186:189], v[106:109]
	v_mfma_f32_16x16x32_bf16 v[98:101], v[130:133], v[200:203], v[98:101]
	v_mfma_f32_16x16x32_bf16 v[90:93], v[138:141], v[200:203], v[90:93]
	v_mfma_f32_16x16x32_bf16 v[82:85], v[130:133], v[208:211], v[82:85]
	v_mfma_f32_16x16x32_bf16 v[74:77], v[138:141], v[208:211], v[74:77]
	v_mfma_f32_16x16x32_bf16 v[126:129], v[134:137], v[182:185], v[126:129]
	v_mfma_f32_16x16x32_bf16 v[122:125], v[142:145], v[182:185], v[122:125]
	v_mfma_f32_16x16x32_bf16 v[118:121], v[134:137], v[190:193], v[118:121]
	v_mfma_f32_16x16x32_bf16 v[106:109], v[142:145], v[190:193], v[106:109]
	v_mfma_f32_16x16x32_bf16 v[98:101], v[134:137], v[204:207], v[98:101]
	v_mfma_f32_16x16x32_bf16 v[90:93], v[142:145], v[204:207], v[90:93]
	v_mfma_f32_16x16x32_bf16 v[82:85], v[134:137], v[212:215], v[82:85]
	v_mfma_f32_16x16x32_bf16 v[74:77], v[142:145], v[212:215], v[74:77]
	v_mfma_f32_16x16x32_bf16 v[114:117], v[146:149], v[162:165], v[114:117]
	v_mfma_f32_16x16x32_bf16 v[110:113], v[154:157], v[162:165], v[110:113]
	v_mfma_f32_16x16x32_bf16 v[102:105], v[146:149], v[186:189], v[102:105]
	v_mfma_f32_16x16x32_bf16 v[94:97], v[154:157], v[186:189], v[94:97]
	v_mfma_f32_16x16x32_bf16 v[86:89], v[146:149], v[200:203], v[86:89]
	v_mfma_f32_16x16x32_bf16 v[78:81], v[154:157], v[200:203], v[78:81]
	v_mfma_f32_16x16x32_bf16 v[70:73], v[146:149], v[208:211], v[70:73]
	v_mfma_f32_16x16x32_bf16 v[66:69], v[154:157], v[208:211], v[66:69]
	v_mfma_f32_16x16x32_bf16 v[114:117], v[150:153], v[182:185], v[114:117]
	v_mfma_f32_16x16x32_bf16 v[110:113], v[158:161], v[182:185], v[110:113]
	v_mfma_f32_16x16x32_bf16 v[102:105], v[150:153], v[190:193], v[102:105]
	v_mfma_f32_16x16x32_bf16 v[94:97], v[158:161], v[190:193], v[94:97]
	v_mfma_f32_16x16x32_bf16 v[86:89], v[150:153], v[204:207], v[86:89]
	v_mfma_f32_16x16x32_bf16 v[78:81], v[158:161], v[204:207], v[78:81]
	v_mfma_f32_16x16x32_bf16 v[70:73], v[150:153], v[212:215], v[70:73]
	v_mfma_f32_16x16x32_bf16 v[66:69], v[158:161], v[212:215], v[66:69]
	s_barrier
; #define PG8_GAS __attribute__((address_space(1)))
; #define PG8_STAGE(bufoff, gbase, voff) do { _Pragma("unroll") for (int _i = 0; _i < 2; ++_i) \
;         __builtin_amdgcn_global_load_lds((const unsigned*)((const char*)(gbase) + (voff)[_i]), (PG8_LAS unsigned*)(lds + (bufoff) + ldsw + _i * 8192), 16, 0, 0); } while (0)
; #define PG8_LDA(dst, b, h) do { _Pragma("unroll") for (int m = 0; m < 4; ++m) _Pragma("unroll") for (int k = 0; k < 2; ++k) dst[m][k] = *(const PG8_LAS bf16x8*)(lds + PG8_SA(b, h) + aoff + m * 2048 + k * 1024); } while (0)
; #define PG8_WAIT_V(n) asm volatile("s_waitcnt vmcnt(" #n ")" ::: "memory")
; #define PG8_WAIT_L(n) asm volatile("s_waitcnt lgkmcnt(" #n ")" ::: "memory")
; #define PG8_BAR __builtin_amdgcn_s_barrier()
; #define PG8_SCHED __builtin_amdgcn_sched_barrier(0)
;     __device__ __forceinline__ void operator()(const f32x4 (&acc)[2][2][4][2], const Unit& un, int wr, int wc, int fr, int fq) const {
;         const int row0 = un.pm * BM + wr * 64 + fr, col0 = un.pn * BM + wc * 32 + 8 * fq;
;         u32x4 rr[2][4][2];
; #pragma unroll
;         for (int ai = 0; ai < 2; ++ai)
; #pragma unroll
;             for (int m = 0; m < 4; ++m)
; #pragma unroll
;                 for (int bj = 0; bj < 2; ++bj) rr[ai][m][bj] = *(const PG8_GAS u32x4*)((PG8_GAS bf16_t*)h + (size_t)(row0 + ai * HALF + m * 16) * 4096 + col0 + bj * HALF);
;         asm volatile("" ::: "memory");
; template <class Epi, class Sched, bool ALIGN_EPI = false, bool SP2 = false, bool F8 = false>
; __device__ __forceinline__ void gemm_phase(PG8_LAS unsigned char* lds, const Gemm g, const Sched& S, const Epi& E) {
;     ...
;             PG8_LDA(At, 1, 1); PG8_STAGE(PG8_SB(1, 0), b3, voffB); PG8_STAGE(PG8_SB(1, 1), b3 + hB, voffB); PG8_STAGE(PG8_SA(1, 0), a3, voffA);
;             PG8_WAIT_V(8); PG8_WAIT_L(0); PG8_BAR; PG8_MMA(1, 0, At, B0); PG8_MMA(1, 1, At, B1); PG8_BAR; PG8_SCHED;
	s_setprio 0
	s_add_i32 s26, s56, s36
	v_lshl_add_u64 v[216:217], v[216:217], 0, s[14:15]
	s_mov_b32 m0, s26
	ds_read_b128 v[162:165], v199 offset:49152
	ds_read_b128 v[182:185], v199 offset:50176
	ds_read_b128 v[186:189], v199 offset:51200
	ds_read_b128 v[190:193], v199 offset:52224
	ds_read_b128 v[200:203], v199 offset:53248
	ds_read_b128 v[204:207], v199 offset:54272
	ds_read_b128 v[208:211], v199 offset:55296
	ds_read_b128 v[212:215], v199 offset:56320
	global_load_lds_dwordx4 v[216:217], off
	s_add_i32 m0, s26, 0x2000
	s_add_u32 s26, s30, 0x2b0080
	v_lshl_add_u64 v[216:217], v[218:219], 0, s[14:15]
	s_addc_u32 s27, s31, 0
	s_add_i32 s30, s57, s36
	global_load_lds_dwordx4 v[216:217], off
	v_lshl_add_u64 v[216:217], s[26:27], 0, v[170:171]
	s_mov_b32 m0, s30
	s_nop 0
	global_load_lds_dwordx4 v[216:217], off
	v_lshl_add_u64 v[216:217], s[26:27], 0, v[166:167]
	s_add_i32 m0, s30, 0x2000
	s_nop 0
	global_load_lds_dwordx4 v[216:217], off
	v_lshl_add_u64 v[216:217], v[220:221], 0, s[14:15]
	s_mov_b32 m0, s44
	s_nop 0
	global_load_lds_dwordx4 v[216:217], off
	v_lshl_add_u64 v[216:217], v[222:223], 0, s[14:15]
	s_mov_b32 m0, s45
	s_nop 0
	global_load_lds_dwordx4 v[216:217], off
	s_waitcnt vmcnt(8) lgkmcnt(0)
	s_setprio 1
	s_barrier
	v_mfma_f32_16x16x32_bf16 v[62:65], v[130:133], v[162:165], v[62:65]
	v_mfma_f32_16x16x32_bf16 v[58:61], v[138:141], v[162:165], v[58:61]
	v_mfma_f32_16x16x32_bf16 v[50:53], v[130:133], v[186:189], v[50:53]
	v_mfma_f32_16x16x32_bf16 v[42:45], v[138:141], v[186:189], v[42:45]
	v_mfma_f32_16x16x32_bf16 v[34:37], v[130:133], v[200:203], v[34:37]
	v_mfma_f32_16x16x32_bf16 v[26:29], v[138:141], v[200:203], v[26:29]
	v_mfma_f32_16x16x32_bf16 v[18:21], v[130:133], v[208:211], v[18:21]
	v_mfma_f32_16x16x32_bf16 v[10:13], v[138:141], v[208:211], v[10:13]
	v_mfma_f32_16x16x32_bf16 v[62:65], v[134:137], v[182:185], v[62:65]
	v_mfma_f32_16x16x32_bf16 v[58:61], v[142:145], v[182:185], v[58:61]
	v_mfma_f32_16x16x32_bf16 v[50:53], v[134:137], v[190:193], v[50:53]
	v_mfma_f32_16x16x32_bf16 v[42:45], v[142:145], v[190:193], v[42:45]
	v_mfma_f32_16x16x32_bf16 v[34:37], v[134:137], v[204:207], v[34:37]
	v_mfma_f32_16x16x32_bf16 v[26:29], v[142:145], v[204:207], v[26:29]
	v_mfma_f32_16x16x32_bf16 v[18:21], v[134:137], v[212:215], v[18:21]
	v_mfma_f32_16x16x32_bf16 v[10:13], v[142:145], v[212:215], v[10:13]
	v_mfma_f32_16x16x32_bf16 v[54:57], v[146:149], v[162:165], v[54:57]
	v_mfma_f32_16x16x32_bf16 v[46:49], v[154:157], v[162:165], v[46:49]
	v_mfma_f32_16x16x32_bf16 v[38:41], v[146:149], v[186:189], v[38:41]
	v_mfma_f32_16x16x32_bf16 v[30:33], v[154:157], v[186:189], v[30:33]
	v_mfma_f32_16x16x32_bf16 v[22:25], v[146:149], v[200:203], v[22:25]
	v_mfma_f32_16x16x32_bf16 v[14:17], v[154:157], v[200:203], v[14:17]
	v_mfma_f32_16x16x32_bf16 v[6:9], v[146:149], v[208:211], v[6:9]
	v_mfma_f32_16x16x32_bf16 v[2:5], v[154:157], v[208:211], v[2:5]
	v_mfma_f32_16x16x32_bf16 v[54:57], v[150:153], v[182:185], v[54:57]
	v_mfma_f32_16x16x32_bf16 v[46:49], v[158:161], v[182:185], v[46:49]
	v_mfma_f32_16x16x32_bf16 v[38:41], v[150:153], v[190:193], v[38:41]
	v_mfma_f32_16x16x32_bf16 v[30:33], v[158:161], v[190:193], v[30:33]
	v_mfma_f32_16x16x32_bf16 v[22:25], v[150:153], v[204:207], v[22:25]
	v_mfma_f32_16x16x32_bf16 v[14:17], v[158:161], v[204:207], v[14:17]
	v_mfma_f32_16x16x32_bf16 v[6:9], v[150:153], v[212:215], v[6:9]
	v_mfma_f32_16x16x32_bf16 v[2:5], v[158:161], v[212:215], v[2:5]
	s_barrier
	s_setprio 0
	s_add_i32 s55, s55, 2
	s_add_u32 s53, s53, 0x100
	s_addc_u32 s54, s54, 0
	s_cmpk_gt_u32 s55, 0xa9
	s_mov_b64 s[26:27], s[28:29]
	s_cbranch_scc0 .LBB0_1078
	v_lshl_or_b32 v132, s52, 8, v196
	v_lshl_add_u32 v130, s51, 8, v194
	v_ashrrev_i32_e32 v133, 31, v132
	v_lshlrev_b64 v[182:183], 1, v[132:133]
	v_ashrrev_i32_e32 v131, 31, v130
	v_lshl_add_u64 v[132:133], s[12:13], 0, v[182:183]
	v_lshlrev_b64 v[134:135], 13, v[130:131]
	v_lshl_add_u64 v[136:137], v[132:133], 0, v[134:135]
	global_load_dwordx4 v[200:203], v[136:137], off
	global_load_dwordx4 v[204:207], v[136:137], off offset:256
	v_or_b32_e32 v136, 16, v130
	v_ashrrev_i32_e32 v137, 31, v136
	v_lshlrev_b64 v[228:229], 13, v[136:137]
	v_lshl_add_u64 v[136:137], v[132:133], 0, v[228:229]
	global_load_dwordx4 v[208:211], v[136:137], off
	global_load_dwordx4 v[212:215], v[136:137], off offset:256
	v_or_b32_e32 v138, 32, v130
	v_or_b32_e32 v130, 48, v130
	v_ashrrev_i32_e32 v139, 31, v138
	v_ashrrev_i32_e32 v131, 31, v130
	v_lshlrev_b64 v[230:231], 13, v[138:139]
	v_lshlrev_b64 v[192:193], 13, v[130:131]
	v_lshl_add_u64 v[190:191], v[134:135], 0, s[16:17]
	v_lshl_add_u64 v[188:189], v[134:135], 0, s[20:21]
	v_lshl_add_u64 v[186:187], v[134:135], 0, s[22:23]
	v_lshl_add_u64 v[184:185], v[134:135], 0, s[24:25]
	v_lshl_add_u64 v[130:131], s[12:13], 0, v[134:135]
	v_lshl_add_u64 v[134:135], v[132:133], 0, v[230:231]
	v_lshl_add_u64 v[136:137], v[132:133], 0, v[192:193]
	v_lshl_add_u64 v[138:139], v[132:133], 0, v[190:191]
	v_lshl_add_u64 v[140:141], v[132:133], 0, v[188:189]
	v_lshl_add_u64 v[232:233], v[132:133], 0, v[186:187]
	v_lshl_add_u64 v[132:133], v[132:133], 0, v[184:185]
	v_lshl_add_u64 v[234:235], v[130:131], 0, v[182:183]
	global_load_dwordx4 v[216:219], v[134:135], off
	global_load_dwordx4 v[220:223], v[134:135], off offset:256
	global_load_dwordx4 v[224:227], v[136:137], off
	global_load_dwordx4 v[162:165], v[136:137], off offset:256
	global_load_dwordx4 v[158:161], v[138:139], off
	global_load_dwordx4 v[154:157], v[138:139], off offset:256
	global_load_dwordx4 v[150:153], v[140:141], off
	global_load_dwordx4 v[146:149], v[140:141], off offset:256
	global_load_dwordx4 v[142:145], v[232:233], off
	s_nop 0
	global_load_dwordx4 v[138:141], v[232:233], off offset:256
	global_load_dwordx4 v[134:137], v[132:133], off
	s_nop 0
	global_load_dwordx4 v[130:133], v[132:133], off offset:256
	s_and_b64 vcc, exec, s[4:5]
	s_mov_b32 s52, s49
	s_mov_b32 s51, s50
	s_mov_b64 s[28:29], s[8:9]
	s_mov_b64 s[26:27], s[6:7]
	s_waitcnt vmcnt(0)
; #define PG8_GAS __attribute__((address_space(1)))
; __device__ __forceinline__ unsigned cvt_pk_bf16(float lo, float hi) { const f32x2c v = {lo, hi}; return __builtin_bit_cast(unsigned, __builtin_convertvector(v, bf16x2c)); }
; __device__ __forceinline__ float bf_lo(unsigned w) { return __uint_as_float(w << 16); }
; __device__ __forceinline__ float bf_hi(unsigned w) { return __uint_as_float(w & 0xffff0000u); }
;     __device__ __forceinline__ void operator()(const f32x4 (&acc)[2][2][4][2], const Unit& un, int wr, int wc, int fr, int fq) const {
;     ...
;                 for (int bj = 0; bj < 2; ++bj) { const u32x4 r = rr[ai][m][bj]; const f32x4 v0 = acc[ai][bj][m][0], v1 = acc[ai][bj][m][1];
;                     u32x4 w; w.x = cvt_pk_bf16(v0[0] + bf_lo(r.x), v0[1] + bf_hi(r.x)); w.y = cvt_pk_bf16(v0[2] + bf_lo(r.y), v0[3] + bf_hi(r.y));
;                     w.z = cvt_pk_bf16(v1[0] + bf_lo(r.z), v1[1] + bf_hi(r.z)); w.w = cvt_pk_bf16(v1[2] + bf_lo(r.w), v1[3] + bf_hi(r.w));
;                     *(PG8_GAS u32x4*)((PG8_GAS bf16_t*)h + (size_t)(row0 + ai * HALF + m * 16) * 4096 + col0 + bj * HALF) = w; }
	v_lshlrev_b32_e32 v232, 16, v200
	v_and_b32_e32 v233, 0xffff0000, v200
	v_lshlrev_b32_e32 v200, 16, v201
	v_and_b32_e32 v201, 0xffff0000, v201
	v_lshlrev_b32_e32 v236, 16, v202
	v_and_b32_e32 v237, 0xffff0000, v202
	v_lshlrev_b32_e32 v202, 16, v203
	v_and_b32_e32 v203, 0xffff0000, v203
	v_lshlrev_b32_e32 v238, 16, v204
	v_and_b32_e32 v239, 0xffff0000, v204
	v_lshlrev_b32_e32 v204, 16, v205
	v_and_b32_e32 v205, 0xffff0000, v205
	v_lshlrev_b32_e32 v240, 16, v206
	v_and_b32_e32 v241, 0xffff0000, v206
	v_lshlrev_b32_e32 v206, 16, v207
	v_and_b32_e32 v207, 0xffff0000, v207
	v_pk_add_f32 v[126:127], v[126:127], v[232:233]
	v_pk_add_f32 v[128:129], v[128:129], v[200:201]
	v_pk_add_f32 v[122:123], v[122:123], v[236:237]
	v_pk_add_f32 v[124:125], v[124:125], v[202:203]
	v_pk_add_f32 v[114:115], v[114:115], v[238:239]
	v_pk_add_f32 v[116:117], v[116:117], v[204:205]
	v_pk_add_f32 v[200:201], v[110:111], v[240:241]
	v_pk_add_f32 v[202:203], v[112:113], v[206:207]
	v_cvt_pk_bf16_f32 v110, v126, v127
	v_cvt_pk_bf16_f32 v111, v128, v129
	v_cvt_pk_bf16_f32 v112, v122, v123
	v_cvt_pk_bf16_f32 v113, v124, v125
	v_lshlrev_b32_e32 v242, 16, v208
	v_and_b32_e32 v243, 0xffff0000, v208
	v_lshlrev_b32_e32 v208, 16, v209
	v_and_b32_e32 v209, 0xffff0000, v209
	v_cvt_pk_bf16_f32 v114, v114, v115
	v_cvt_pk_bf16_f32 v115, v116, v117
	v_cvt_pk_bf16_f32 v116, v200, v201
	v_cvt_pk_bf16_f32 v117, v202, v203
	global_store_dwordx4 v[234:235], v[110:113], off
	global_store_dwordx4 v[234:235], v[114:117], off offset:256
	v_pk_add_f32 v[118:119], v[118:119], v[242:243]
	v_lshlrev_b32_e32 v110, 16, v210
	v_and_b32_e32 v111, 0xffff0000, v210
	v_pk_add_f32 v[120:121], v[120:121], v[208:209]
	v_pk_add_f32 v[106:107], v[106:107], v[110:111]
	v_cvt_pk_bf16_f32 v118, v118, v119
	v_cvt_pk_bf16_f32 v119, v120, v121
	v_cvt_pk_bf16_f32 v120, v106, v107
	v_lshlrev_b32_e32 v106, 16, v211
	v_and_b32_e32 v107, 0xffff0000, v211
	v_pk_add_f32 v[106:107], v[108:109], v[106:107]
	v_lshlrev_b32_e32 v108, 16, v212
	v_and_b32_e32 v109, 0xffff0000, v212
	v_pk_add_f32 v[102:103], v[102:103], v[108:109]
	v_lshlrev_b32_e32 v108, 16, v213
	v_and_b32_e32 v109, 0xffff0000, v213
	v_pk_add_f32 v[104:105], v[104:105], v[108:109]
	v_cvt_pk_bf16_f32 v102, v102, v103
	v_cvt_pk_bf16_f32 v103, v104, v105
	v_lshlrev_b32_e32 v104, 16, v214
	v_and_b32_e32 v105, 0xffff0000, v214
	v_pk_add_f32 v[94:95], v[94:95], v[104:105]
	v_cvt_pk_bf16_f32 v121, v106, v107
	v_cvt_pk_bf16_f32 v104, v94, v95
	v_lshlrev_b32_e32 v94, 16, v215
	v_and_b32_e32 v95, 0xffff0000, v215
	v_pk_add_f32 v[94:95], v[96:97], v[94:95]
	v_lshlrev_b32_e32 v96, 16, v217
	v_cvt_pk_bf16_f32 v105, v94, v95
	v_lshlrev_b32_e32 v94, 16, v216
	v_and_b32_e32 v95, 0xffff0000, v216
	v_and_b32_e32 v97, 0xffff0000, v217
	v_pk_add_f32 v[94:95], v[98:99], v[94:95]
	v_pk_add_f32 v[96:97], v[100:101], v[96:97]
	v_cvt_pk_bf16_f32 v94, v94, v95
	v_cvt_pk_bf16_f32 v95, v96, v97
	v_lshlrev_b32_e32 v96, 16, v218
	v_and_b32_e32 v97, 0xffff0000, v218
	v_pk_add_f32 v[90:91], v[90:91], v[96:97]
	v_lshl_add_u64 v[106:107], s[12:13], 0, v[228:229]
	v_cvt_pk_bf16_f32 v96, v90, v91
	v_lshlrev_b32_e32 v90, 16, v219
	v_and_b32_e32 v91, 0xffff0000, v219
	v_pk_add_f32 v[90:91], v[92:93], v[90:91]
	v_lshlrev_b32_e32 v92, 16, v220
	v_and_b32_e32 v93, 0xffff0000, v220
	v_pk_add_f32 v[86:87], v[86:87], v[92:93]
	v_lshlrev_b32_e32 v92, 16, v221
	v_and_b32_e32 v93, 0xffff0000, v221
	v_pk_add_f32 v[88:89], v[88:89], v[92:93]
	v_cvt_pk_bf16_f32 v86, v86, v87
	v_cvt_pk_bf16_f32 v87, v88, v89
	v_lshlrev_b32_e32 v88, 16, v222
	v_and_b32_e32 v89, 0xffff0000, v222
	v_pk_add_f32 v[78:79], v[78:79], v[88:89]
	v_cvt_pk_bf16_f32 v97, v90, v91
	v_cvt_pk_bf16_f32 v88, v78, v79
	v_lshlrev_b32_e32 v78, 16, v223
	v_and_b32_e32 v79, 0xffff0000, v223
	v_pk_add_f32 v[78:79], v[80:81], v[78:79]
	v_lshlrev_b32_e32 v80, 16, v225
	v_cvt_pk_bf16_f32 v89, v78, v79
	v_lshlrev_b32_e32 v78, 16, v224
	v_and_b32_e32 v79, 0xffff0000, v224
	v_and_b32_e32 v81, 0xffff0000, v225
	v_pk_add_f32 v[78:79], v[82:83], v[78:79]
	v_pk_add_f32 v[80:81], v[84:85], v[80:81]
	v_cvt_pk_bf16_f32 v78, v78, v79
	v_cvt_pk_bf16_f32 v79, v80, v81
	v_lshlrev_b32_e32 v80, 16, v226
	v_and_b32_e32 v81, 0xffff0000, v226
	v_pk_add_f32 v[74:75], v[74:75], v[80:81]
	v_lshl_add_u64 v[90:91], s[12:13], 0, v[230:231]
	v_cvt_pk_bf16_f32 v80, v74, v75
	v_lshlrev_b32_e32 v74, 16, v227
	v_and_b32_e32 v75, 0xffff0000, v227
	v_pk_add_f32 v[74:75], v[76:77], v[74:75]
	v_lshlrev_b32_e32 v76, 16, v162
	v_and_b32_e32 v77, 0xffff0000, v162
	v_pk_add_f32 v[70:71], v[70:71], v[76:77]
	v_lshlrev_b32_e32 v76, 16, v163
	v_and_b32_e32 v77, 0xffff0000, v163
	v_pk_add_f32 v[72:73], v[72:73], v[76:77]
	v_cvt_pk_bf16_f32 v70, v70, v71
	v_cvt_pk_bf16_f32 v71, v72, v73
	v_lshlrev_b32_e32 v72, 16, v164
	v_and_b32_e32 v73, 0xffff0000, v164
	v_pk_add_f32 v[66:67], v[66:67], v[72:73]
	v_cvt_pk_bf16_f32 v81, v74, v75
	v_cvt_pk_bf16_f32 v72, v66, v67
	v_lshlrev_b32_e32 v66, 16, v165
	v_and_b32_e32 v67, 0xffff0000, v165
	v_pk_add_f32 v[66:67], v[68:69], v[66:67]
	v_lshl_add_u64 v[74:75], s[12:13], 0, v[192:193]
	v_cvt_pk_bf16_f32 v73, v66, v67
	v_lshlrev_b32_e32 v66, 16, v158
	v_and_b32_e32 v67, 0xffff0000, v158
	v_pk_add_f32 v[62:63], v[62:63], v[66:67]
	v_lshlrev_b32_e32 v66, 16, v159
	v_and_b32_e32 v67, 0xffff0000, v159
	v_pk_add_f32 v[64:65], v[64:65], v[66:67]
	v_cvt_pk_bf16_f32 v62, v62, v63
	v_cvt_pk_bf16_f32 v63, v64, v65
	v_lshlrev_b32_e32 v64, 16, v160
	v_and_b32_e32 v65, 0xffff0000, v160
	v_pk_add_f32 v[58:59], v[58:59], v[64:65]
	v_lshl_add_u64 v[106:107], v[106:107], 0, v[182:183]
; #define PG8_GAS __attribute__((address_space(1)))
; __device__ __forceinline__ unsigned cvt_pk_bf16(float lo, float hi) { const f32x2c v = {lo, hi}; return __builtin_bit_cast(unsigned, __builtin_convertvector(v, bf16x2c)); }
; __device__ __forceinline__ float bf_lo(unsigned w) { return __uint_as_float(w << 16); }
; __device__ __forceinline__ float bf_hi(unsigned w) { return __uint_as_float(w & 0xffff0000u); }
; #define PG8_WAIT_V(n) asm volatile("s_waitcnt vmcnt(" #n ")" ::: "memory")
; #define PG8_BAR __builtin_amdgcn_s_barrier()
;     __device__ __forceinline__ void operator()(const f32x4 (&acc)[2][2][4][2], const Unit& un, int wr, int wc, int fr, int fq) const {
;     ...
;                 for (int bj = 0; bj < 2; ++bj) { const u32x4 r = rr[ai][m][bj]; const f32x4 v0 = acc[ai][bj][m][0], v1 = acc[ai][bj][m][1];
;                     u32x4 w; w.x = cvt_pk_bf16(v0[0] + bf_lo(r.x), v0[1] + bf_hi(r.x)); w.y = cvt_pk_bf16(v0[2] + bf_lo(r.y), v0[3] + bf_hi(r.y));
;                     w.z = cvt_pk_bf16(v1[0] + bf_lo(r.z), v1[1] + bf_hi(r.z)); w.w = cvt_pk_bf16(v1[2] + bf_lo(r.w), v1[3] + bf_hi(r.w));
;                     *(PG8_GAS u32x4*)((PG8_GAS bf16_t*)h + (size_t)(row0 + ai * HALF + m * 16) * 4096 + col0 + bj * HALF) = w; }
; template <class Epi, class Sched, bool ALIGN_EPI = false, bool SP2 = false, bool F8 = false>
; __device__ __forceinline__ void gemm_phase(PG8_LAS unsigned char* lds, const Gemm g, const Sched& S, const Epi& E) {
;     ...
;         if (!has_next) break;
; #pragma unroll
;         for (int a = 0; a < 2; ++a)
; #pragma unroll
;             for (int b = 0; b < 2; ++b)
; #pragma unroll
;                 for (int m = 0; m < 4; ++m)
; #pragma unroll
;                     for (int n = 0; n < 2; ++n) acc[a][b][m][n] = (f32x4){0.f, 0.f, 0.f, 0.f};
;         cur = nxt; cA = nA; cB = nB; ++ui;
;         if constexpr (ALIGN_EPI) { if (wr == 1) PG8_BAR; }
;     }
;     PG8_WAIT_V(0);
;     if constexpr (!ALIGN_EPI) { if (wr == 0) PG8_BAR; }
	v_cvt_pk_bf16_f32 v64, v58, v59
	v_lshlrev_b32_e32 v58, 16, v161
	v_and_b32_e32 v59, 0xffff0000, v161
	v_pk_add_f32 v[58:59], v[60:61], v[58:59]
	v_lshlrev_b32_e32 v60, 16, v154
	v_and_b32_e32 v61, 0xffff0000, v154
	v_pk_add_f32 v[54:55], v[54:55], v[60:61]
	v_lshlrev_b32_e32 v60, 16, v155
	v_and_b32_e32 v61, 0xffff0000, v155
	v_pk_add_f32 v[56:57], v[56:57], v[60:61]
	v_cvt_pk_bf16_f32 v54, v54, v55
	v_cvt_pk_bf16_f32 v55, v56, v57
	v_lshlrev_b32_e32 v56, 16, v156
	v_and_b32_e32 v57, 0xffff0000, v156
	v_pk_add_f32 v[46:47], v[46:47], v[56:57]
	v_cvt_pk_bf16_f32 v65, v58, v59
	v_cvt_pk_bf16_f32 v56, v46, v47
	v_lshlrev_b32_e32 v46, 16, v157
	v_and_b32_e32 v47, 0xffff0000, v157
	v_pk_add_f32 v[46:47], v[48:49], v[46:47]
	v_lshlrev_b32_e32 v48, 16, v151
	v_cvt_pk_bf16_f32 v57, v46, v47
	v_lshlrev_b32_e32 v46, 16, v150
	v_and_b32_e32 v47, 0xffff0000, v150
	v_and_b32_e32 v49, 0xffff0000, v151
	v_pk_add_f32 v[46:47], v[50:51], v[46:47]
	v_pk_add_f32 v[48:49], v[52:53], v[48:49]
	v_cvt_pk_bf16_f32 v46, v46, v47
	v_cvt_pk_bf16_f32 v47, v48, v49
	v_lshlrev_b32_e32 v48, 16, v152
	v_and_b32_e32 v49, 0xffff0000, v152
	v_pk_add_f32 v[42:43], v[42:43], v[48:49]
	v_lshl_add_u64 v[58:59], s[12:13], 0, v[190:191]
	v_cvt_pk_bf16_f32 v48, v42, v43
	v_lshlrev_b32_e32 v42, 16, v153
	v_and_b32_e32 v43, 0xffff0000, v153
	v_pk_add_f32 v[42:43], v[44:45], v[42:43]
	v_lshlrev_b32_e32 v44, 16, v146
	v_and_b32_e32 v45, 0xffff0000, v146
	v_pk_add_f32 v[38:39], v[38:39], v[44:45]
	v_lshlrev_b32_e32 v44, 16, v147
	v_and_b32_e32 v45, 0xffff0000, v147
	v_pk_add_f32 v[40:41], v[40:41], v[44:45]
	v_cvt_pk_bf16_f32 v38, v38, v39
	v_cvt_pk_bf16_f32 v39, v40, v41
	v_lshlrev_b32_e32 v40, 16, v148
	v_and_b32_e32 v41, 0xffff0000, v148
	v_pk_add_f32 v[30:31], v[30:31], v[40:41]
	v_cvt_pk_bf16_f32 v49, v42, v43
	v_cvt_pk_bf16_f32 v40, v30, v31
	v_lshlrev_b32_e32 v30, 16, v149
	v_and_b32_e32 v31, 0xffff0000, v149
	v_pk_add_f32 v[30:31], v[32:33], v[30:31]
	v_lshlrev_b32_e32 v32, 16, v143
	v_cvt_pk_bf16_f32 v41, v30, v31
	v_lshlrev_b32_e32 v30, 16, v142
	v_and_b32_e32 v31, 0xffff0000, v142
	v_and_b32_e32 v33, 0xffff0000, v143
	v_pk_add_f32 v[30:31], v[34:35], v[30:31]
	v_pk_add_f32 v[32:33], v[36:37], v[32:33]
	v_cvt_pk_bf16_f32 v30, v30, v31
	v_cvt_pk_bf16_f32 v31, v32, v33
	v_lshlrev_b32_e32 v32, 16, v144
	v_and_b32_e32 v33, 0xffff0000, v144
	v_pk_add_f32 v[26:27], v[26:27], v[32:33]
	v_lshl_add_u64 v[42:43], s[12:13], 0, v[188:189]
	v_cvt_pk_bf16_f32 v32, v26, v27
	v_lshlrev_b32_e32 v26, 16, v145
	v_and_b32_e32 v27, 0xffff0000, v145
	v_pk_add_f32 v[26:27], v[28:29], v[26:27]
	v_lshlrev_b32_e32 v28, 16, v138
	v_and_b32_e32 v29, 0xffff0000, v138
	v_pk_add_f32 v[22:23], v[22:23], v[28:29]
	v_lshlrev_b32_e32 v28, 16, v139
	v_and_b32_e32 v29, 0xffff0000, v139
	v_pk_add_f32 v[24:25], v[24:25], v[28:29]
	v_cvt_pk_bf16_f32 v22, v22, v23
	v_cvt_pk_bf16_f32 v23, v24, v25
	v_lshlrev_b32_e32 v24, 16, v140
	v_and_b32_e32 v25, 0xffff0000, v140
	v_pk_add_f32 v[14:15], v[14:15], v[24:25]
	v_cvt_pk_bf16_f32 v33, v26, v27
	v_cvt_pk_bf16_f32 v24, v14, v15
	v_lshlrev_b32_e32 v14, 16, v141
	v_and_b32_e32 v15, 0xffff0000, v141
	v_pk_add_f32 v[14:15], v[16:17], v[14:15]
	v_lshlrev_b32_e32 v16, 16, v135
	v_cvt_pk_bf16_f32 v25, v14, v15
	v_lshlrev_b32_e32 v14, 16, v134
	v_and_b32_e32 v15, 0xffff0000, v134
	v_and_b32_e32 v17, 0xffff0000, v135
	v_pk_add_f32 v[14:15], v[18:19], v[14:15]
	v_pk_add_f32 v[16:17], v[20:21], v[16:17]
	v_cvt_pk_bf16_f32 v14, v14, v15
	v_cvt_pk_bf16_f32 v15, v16, v17
	v_lshlrev_b32_e32 v16, 16, v136
	v_and_b32_e32 v17, 0xffff0000, v136
	v_pk_add_f32 v[10:11], v[10:11], v[16:17]
	v_lshl_add_u64 v[26:27], s[12:13], 0, v[186:187]
	v_cvt_pk_bf16_f32 v16, v10, v11
	v_lshlrev_b32_e32 v10, 16, v137
	v_and_b32_e32 v11, 0xffff0000, v137
	v_pk_add_f32 v[10:11], v[12:13], v[10:11]
	v_lshlrev_b32_e32 v12, 16, v130
	v_and_b32_e32 v13, 0xffff0000, v130
	v_pk_add_f32 v[6:7], v[6:7], v[12:13]
	v_lshlrev_b32_e32 v12, 16, v131
	v_and_b32_e32 v13, 0xffff0000, v131
	v_pk_add_f32 v[8:9], v[8:9], v[12:13]
	v_cvt_pk_bf16_f32 v6, v6, v7
	v_cvt_pk_bf16_f32 v7, v8, v9
	v_lshlrev_b32_e32 v8, 16, v132
	v_and_b32_e32 v9, 0xffff0000, v132
	v_pk_add_f32 v[2:3], v[2:3], v[8:9]
	v_cvt_pk_bf16_f32 v17, v10, v11
	v_cvt_pk_bf16_f32 v8, v2, v3
	v_lshlrev_b32_e32 v2, 16, v133
	v_and_b32_e32 v3, 0xffff0000, v133
	v_lshl_add_u64 v[10:11], s[12:13], 0, v[184:185]
	v_pk_add_f32 v[2:3], v[4:5], v[2:3]
	v_lshl_add_u64 v[90:91], v[90:91], 0, v[182:183]
	v_lshl_add_u64 v[74:75], v[74:75], 0, v[182:183]
	v_lshl_add_u64 v[58:59], v[58:59], 0, v[182:183]
	v_lshl_add_u64 v[42:43], v[42:43], 0, v[182:183]
	v_lshl_add_u64 v[26:27], v[26:27], 0, v[182:183]
	v_lshl_add_u64 v[10:11], v[10:11], 0, v[182:183]
	v_cvt_pk_bf16_f32 v9, v2, v3
	global_store_dwordx4 v[106:107], v[118:121], off
	global_store_dwordx4 v[106:107], v[102:105], off offset:256
	global_store_dwordx4 v[90:91], v[94:97], off
	global_store_dwordx4 v[90:91], v[86:89], off offset:256
	global_store_dwordx4 v[74:75], v[78:81], off
	global_store_dwordx4 v[74:75], v[70:73], off offset:256
	global_store_dwordx4 v[58:59], v[62:65], off
	global_store_dwordx4 v[58:59], v[54:57], off offset:256
	global_store_dwordx4 v[42:43], v[46:49], off
	global_store_dwordx4 v[42:43], v[38:41], off offset:256
	global_store_dwordx4 v[26:27], v[30:33], off
	global_store_dwordx4 v[26:27], v[22:25], off offset:256
	global_store_dwordx4 v[10:11], v[14:17], off
	global_store_dwordx4 v[10:11], v[6:9], off offset:256
	s_cbranch_vccz .LBB0_1071
	s_waitcnt vmcnt(0)
	s_cmpk_gt_u32 s18, 0xff
	s_cbranch_scc1 .LBB0_1082
	s_barrier
